# static-bound softmax reference: drop per-tile max/alpha/rescale in A,C far paths
# speedup vs baseline: 1.0112x; 1.0112x over previous
; __device__ __forceinline__ void phase_attn(const Params& p, int l, unsigned char* shm) {
;   const bf16_t* qkv = (const bf16_t*)(p.ws + WS_QKV); const bf16_t* gates = (const bf16_t*)(p.ws + WS_GATES);
;   bf16_t* merged = (bf16_t*)(p.ws + WS_XN);
;   const float* lutall = (const float*)(p.ws + WS_LUT); const float* lamp = (const float*)(p.ws + WS_LAM);
;   AttnEpi E; E.park = (float*)(p.ws + WS_PARK) + (size_t)blockIdx.x * 65536; E.gsub = p.in[22] + l * 128; E.lam = lamp[2 * l]; E.oml = lamp[2 * l + 1];
;   for (int it = blockIdx.x; it < 1024; it += gridDim.x) {
;     int S, tok0, h, qb;
;     if (it < 512) { S = 16384; tok0 = 16384; h = it & 7; qb = it >> 3; }
;     else { const int j = it - 512; S = 2048; h = j & 7; qb = (j >> 3) & 7; tok0 = (j >> 6) * 2048; }
;     const int g = h >> 2, q0 = qb * 256;
;     const bf16_t* rowQ = qkv + (size_t)(tok0 + q0) * QKVW; const bf16_t* seqK = qkv + (size_t)tok0 * QKVW;
;     const bf16_t* grow = gates + (size_t)(tok0 + q0) * GW + h * 128;
;     E.merged = merged + (size_t)(tok0 + q0) * DM + h * 128; E.sinkl2 = p.in[17][l * 8 + h] * LOG2E;
;     E.gate = grow; E.gq = p.in[11] + l * 128;
.LBB0_70:
	s_and_b64 vcc, exec, s[0:1]
	s_cbranch_vccz .LBB0_214
	v_readlane_b32 s0, v252, 49
	v_readlane_b32 s1, v252, 50
	s_andn2_b64 vcc, exec, s[0:1]
	s_cbranch_vccnz .LBB0_213
	v_readlane_b32 s12, v254, 63
	v_readlane_b32 s16, v254, 31
	v_readlane_b32 s17, v254, 32
	v_readlane_b32 s18, v254, 33
	v_readlane_b32 s19, v254, 34
	v_readlane_b32 s20, v254, 39
	v_readlane_b32 s21, v254, 40
	v_readlane_b32 s22, v254, 41
	v_readlane_b32 s23, v254, 42
	s_nop 3
	s_lshl_b32 s28, s12, 9
	s_add_u32 s16, s16, s28
	s_addc_u32 s17, s17, 0
	s_add_u32 s18, s18, s28
	s_addc_u32 s19, s19, 0
	s_lshl_b32 s28, s12, 8
	s_add_u32 s20, s20, s28
	s_addc_u32 s21, s21, 0
	s_add_u32 s22, s22, s28
	s_addc_u32 s23, s23, 0
	s_mov_b32 s24, 0
	s_mov_b32 s25, 0
	s_mov_b32 s26, 0
	s_mov_b32 s27, 0
	s_load_dwordx16 s[52:67], s[16:17], 0x0
	s_waitcnt lgkmcnt(0)
	s_and_b32 s28, s52, 0x7fffffff
	s_max_u32 s24, s24, s28
	s_and_b32 s28, s53, 0x7fffffff
	s_max_u32 s24, s24, s28
	s_and_b32 s28, s54, 0x7fffffff
	s_max_u32 s24, s24, s28
	s_and_b32 s28, s55, 0x7fffffff
	s_max_u32 s24, s24, s28
	s_and_b32 s28, s56, 0x7fffffff
	s_max_u32 s24, s24, s28
	s_and_b32 s28, s57, 0x7fffffff
	s_max_u32 s24, s24, s28
	s_and_b32 s28, s58, 0x7fffffff
	s_max_u32 s24, s24, s28
	s_and_b32 s28, s59, 0x7fffffff
	s_max_u32 s24, s24, s28
	s_and_b32 s28, s60, 0x7fffffff
	s_max_u32 s24, s24, s28
	s_and_b32 s28, s61, 0x7fffffff
	s_max_u32 s24, s24, s28
	s_and_b32 s28, s62, 0x7fffffff
	s_max_u32 s24, s24, s28
	s_and_b32 s28, s63, 0x7fffffff
	s_max_u32 s24, s24, s28
	s_and_b32 s28, s64, 0x7fffffff
	s_max_u32 s24, s24, s28
	s_and_b32 s28, s65, 0x7fffffff
	s_max_u32 s24, s24, s28
	s_and_b32 s28, s66, 0x7fffffff
	s_max_u32 s24, s24, s28
	s_and_b32 s28, s67, 0x7fffffff
	s_max_u32 s24, s24, s28
	s_load_dwordx16 s[52:67], s[16:17], 0x40
	s_waitcnt lgkmcnt(0)
	s_and_b32 s28, s52, 0x7fffffff
	s_max_u32 s24, s24, s28
	s_and_b32 s28, s53, 0x7fffffff
	s_max_u32 s24, s24, s28
	s_and_b32 s28, s54, 0x7fffffff
	s_max_u32 s24, s24, s28
	s_and_b32 s28, s55, 0x7fffffff
	s_max_u32 s24, s24, s28
	s_and_b32 s28, s56, 0x7fffffff
	s_max_u32 s24, s24, s28
	s_and_b32 s28, s57, 0x7fffffff
	s_max_u32 s24, s24, s28
	s_and_b32 s28, s58, 0x7fffffff
	s_max_u32 s24, s24, s28
	s_and_b32 s28, s59, 0x7fffffff
	s_max_u32 s24, s24, s28
	s_and_b32 s28, s60, 0x7fffffff
	s_max_u32 s24, s24, s28
	s_and_b32 s28, s61, 0x7fffffff
	s_max_u32 s24, s24, s28
	s_and_b32 s28, s62, 0x7fffffff
	s_max_u32 s24, s24, s28
	s_and_b32 s28, s63, 0x7fffffff
	s_max_u32 s24, s24, s28
	s_and_b32 s28, s64, 0x7fffffff
	s_max_u32 s24, s24, s28
	s_and_b32 s28, s65, 0x7fffffff
	s_max_u32 s24, s24, s28
	s_and_b32 s28, s66, 0x7fffffff
	s_max_u32 s24, s24, s28
	s_and_b32 s28, s67, 0x7fffffff
	s_max_u32 s24, s24, s28
	s_load_dwordx16 s[52:67], s[16:17], 0x80
	s_waitcnt lgkmcnt(0)
	s_and_b32 s28, s52, 0x7fffffff
	s_max_u32 s24, s24, s28
	s_and_b32 s28, s53, 0x7fffffff
	s_max_u32 s24, s24, s28
	s_and_b32 s28, s54, 0x7fffffff
	s_max_u32 s24, s24, s28
	s_and_b32 s28, s55, 0x7fffffff
	s_max_u32 s24, s24, s28
	s_and_b32 s28, s56, 0x7fffffff
	s_max_u32 s24, s24, s28
	s_and_b32 s28, s57, 0x7fffffff
	s_max_u32 s24, s24, s28
	s_and_b32 s28, s58, 0x7fffffff
	s_max_u32 s24, s24, s28
	s_and_b32 s28, s59, 0x7fffffff
	s_max_u32 s24, s24, s28
	s_and_b32 s28, s60, 0x7fffffff
	s_max_u32 s24, s24, s28
	s_and_b32 s28, s61, 0x7fffffff
	s_max_u32 s24, s24, s28
	s_and_b32 s28, s62, 0x7fffffff
	s_max_u32 s24, s24, s28
	s_and_b32 s28, s63, 0x7fffffff
	s_max_u32 s24, s24, s28
	s_and_b32 s28, s64, 0x7fffffff
	s_max_u32 s24, s24, s28
	s_and_b32 s28, s65, 0x7fffffff
	s_max_u32 s24, s24, s28
	s_and_b32 s28, s66, 0x7fffffff
	s_max_u32 s24, s24, s28
	s_and_b32 s28, s67, 0x7fffffff
	s_max_u32 s24, s24, s28
	s_load_dwordx16 s[52:67], s[16:17], 0xc0
	s_waitcnt lgkmcnt(0)
	s_and_b32 s28, s52, 0x7fffffff
	s_max_u32 s24, s24, s28
	s_and_b32 s28, s53, 0x7fffffff
	s_max_u32 s24, s24, s28
	s_and_b32 s28, s54, 0x7fffffff
	s_max_u32 s24, s24, s28
	s_and_b32 s28, s55, 0x7fffffff
	s_max_u32 s24, s24, s28
	s_and_b32 s28, s56, 0x7fffffff
	s_max_u32 s24, s24, s28
	s_and_b32 s28, s57, 0x7fffffff
	s_max_u32 s24, s24, s28
	s_and_b32 s28, s58, 0x7fffffff
	s_max_u32 s24, s24, s28
	s_and_b32 s28, s59, 0x7fffffff
	s_max_u32 s24, s24, s28
	s_and_b32 s28, s60, 0x7fffffff
	s_max_u32 s24, s24, s28
	s_and_b32 s28, s61, 0x7fffffff
	s_max_u32 s24, s24, s28
	s_and_b32 s28, s62, 0x7fffffff
	s_max_u32 s24, s24, s28
	s_and_b32 s28, s63, 0x7fffffff
	s_max_u32 s24, s24, s28
	s_and_b32 s28, s64, 0x7fffffff
	s_max_u32 s24, s24, s28
	s_and_b32 s28, s65, 0x7fffffff
	s_max_u32 s24, s24, s28
	s_and_b32 s28, s66, 0x7fffffff
	s_max_u32 s24, s24, s28
	s_and_b32 s28, s67, 0x7fffffff
	s_max_u32 s24, s24, s28
	s_load_dwordx16 s[52:67], s[16:17], 0x100
	s_waitcnt lgkmcnt(0)
	s_and_b32 s28, s52, 0x7fffffff
	s_max_u32 s24, s24, s28
	s_and_b32 s28, s53, 0x7fffffff
	s_max_u32 s24, s24, s28
	s_and_b32 s28, s54, 0x7fffffff
	s_max_u32 s24, s24, s28
	s_and_b32 s28, s55, 0x7fffffff
	s_max_u32 s24, s24, s28
	s_and_b32 s28, s56, 0x7fffffff
	s_max_u32 s24, s24, s28
	s_and_b32 s28, s57, 0x7fffffff
	s_max_u32 s24, s24, s28
	s_and_b32 s28, s58, 0x7fffffff
	s_max_u32 s24, s24, s28
	s_and_b32 s28, s59, 0x7fffffff
	s_max_u32 s24, s24, s28
	s_and_b32 s28, s60, 0x7fffffff
	s_max_u32 s24, s24, s28
	s_and_b32 s28, s61, 0x7fffffff
	s_max_u32 s24, s24, s28
	s_and_b32 s28, s62, 0x7fffffff
	s_max_u32 s24, s24, s28
	s_and_b32 s28, s63, 0x7fffffff
	s_max_u32 s24, s24, s28
	s_and_b32 s28, s64, 0x7fffffff
	s_max_u32 s24, s24, s28
	s_and_b32 s28, s65, 0x7fffffff
	s_max_u32 s24, s24, s28
	s_and_b32 s28, s66, 0x7fffffff
	s_max_u32 s24, s24, s28
	s_and_b32 s28, s67, 0x7fffffff
	s_max_u32 s24, s24, s28
	s_load_dwordx16 s[52:67], s[16:17], 0x140
	s_waitcnt lgkmcnt(0)
; __device__ __forceinline__ void phase_attn(const Params& p, int l, unsigned char* shm) {
;     ...
;   AttnEpi E; E.park = (float*)(p.ws + WS_PARK) + (size_t)blockIdx.x * 65536; E.gsub = p.in[22] + l * 128; E.lam = lamp[2 * l]; E.oml = lamp[2 * l + 1];
;   for (int it = blockIdx.x; it < 1024; it += gridDim.x) {
;     int S, tok0, h, qb;
;     if (it < 512) { S = 16384; tok0 = 16384; h = it & 7; qb = it >> 3; }
;     else { const int j = it - 512; S = 2048; h = j & 7; qb = (j >> 3) & 7; tok0 = (j >> 6) * 2048; }
;     const int g = h >> 2, q0 = qb * 256;
;     const bf16_t* rowQ = qkv + (size_t)(tok0 + q0) * QKVW; const bf16_t* seqK = qkv + (size_t)tok0 * QKVW;
;     const bf16_t* grow = gates + (size_t)(tok0 + q0) * GW + h * 128;
;     E.merged = merged + (size_t)(tok0 + q0) * DM + h * 128; E.sinkl2 = p.in[17][l * 8 + h] * LOG2E;
;     E.gate = grow; E.gq = p.in[11] + l * 128;
;     attn_body<0>(rowQ + h * 128, seqK + 1024 + g * 128, seqK + 1280 + g * 128, S / 64, q0, (char*)shm, (const float*)(p.ws + WS_ROPE), E);
;     { const int t_lo = max(0, 4 * qb - 2), t_hi = min(S / 64, 4 * qb + 6);
;       const bf16_t* kb = seqK + (size_t)t_lo * 64 * QKVW;
;       E.gate = grow + 1024; E.gq = p.in[13] + l * 128;
;       attn_body<1>(rowQ + 1536 + h * 128, kb + 2560 + g * 128, kb + 2816 + g * 128, t_hi - t_lo, t_lo * 64 - q0, (char*)shm, lutall + h * 259, E); }
;     E.gate = grow + 2048; E.gq = p.in[15] + l * 64;
;     attn_body<2>(rowQ + 3072 + h * 128, seqK + 4096 + g * 128, seqK + 4352 + g * 128, S / 64, -q0, (char*)shm, lutall + (8 + h) * 259, E);
	s_and_b32 s28, s52, 0x7fffffff
	s_max_u32 s24, s24, s28
	s_and_b32 s28, s53, 0x7fffffff
	s_max_u32 s24, s24, s28
	s_and_b32 s28, s54, 0x7fffffff
	s_max_u32 s24, s24, s28
	s_and_b32 s28, s55, 0x7fffffff
	s_max_u32 s24, s24, s28
	s_and_b32 s28, s56, 0x7fffffff
	s_max_u32 s24, s24, s28
	s_and_b32 s28, s57, 0x7fffffff
	s_max_u32 s24, s24, s28
	s_and_b32 s28, s58, 0x7fffffff
	s_max_u32 s24, s24, s28
	s_and_b32 s28, s59, 0x7fffffff
	s_max_u32 s24, s24, s28
	s_and_b32 s28, s60, 0x7fffffff
	s_max_u32 s24, s24, s28
	s_and_b32 s28, s61, 0x7fffffff
	s_max_u32 s24, s24, s28
	s_and_b32 s28, s62, 0x7fffffff
	s_max_u32 s24, s24, s28
	s_and_b32 s28, s63, 0x7fffffff
	s_max_u32 s24, s24, s28
	s_and_b32 s28, s64, 0x7fffffff
	s_max_u32 s24, s24, s28
	s_and_b32 s28, s65, 0x7fffffff
	s_max_u32 s24, s24, s28
	s_and_b32 s28, s66, 0x7fffffff
	s_max_u32 s24, s24, s28
	s_and_b32 s28, s67, 0x7fffffff
	s_max_u32 s24, s24, s28
	s_load_dwordx16 s[52:67], s[16:17], 0x180
	s_waitcnt lgkmcnt(0)
	s_and_b32 s28, s52, 0x7fffffff
	s_max_u32 s24, s24, s28
	s_and_b32 s28, s53, 0x7fffffff
	s_max_u32 s24, s24, s28
	s_and_b32 s28, s54, 0x7fffffff
	s_max_u32 s24, s24, s28
	s_and_b32 s28, s55, 0x7fffffff
	s_max_u32 s24, s24, s28
	s_and_b32 s28, s56, 0x7fffffff
	s_max_u32 s24, s24, s28
	s_and_b32 s28, s57, 0x7fffffff
	s_max_u32 s24, s24, s28
	s_and_b32 s28, s58, 0x7fffffff
	s_max_u32 s24, s24, s28
	s_and_b32 s28, s59, 0x7fffffff
	s_max_u32 s24, s24, s28
	s_and_b32 s28, s60, 0x7fffffff
	s_max_u32 s24, s24, s28
	s_and_b32 s28, s61, 0x7fffffff
	s_max_u32 s24, s24, s28
	s_and_b32 s28, s62, 0x7fffffff
	s_max_u32 s24, s24, s28
	s_and_b32 s28, s63, 0x7fffffff
	s_max_u32 s24, s24, s28
	s_and_b32 s28, s64, 0x7fffffff
	s_max_u32 s24, s24, s28
	s_and_b32 s28, s65, 0x7fffffff
	s_max_u32 s24, s24, s28
	s_and_b32 s28, s66, 0x7fffffff
	s_max_u32 s24, s24, s28
	s_and_b32 s28, s67, 0x7fffffff
	s_max_u32 s24, s24, s28
	s_load_dwordx16 s[52:67], s[16:17], 0x1c0
	s_waitcnt lgkmcnt(0)
	s_and_b32 s28, s52, 0x7fffffff
	s_max_u32 s24, s24, s28
	s_and_b32 s28, s53, 0x7fffffff
	s_max_u32 s24, s24, s28
	s_and_b32 s28, s54, 0x7fffffff
	s_max_u32 s24, s24, s28
	s_and_b32 s28, s55, 0x7fffffff
	s_max_u32 s24, s24, s28
	s_and_b32 s28, s56, 0x7fffffff
	s_max_u32 s24, s24, s28
	s_and_b32 s28, s57, 0x7fffffff
	s_max_u32 s24, s24, s28
	s_and_b32 s28, s58, 0x7fffffff
	s_max_u32 s24, s24, s28
	s_and_b32 s28, s59, 0x7fffffff
	s_max_u32 s24, s24, s28
	s_and_b32 s28, s60, 0x7fffffff
	s_max_u32 s24, s24, s28
	s_and_b32 s28, s61, 0x7fffffff
	s_max_u32 s24, s24, s28
	s_and_b32 s28, s62, 0x7fffffff
	s_max_u32 s24, s24, s28
	s_and_b32 s28, s63, 0x7fffffff
	s_max_u32 s24, s24, s28
	s_and_b32 s28, s64, 0x7fffffff
	s_max_u32 s24, s24, s28
	s_and_b32 s28, s65, 0x7fffffff
	s_max_u32 s24, s24, s28
	s_and_b32 s28, s66, 0x7fffffff
	s_max_u32 s24, s24, s28
	s_and_b32 s28, s67, 0x7fffffff
	s_max_u32 s24, s24, s28
	s_load_dwordx16 s[52:67], s[18:19], 0x0
	s_waitcnt lgkmcnt(0)
	s_and_b32 s28, s52, 0x7fffffff
	s_max_u32 s25, s25, s28
	s_and_b32 s28, s53, 0x7fffffff
	s_max_u32 s25, s25, s28
	s_and_b32 s28, s54, 0x7fffffff
	s_max_u32 s25, s25, s28
	s_and_b32 s28, s55, 0x7fffffff
	s_max_u32 s25, s25, s28
	s_and_b32 s28, s56, 0x7fffffff
	s_max_u32 s25, s25, s28
	s_and_b32 s28, s57, 0x7fffffff
	s_max_u32 s25, s25, s28
	s_and_b32 s28, s58, 0x7fffffff
	s_max_u32 s25, s25, s28
	s_and_b32 s28, s59, 0x7fffffff
	s_max_u32 s25, s25, s28
	s_and_b32 s28, s60, 0x7fffffff
	s_max_u32 s25, s25, s28
	s_and_b32 s28, s61, 0x7fffffff
	s_max_u32 s25, s25, s28
	s_and_b32 s28, s62, 0x7fffffff
	s_max_u32 s25, s25, s28
	s_and_b32 s28, s63, 0x7fffffff
	s_max_u32 s25, s25, s28
	s_and_b32 s28, s64, 0x7fffffff
	s_max_u32 s25, s25, s28
	s_and_b32 s28, s65, 0x7fffffff
	s_max_u32 s25, s25, s28
	s_and_b32 s28, s66, 0x7fffffff
	s_max_u32 s25, s25, s28
	s_and_b32 s28, s67, 0x7fffffff
	s_max_u32 s25, s25, s28
	s_load_dwordx16 s[52:67], s[18:19], 0x40
	s_waitcnt lgkmcnt(0)
	s_and_b32 s28, s52, 0x7fffffff
	s_max_u32 s25, s25, s28
	s_and_b32 s28, s53, 0x7fffffff
	s_max_u32 s25, s25, s28
	s_and_b32 s28, s54, 0x7fffffff
	s_max_u32 s25, s25, s28
	s_and_b32 s28, s55, 0x7fffffff
	s_max_u32 s25, s25, s28
	s_and_b32 s28, s56, 0x7fffffff
	s_max_u32 s25, s25, s28
	s_and_b32 s28, s57, 0x7fffffff
	s_max_u32 s25, s25, s28
	s_and_b32 s28, s58, 0x7fffffff
	s_max_u32 s25, s25, s28
	s_and_b32 s28, s59, 0x7fffffff
	s_max_u32 s25, s25, s28
	s_and_b32 s28, s60, 0x7fffffff
	s_max_u32 s25, s25, s28
	s_and_b32 s28, s61, 0x7fffffff
	s_max_u32 s25, s25, s28
	s_and_b32 s28, s62, 0x7fffffff
	s_max_u32 s25, s25, s28
	s_and_b32 s28, s63, 0x7fffffff
	s_max_u32 s25, s25, s28
	s_and_b32 s28, s64, 0x7fffffff
	s_max_u32 s25, s25, s28
	s_and_b32 s28, s65, 0x7fffffff
	s_max_u32 s25, s25, s28
	s_and_b32 s28, s66, 0x7fffffff
	s_max_u32 s25, s25, s28
	s_and_b32 s28, s67, 0x7fffffff
	s_max_u32 s25, s25, s28
	s_load_dwordx16 s[52:67], s[18:19], 0x80
	s_waitcnt lgkmcnt(0)
	s_and_b32 s28, s52, 0x7fffffff
	s_max_u32 s25, s25, s28
	s_and_b32 s28, s53, 0x7fffffff
	s_max_u32 s25, s25, s28
	s_and_b32 s28, s54, 0x7fffffff
	s_max_u32 s25, s25, s28
	s_and_b32 s28, s55, 0x7fffffff
	s_max_u32 s25, s25, s28
	s_and_b32 s28, s56, 0x7fffffff
	s_max_u32 s25, s25, s28
	s_and_b32 s28, s57, 0x7fffffff
	s_max_u32 s25, s25, s28
	s_and_b32 s28, s58, 0x7fffffff
	s_max_u32 s25, s25, s28
	s_and_b32 s28, s59, 0x7fffffff
	s_max_u32 s25, s25, s28
	s_and_b32 s28, s60, 0x7fffffff
	s_max_u32 s25, s25, s28
	s_and_b32 s28, s61, 0x7fffffff
	s_max_u32 s25, s25, s28
	s_and_b32 s28, s62, 0x7fffffff
	s_max_u32 s25, s25, s28
	s_and_b32 s28, s63, 0x7fffffff
	s_max_u32 s25, s25, s28
	s_and_b32 s28, s64, 0x7fffffff
	s_max_u32 s25, s25, s28
	s_and_b32 s28, s65, 0x7fffffff
	s_max_u32 s25, s25, s28
	s_and_b32 s28, s66, 0x7fffffff
	s_max_u32 s25, s25, s28
	s_and_b32 s28, s67, 0x7fffffff
	s_max_u32 s25, s25, s28
	s_load_dwordx16 s[52:67], s[18:19], 0xc0
	s_waitcnt lgkmcnt(0)
; __device__ __forceinline__ void phase_attn(const Params& p, int l, unsigned char* shm) {
;     ...
;   AttnEpi E; E.park = (float*)(p.ws + WS_PARK) + (size_t)blockIdx.x * 65536; E.gsub = p.in[22] + l * 128; E.lam = lamp[2 * l]; E.oml = lamp[2 * l + 1];
;   for (int it = blockIdx.x; it < 1024; it += gridDim.x) {
;     int S, tok0, h, qb;
;     if (it < 512) { S = 16384; tok0 = 16384; h = it & 7; qb = it >> 3; }
;     else { const int j = it - 512; S = 2048; h = j & 7; qb = (j >> 3) & 7; tok0 = (j >> 6) * 2048; }
;     const int g = h >> 2, q0 = qb * 256;
;     const bf16_t* rowQ = qkv + (size_t)(tok0 + q0) * QKVW; const bf16_t* seqK = qkv + (size_t)tok0 * QKVW;
;     const bf16_t* grow = gates + (size_t)(tok0 + q0) * GW + h * 128;
;     E.merged = merged + (size_t)(tok0 + q0) * DM + h * 128; E.sinkl2 = p.in[17][l * 8 + h] * LOG2E;
;     E.gate = grow; E.gq = p.in[11] + l * 128;
;     attn_body<0>(rowQ + h * 128, seqK + 1024 + g * 128, seqK + 1280 + g * 128, S / 64, q0, (char*)shm, (const float*)(p.ws + WS_ROPE), E);
;     { const int t_lo = max(0, 4 * qb - 2), t_hi = min(S / 64, 4 * qb + 6);
;       const bf16_t* kb = seqK + (size_t)t_lo * 64 * QKVW;
;       E.gate = grow + 1024; E.gq = p.in[13] + l * 128;
;       attn_body<1>(rowQ + 1536 + h * 128, kb + 2560 + g * 128, kb + 2816 + g * 128, t_hi - t_lo, t_lo * 64 - q0, (char*)shm, lutall + h * 259, E); }
;     E.gate = grow + 2048; E.gq = p.in[15] + l * 64;
;     attn_body<2>(rowQ + 3072 + h * 128, seqK + 4096 + g * 128, seqK + 4352 + g * 128, S / 64, -q0, (char*)shm, lutall + (8 + h) * 259, E);
	s_and_b32 s28, s52, 0x7fffffff
	s_max_u32 s25, s25, s28
	s_and_b32 s28, s53, 0x7fffffff
	s_max_u32 s25, s25, s28
	s_and_b32 s28, s54, 0x7fffffff
	s_max_u32 s25, s25, s28
	s_and_b32 s28, s55, 0x7fffffff
	s_max_u32 s25, s25, s28
	s_and_b32 s28, s56, 0x7fffffff
	s_max_u32 s25, s25, s28
	s_and_b32 s28, s57, 0x7fffffff
	s_max_u32 s25, s25, s28
	s_and_b32 s28, s58, 0x7fffffff
	s_max_u32 s25, s25, s28
	s_and_b32 s28, s59, 0x7fffffff
	s_max_u32 s25, s25, s28
	s_and_b32 s28, s60, 0x7fffffff
	s_max_u32 s25, s25, s28
	s_and_b32 s28, s61, 0x7fffffff
	s_max_u32 s25, s25, s28
	s_and_b32 s28, s62, 0x7fffffff
	s_max_u32 s25, s25, s28
	s_and_b32 s28, s63, 0x7fffffff
	s_max_u32 s25, s25, s28
	s_and_b32 s28, s64, 0x7fffffff
	s_max_u32 s25, s25, s28
	s_and_b32 s28, s65, 0x7fffffff
	s_max_u32 s25, s25, s28
	s_and_b32 s28, s66, 0x7fffffff
	s_max_u32 s25, s25, s28
	s_and_b32 s28, s67, 0x7fffffff
	s_max_u32 s25, s25, s28
	s_load_dwordx16 s[52:67], s[18:19], 0x100
	s_waitcnt lgkmcnt(0)
	s_and_b32 s28, s52, 0x7fffffff
	s_max_u32 s25, s25, s28
	s_and_b32 s28, s53, 0x7fffffff
	s_max_u32 s25, s25, s28
	s_and_b32 s28, s54, 0x7fffffff
	s_max_u32 s25, s25, s28
	s_and_b32 s28, s55, 0x7fffffff
	s_max_u32 s25, s25, s28
	s_and_b32 s28, s56, 0x7fffffff
	s_max_u32 s25, s25, s28
	s_and_b32 s28, s57, 0x7fffffff
	s_max_u32 s25, s25, s28
	s_and_b32 s28, s58, 0x7fffffff
	s_max_u32 s25, s25, s28
	s_and_b32 s28, s59, 0x7fffffff
	s_max_u32 s25, s25, s28
	s_and_b32 s28, s60, 0x7fffffff
	s_max_u32 s25, s25, s28
	s_and_b32 s28, s61, 0x7fffffff
	s_max_u32 s25, s25, s28
	s_and_b32 s28, s62, 0x7fffffff
	s_max_u32 s25, s25, s28
	s_and_b32 s28, s63, 0x7fffffff
	s_max_u32 s25, s25, s28
	s_and_b32 s28, s64, 0x7fffffff
	s_max_u32 s25, s25, s28
	s_and_b32 s28, s65, 0x7fffffff
	s_max_u32 s25, s25, s28
	s_and_b32 s28, s66, 0x7fffffff
	s_max_u32 s25, s25, s28
	s_and_b32 s28, s67, 0x7fffffff
	s_max_u32 s25, s25, s28
	s_load_dwordx16 s[52:67], s[18:19], 0x140
	s_waitcnt lgkmcnt(0)
	s_and_b32 s28, s52, 0x7fffffff
	s_max_u32 s25, s25, s28
	s_and_b32 s28, s53, 0x7fffffff
	s_max_u32 s25, s25, s28
	s_and_b32 s28, s54, 0x7fffffff
	s_max_u32 s25, s25, s28
	s_and_b32 s28, s55, 0x7fffffff
	s_max_u32 s25, s25, s28
	s_and_b32 s28, s56, 0x7fffffff
	s_max_u32 s25, s25, s28
	s_and_b32 s28, s57, 0x7fffffff
	s_max_u32 s25, s25, s28
	s_and_b32 s28, s58, 0x7fffffff
	s_max_u32 s25, s25, s28
	s_and_b32 s28, s59, 0x7fffffff
	s_max_u32 s25, s25, s28
	s_and_b32 s28, s60, 0x7fffffff
	s_max_u32 s25, s25, s28
	s_and_b32 s28, s61, 0x7fffffff
	s_max_u32 s25, s25, s28
	s_and_b32 s28, s62, 0x7fffffff
	s_max_u32 s25, s25, s28
	s_and_b32 s28, s63, 0x7fffffff
	s_max_u32 s25, s25, s28
	s_and_b32 s28, s64, 0x7fffffff
	s_max_u32 s25, s25, s28
	s_and_b32 s28, s65, 0x7fffffff
	s_max_u32 s25, s25, s28
	s_and_b32 s28, s66, 0x7fffffff
	s_max_u32 s25, s25, s28
	s_and_b32 s28, s67, 0x7fffffff
	s_max_u32 s25, s25, s28
	s_load_dwordx16 s[52:67], s[18:19], 0x180
	s_waitcnt lgkmcnt(0)
	s_and_b32 s28, s52, 0x7fffffff
	s_max_u32 s25, s25, s28
	s_and_b32 s28, s53, 0x7fffffff
	s_max_u32 s25, s25, s28
	s_and_b32 s28, s54, 0x7fffffff
	s_max_u32 s25, s25, s28
	s_and_b32 s28, s55, 0x7fffffff
	s_max_u32 s25, s25, s28
	s_and_b32 s28, s56, 0x7fffffff
	s_max_u32 s25, s25, s28
	s_and_b32 s28, s57, 0x7fffffff
	s_max_u32 s25, s25, s28
	s_and_b32 s28, s58, 0x7fffffff
	s_max_u32 s25, s25, s28
	s_and_b32 s28, s59, 0x7fffffff
	s_max_u32 s25, s25, s28
	s_and_b32 s28, s60, 0x7fffffff
	s_max_u32 s25, s25, s28
	s_and_b32 s28, s61, 0x7fffffff
	s_max_u32 s25, s25, s28
	s_and_b32 s28, s62, 0x7fffffff
	s_max_u32 s25, s25, s28
	s_and_b32 s28, s63, 0x7fffffff
	s_max_u32 s25, s25, s28
	s_and_b32 s28, s64, 0x7fffffff
	s_max_u32 s25, s25, s28
	s_and_b32 s28, s65, 0x7fffffff
	s_max_u32 s25, s25, s28
	s_and_b32 s28, s66, 0x7fffffff
	s_max_u32 s25, s25, s28
	s_and_b32 s28, s67, 0x7fffffff
	s_max_u32 s25, s25, s28
	s_load_dwordx16 s[52:67], s[18:19], 0x1c0
	s_waitcnt lgkmcnt(0)
	s_and_b32 s28, s52, 0x7fffffff
	s_max_u32 s25, s25, s28
	s_and_b32 s28, s53, 0x7fffffff
	s_max_u32 s25, s25, s28
	s_and_b32 s28, s54, 0x7fffffff
	s_max_u32 s25, s25, s28
	s_and_b32 s28, s55, 0x7fffffff
	s_max_u32 s25, s25, s28
	s_and_b32 s28, s56, 0x7fffffff
	s_max_u32 s25, s25, s28
	s_and_b32 s28, s57, 0x7fffffff
	s_max_u32 s25, s25, s28
	s_and_b32 s28, s58, 0x7fffffff
	s_max_u32 s25, s25, s28
	s_and_b32 s28, s59, 0x7fffffff
	s_max_u32 s25, s25, s28
	s_and_b32 s28, s60, 0x7fffffff
	s_max_u32 s25, s25, s28
	s_and_b32 s28, s61, 0x7fffffff
	s_max_u32 s25, s25, s28
	s_and_b32 s28, s62, 0x7fffffff
	s_max_u32 s25, s25, s28
	s_and_b32 s28, s63, 0x7fffffff
	s_max_u32 s25, s25, s28
	s_and_b32 s28, s64, 0x7fffffff
	s_max_u32 s25, s25, s28
	s_and_b32 s28, s65, 0x7fffffff
	s_max_u32 s25, s25, s28
	s_and_b32 s28, s66, 0x7fffffff
	s_max_u32 s25, s25, s28
	s_and_b32 s28, s67, 0x7fffffff
	s_max_u32 s25, s25, s28
	s_load_dwordx16 s[52:67], s[20:21], 0x0
	s_waitcnt lgkmcnt(0)
	s_and_b32 s28, s52, 0x7fffffff
	s_max_u32 s26, s26, s28
	s_and_b32 s28, s53, 0x7fffffff
	s_max_u32 s26, s26, s28
	s_and_b32 s28, s54, 0x7fffffff
	s_max_u32 s26, s26, s28
	s_and_b32 s28, s55, 0x7fffffff
	s_max_u32 s26, s26, s28
	s_and_b32 s28, s56, 0x7fffffff
	s_max_u32 s26, s26, s28
	s_and_b32 s28, s57, 0x7fffffff
	s_max_u32 s26, s26, s28
	s_and_b32 s28, s58, 0x7fffffff
	s_max_u32 s26, s26, s28
	s_and_b32 s28, s59, 0x7fffffff
	s_max_u32 s26, s26, s28
	s_and_b32 s28, s60, 0x7fffffff
	s_max_u32 s26, s26, s28
	s_and_b32 s28, s61, 0x7fffffff
	s_max_u32 s26, s26, s28
	s_and_b32 s28, s62, 0x7fffffff
	s_max_u32 s26, s26, s28
	s_and_b32 s28, s63, 0x7fffffff
	s_max_u32 s26, s26, s28
	s_and_b32 s28, s64, 0x7fffffff
	s_max_u32 s26, s26, s28
	s_and_b32 s28, s65, 0x7fffffff
	s_max_u32 s26, s26, s28
	s_and_b32 s28, s66, 0x7fffffff
	s_max_u32 s26, s26, s28
	s_and_b32 s28, s67, 0x7fffffff
	s_max_u32 s26, s26, s28
	s_load_dwordx16 s[52:67], s[20:21], 0x40
	s_waitcnt lgkmcnt(0)
; __device__ __forceinline__ void phase_attn(const Params& p, int l, unsigned char* shm) {
;     ...
;   AttnEpi E; E.park = (float*)(p.ws + WS_PARK) + (size_t)blockIdx.x * 65536; E.gsub = p.in[22] + l * 128; E.lam = lamp[2 * l]; E.oml = lamp[2 * l + 1];
;   for (int it = blockIdx.x; it < 1024; it += gridDim.x) {
;     int S, tok0, h, qb;
;     if (it < 512) { S = 16384; tok0 = 16384; h = it & 7; qb = it >> 3; }
;     else { const int j = it - 512; S = 2048; h = j & 7; qb = (j >> 3) & 7; tok0 = (j >> 6) * 2048; }
;     const int g = h >> 2, q0 = qb * 256;
;     const bf16_t* rowQ = qkv + (size_t)(tok0 + q0) * QKVW; const bf16_t* seqK = qkv + (size_t)tok0 * QKVW;
;     const bf16_t* grow = gates + (size_t)(tok0 + q0) * GW + h * 128;
;     E.merged = merged + (size_t)(tok0 + q0) * DM + h * 128; E.sinkl2 = p.in[17][l * 8 + h] * LOG2E;
;     E.gate = grow; E.gq = p.in[11] + l * 128;
;     attn_body<0>(rowQ + h * 128, seqK + 1024 + g * 128, seqK + 1280 + g * 128, S / 64, q0, (char*)shm, (const float*)(p.ws + WS_ROPE), E);
;     { const int t_lo = max(0, 4 * qb - 2), t_hi = min(S / 64, 4 * qb + 6);
;       const bf16_t* kb = seqK + (size_t)t_lo * 64 * QKVW;
;       E.gate = grow + 1024; E.gq = p.in[13] + l * 128;
;       attn_body<1>(rowQ + 1536 + h * 128, kb + 2560 + g * 128, kb + 2816 + g * 128, t_hi - t_lo, t_lo * 64 - q0, (char*)shm, lutall + h * 259, E); }
;     E.gate = grow + 2048; E.gq = p.in[15] + l * 64;
;     attn_body<2>(rowQ + 3072 + h * 128, seqK + 4096 + g * 128, seqK + 4352 + g * 128, S / 64, -q0, (char*)shm, lutall + (8 + h) * 259, E);
	s_and_b32 s28, s52, 0x7fffffff
	s_max_u32 s26, s26, s28
	s_and_b32 s28, s53, 0x7fffffff
	s_max_u32 s26, s26, s28
	s_and_b32 s28, s54, 0x7fffffff
	s_max_u32 s26, s26, s28
	s_and_b32 s28, s55, 0x7fffffff
	s_max_u32 s26, s26, s28
	s_and_b32 s28, s56, 0x7fffffff
	s_max_u32 s26, s26, s28
	s_and_b32 s28, s57, 0x7fffffff
	s_max_u32 s26, s26, s28
	s_and_b32 s28, s58, 0x7fffffff
	s_max_u32 s26, s26, s28
	s_and_b32 s28, s59, 0x7fffffff
	s_max_u32 s26, s26, s28
	s_and_b32 s28, s60, 0x7fffffff
	s_max_u32 s26, s26, s28
	s_and_b32 s28, s61, 0x7fffffff
	s_max_u32 s26, s26, s28
	s_and_b32 s28, s62, 0x7fffffff
	s_max_u32 s26, s26, s28
	s_and_b32 s28, s63, 0x7fffffff
	s_max_u32 s26, s26, s28
	s_and_b32 s28, s64, 0x7fffffff
	s_max_u32 s26, s26, s28
	s_and_b32 s28, s65, 0x7fffffff
	s_max_u32 s26, s26, s28
	s_and_b32 s28, s66, 0x7fffffff
	s_max_u32 s26, s26, s28
	s_and_b32 s28, s67, 0x7fffffff
	s_max_u32 s26, s26, s28
	s_load_dwordx16 s[52:67], s[20:21], 0x80
	s_waitcnt lgkmcnt(0)
	s_and_b32 s28, s52, 0x7fffffff
	s_max_u32 s26, s26, s28
	s_and_b32 s28, s53, 0x7fffffff
	s_max_u32 s26, s26, s28
	s_and_b32 s28, s54, 0x7fffffff
	s_max_u32 s26, s26, s28
	s_and_b32 s28, s55, 0x7fffffff
	s_max_u32 s26, s26, s28
	s_and_b32 s28, s56, 0x7fffffff
	s_max_u32 s26, s26, s28
	s_and_b32 s28, s57, 0x7fffffff
	s_max_u32 s26, s26, s28
	s_and_b32 s28, s58, 0x7fffffff
	s_max_u32 s26, s26, s28
	s_and_b32 s28, s59, 0x7fffffff
	s_max_u32 s26, s26, s28
	s_and_b32 s28, s60, 0x7fffffff
	s_max_u32 s26, s26, s28
	s_and_b32 s28, s61, 0x7fffffff
	s_max_u32 s26, s26, s28
	s_and_b32 s28, s62, 0x7fffffff
	s_max_u32 s26, s26, s28
	s_and_b32 s28, s63, 0x7fffffff
	s_max_u32 s26, s26, s28
	s_and_b32 s28, s64, 0x7fffffff
	s_max_u32 s26, s26, s28
	s_and_b32 s28, s65, 0x7fffffff
	s_max_u32 s26, s26, s28
	s_and_b32 s28, s66, 0x7fffffff
	s_max_u32 s26, s26, s28
	s_and_b32 s28, s67, 0x7fffffff
	s_max_u32 s26, s26, s28
	s_load_dwordx16 s[52:67], s[20:21], 0xc0
	s_waitcnt lgkmcnt(0)
	s_and_b32 s28, s52, 0x7fffffff
	s_max_u32 s26, s26, s28
	s_and_b32 s28, s53, 0x7fffffff
	s_max_u32 s26, s26, s28
	s_and_b32 s28, s54, 0x7fffffff
	s_max_u32 s26, s26, s28
	s_and_b32 s28, s55, 0x7fffffff
	s_max_u32 s26, s26, s28
	s_and_b32 s28, s56, 0x7fffffff
	s_max_u32 s26, s26, s28
	s_and_b32 s28, s57, 0x7fffffff
	s_max_u32 s26, s26, s28
	s_and_b32 s28, s58, 0x7fffffff
	s_max_u32 s26, s26, s28
	s_and_b32 s28, s59, 0x7fffffff
	s_max_u32 s26, s26, s28
	s_and_b32 s28, s60, 0x7fffffff
	s_max_u32 s26, s26, s28
	s_and_b32 s28, s61, 0x7fffffff
	s_max_u32 s26, s26, s28
	s_and_b32 s28, s62, 0x7fffffff
	s_max_u32 s26, s26, s28
	s_and_b32 s28, s63, 0x7fffffff
	s_max_u32 s26, s26, s28
	s_and_b32 s28, s64, 0x7fffffff
	s_max_u32 s26, s26, s28
	s_and_b32 s28, s65, 0x7fffffff
	s_max_u32 s26, s26, s28
	s_and_b32 s28, s66, 0x7fffffff
	s_max_u32 s26, s26, s28
	s_and_b32 s28, s67, 0x7fffffff
	s_max_u32 s26, s26, s28
	s_load_dwordx16 s[52:67], s[22:23], 0x0
	s_waitcnt lgkmcnt(0)
	s_and_b32 s28, s52, 0x7fffffff
	s_max_u32 s27, s27, s28
	s_and_b32 s28, s53, 0x7fffffff
	s_max_u32 s27, s27, s28
	s_and_b32 s28, s54, 0x7fffffff
	s_max_u32 s27, s27, s28
	s_and_b32 s28, s55, 0x7fffffff
	s_max_u32 s27, s27, s28
	s_and_b32 s28, s56, 0x7fffffff
	s_max_u32 s27, s27, s28
	s_and_b32 s28, s57, 0x7fffffff
	s_max_u32 s27, s27, s28
	s_and_b32 s28, s58, 0x7fffffff
	s_max_u32 s27, s27, s28
	s_and_b32 s28, s59, 0x7fffffff
	s_max_u32 s27, s27, s28
	s_and_b32 s28, s60, 0x7fffffff
	s_max_u32 s27, s27, s28
	s_and_b32 s28, s61, 0x7fffffff
	s_max_u32 s27, s27, s28
	s_and_b32 s28, s62, 0x7fffffff
	s_max_u32 s27, s27, s28
	s_and_b32 s28, s63, 0x7fffffff
	s_max_u32 s27, s27, s28
	s_and_b32 s28, s64, 0x7fffffff
	s_max_u32 s27, s27, s28
	s_and_b32 s28, s65, 0x7fffffff
	s_max_u32 s27, s27, s28
	s_and_b32 s28, s66, 0x7fffffff
	s_max_u32 s27, s27, s28
	s_and_b32 s28, s67, 0x7fffffff
	s_max_u32 s27, s27, s28
	s_load_dwordx16 s[52:67], s[22:23], 0x40
	s_waitcnt lgkmcnt(0)
	s_and_b32 s28, s52, 0x7fffffff
	s_max_u32 s27, s27, s28
	s_and_b32 s28, s53, 0x7fffffff
	s_max_u32 s27, s27, s28
	s_and_b32 s28, s54, 0x7fffffff
	s_max_u32 s27, s27, s28
	s_and_b32 s28, s55, 0x7fffffff
	s_max_u32 s27, s27, s28
	s_and_b32 s28, s56, 0x7fffffff
	s_max_u32 s27, s27, s28
	s_and_b32 s28, s57, 0x7fffffff
	s_max_u32 s27, s27, s28
	s_and_b32 s28, s58, 0x7fffffff
	s_max_u32 s27, s27, s28
	s_and_b32 s28, s59, 0x7fffffff
	s_max_u32 s27, s27, s28
	s_and_b32 s28, s60, 0x7fffffff
	s_max_u32 s27, s27, s28
	s_and_b32 s28, s61, 0x7fffffff
	s_max_u32 s27, s27, s28
	s_and_b32 s28, s62, 0x7fffffff
	s_max_u32 s27, s27, s28
	s_and_b32 s28, s63, 0x7fffffff
	s_max_u32 s27, s27, s28
	s_and_b32 s28, s64, 0x7fffffff
	s_max_u32 s27, s27, s28
	s_and_b32 s28, s65, 0x7fffffff
	s_max_u32 s27, s27, s28
	s_and_b32 s28, s66, 0x7fffffff
	s_max_u32 s27, s27, s28
	s_and_b32 s28, s67, 0x7fffffff
	s_max_u32 s27, s27, s28
	s_load_dwordx16 s[52:67], s[22:23], 0x80
	s_waitcnt lgkmcnt(0)
; __device__ __forceinline__ void phase_attn(const Params& p, int l, unsigned char* shm) {
;     ...
;   const float* lutall = (const float*)(p.ws + WS_LUT); const float* lamp = (const float*)(p.ws + WS_LAM);
;   AttnEpi E; E.park = (float*)(p.ws + WS_PARK) + (size_t)blockIdx.x * 65536; E.gsub = p.in[22] + l * 128; E.lam = lamp[2 * l]; E.oml = lamp[2 * l + 1];
;   for (int it = blockIdx.x; it < 1024; it += gridDim.x) {
;     int S, tok0, h, qb;
;     if (it < 512) { S = 16384; tok0 = 16384; h = it & 7; qb = it >> 3; }
;     else { const int j = it - 512; S = 2048; h = j & 7; qb = (j >> 3) & 7; tok0 = (j >> 6) * 2048; }
;     const int g = h >> 2, q0 = qb * 256;
;     const bf16_t* rowQ = qkv + (size_t)(tok0 + q0) * QKVW; const bf16_t* seqK = qkv + (size_t)tok0 * QKVW;
;     const bf16_t* grow = gates + (size_t)(tok0 + q0) * GW + h * 128;
;     E.merged = merged + (size_t)(tok0 + q0) * DM + h * 128; E.sinkl2 = p.in[17][l * 8 + h] * LOG2E;
;     E.gate = grow; E.gq = p.in[11] + l * 128;
;     attn_body<0>(rowQ + h * 128, seqK + 1024 + g * 128, seqK + 1280 + g * 128, S / 64, q0, (char*)shm, (const float*)(p.ws + WS_ROPE), E);
	s_and_b32 s28, s52, 0x7fffffff
	s_max_u32 s27, s27, s28
	s_and_b32 s28, s53, 0x7fffffff
	s_max_u32 s27, s27, s28
	s_and_b32 s28, s54, 0x7fffffff
	s_max_u32 s27, s27, s28
	s_and_b32 s28, s55, 0x7fffffff
	s_max_u32 s27, s27, s28
	s_and_b32 s28, s56, 0x7fffffff
	s_max_u32 s27, s27, s28
	s_and_b32 s28, s57, 0x7fffffff
	s_max_u32 s27, s27, s28
	s_and_b32 s28, s58, 0x7fffffff
	s_max_u32 s27, s27, s28
	s_and_b32 s28, s59, 0x7fffffff
	s_max_u32 s27, s27, s28
	s_and_b32 s28, s60, 0x7fffffff
	s_max_u32 s27, s27, s28
	s_and_b32 s28, s61, 0x7fffffff
	s_max_u32 s27, s27, s28
	s_and_b32 s28, s62, 0x7fffffff
	s_max_u32 s27, s27, s28
	s_and_b32 s28, s63, 0x7fffffff
	s_max_u32 s27, s27, s28
	s_and_b32 s28, s64, 0x7fffffff
	s_max_u32 s27, s27, s28
	s_and_b32 s28, s65, 0x7fffffff
	s_max_u32 s27, s27, s28
	s_and_b32 s28, s66, 0x7fffffff
	s_max_u32 s27, s27, s28
	s_and_b32 s28, s67, 0x7fffffff
	s_max_u32 s27, s27, s28
	s_load_dwordx16 s[52:67], s[22:23], 0xc0
	s_waitcnt lgkmcnt(0)
	s_and_b32 s28, s52, 0x7fffffff
	s_max_u32 s27, s27, s28
	s_and_b32 s28, s53, 0x7fffffff
	s_max_u32 s27, s27, s28
	s_and_b32 s28, s54, 0x7fffffff
	s_max_u32 s27, s27, s28
	s_and_b32 s28, s55, 0x7fffffff
	s_max_u32 s27, s27, s28
	s_and_b32 s28, s56, 0x7fffffff
	s_max_u32 s27, s27, s28
	s_and_b32 s28, s57, 0x7fffffff
	s_max_u32 s27, s27, s28
	s_and_b32 s28, s58, 0x7fffffff
	s_max_u32 s27, s27, s28
	s_and_b32 s28, s59, 0x7fffffff
	s_max_u32 s27, s27, s28
	s_and_b32 s28, s60, 0x7fffffff
	s_max_u32 s27, s27, s28
	s_and_b32 s28, s61, 0x7fffffff
	s_max_u32 s27, s27, s28
	s_and_b32 s28, s62, 0x7fffffff
	s_max_u32 s27, s27, s28
	s_and_b32 s28, s63, 0x7fffffff
	s_max_u32 s27, s27, s28
	s_and_b32 s28, s64, 0x7fffffff
	s_max_u32 s27, s27, s28
	s_and_b32 s28, s65, 0x7fffffff
	s_max_u32 s27, s27, s28
	s_and_b32 s28, s66, 0x7fffffff
	s_max_u32 s27, s27, s28
	s_and_b32 s28, s67, 0x7fffffff
	s_max_u32 s27, s27, s28
	v_mov_b32_e32 v2, s24
	v_mul_f32_e32 v2, s25, v2
	v_mul_f32_e32 v2, 0x43028f5c, v2
	v_add_f32_e32 v2, 1.0, v2
	v_mov_b32_e32 v3, s26
	v_mul_f32_e32 v3, s27, v3
	v_mul_f32_e32 v3, 0x413c5bb7, v3
	v_add_f32_e32 v3, 1.0, v3
	s_nop 0
	v_readfirstlane_b32 s28, v2
	v_readfirstlane_b32 s29, v3
	s_nop 3
	v_writelane_b32 v255, s28, 20
	v_writelane_b32 v255, s29, 21
	s_lshl_b32 s0, s12, 7
	s_ashr_i32 s1, s0, 31
	v_readlane_b32 s52, v254, 41
	s_lshl_b64 s[0:1], s[0:1], 2
	v_readlane_b32 s64, v254, 53
	v_readlane_b32 s65, v254, 54
	s_add_u32 s6, s64, s0
	s_addc_u32 s7, s65, s1
	v_readlane_b32 s13, v255, 0
	v_writelane_b32 v255, s6, 5
	v_readlane_b32 s10, v252, 47
	v_readlane_b32 s11, v252, 48
	v_writelane_b32 v255, s7, 6
	s_lshl_b32 s6, s12, 1
	s_ashr_i32 s7, s6, 31
	s_lshl_b64 s[6:7], s[6:7], 2
	s_add_u32 s6, s10, s6
	s_addc_u32 s7, s11, s7
	global_load_dwordx2 v[184:185], v1, s[6:7]
	v_readlane_b32 s53, v254, 42
	v_readlane_b32 s54, v254, 43
	v_readlane_b32 s55, v254, 44
	v_readlane_b32 s56, v254, 45
	v_readlane_b32 s57, v254, 46
	v_readlane_b32 s58, v254, 47
	v_readlane_b32 s59, v254, 48
	v_readlane_b32 s60, v254, 49
	v_readlane_b32 s61, v254, 50
	v_readlane_b32 s62, v254, 51
	v_readlane_b32 s63, v254, 52
	v_readlane_b32 s66, v254, 55
	v_readlane_b32 s67, v254, 56
	s_lshl_b32 s6, s12, 6
	v_readlane_b32 s52, v254, 25
	s_lshl_b32 s2, s12, 3
	s_ashr_i32 s7, s6, 31
	v_readlane_b32 s58, v254, 31
	v_readlane_b32 s59, v254, 32
	s_add_u32 s12, s58, s0
	v_readlane_b32 s62, v254, 35
	s_addc_u32 s13, s59, s1
	v_readlane_b32 s63, v254, 36
	s_add_u32 s42, s62, s0
	v_readlane_b32 s66, v254, 39
	s_addc_u32 s43, s63, s1
	s_lshl_b64 s[0:1], s[6:7], 2
	v_readlane_b32 s53, v254, 26
	v_readlane_b32 s67, v254, 40
	s_add_u32 s52, s66, s0
	s_addc_u32 s53, s67, s1
	v_readlane_b32 s0, v254, 16
	v_writelane_b32 v255, s2, 7
	s_mov_b32 s93, s0
	s_mov_b32 s10, s0
	v_readlane_b32 s54, v254, 27
	v_readlane_b32 s55, v254, 28
	v_readlane_b32 s56, v254, 29
	v_readlane_b32 s57, v254, 30
	v_readlane_b32 s60, v254, 33
	v_readlane_b32 s61, v254, 34
	v_readlane_b32 s64, v254, 37
	v_readlane_b32 s65, v254, 38
	v_readlane_b32 s1, v254, 17
	s_waitcnt vmcnt(0)
	v_mov_b32_e32 v186, v184
	v_mov_b32_e32 v187, v184
	s_branch .LBB0_74

; template <int MODE>
; __device__ __forceinline__ void attn_body(const bf16_t* __restrict__ Qb, const bf16_t* __restrict__ Kh, const bf16_t* __restrict__ Vh, int NT, int krel0,
;                                           char* lds, const float* __restrict__ lutg, const AttnEpi& E) {
;     ...
;   const bf16_t* Qw = Qb + (size_t)(wid * 32 + r32) * LDQK + hi * 8;
;   {
;     float qf[ND0][8]; float ss = 0.f;
; #pragma unroll
;     for (int d0 = 0; d0 < ND0; ++d0) { const bf16x8 raw = *reinterpret_cast<const bf16x8*>(Qw + d0 * 16);
; #pragma unroll
;       for (int j = 0; j < 8; ++j) { const float v = __uint_as_float(((unsigned)(unsigned short)raw[j]) << 16); qf[d0][j] = v; ss += v * v; } }
;     { auto rr = __builtin_amdgcn_permlane32_swap(__float_as_uint(ss), __float_as_uint(ss), false, false);
;       ss = __uint_as_float(rr[0]) + __uint_as_float(rr[1]); }
;     const float rs = rsqrtf(ss * (MODE < 2 ? (1.f / 128.f) : (1.f / 64.f)) + EPS);
; #pragma unroll
;     for (int d0 = 0; d0 < ND0; ++d0) { const f32x4 g0 = *(const f32x4*)(E.gq + d0 * 16 + hi * 8), g1 = *(const f32x4*)(E.gq + d0 * 16 + hi * 8 + 4);
; #pragma unroll
;       for (int j = 0; j < 4; ++j) { qf[d0][j] = qf[d0][j] * rs * g0[j]; qf[d0][4 + j] = qf[d0][4 + j] * rs * g1[j]; } }
;     if constexpr (MODE == 0) {
;       const int sp = krel0 + wid * 32 + r32;
; #pragma unroll
;       for (int h = 0; h < 2; ++h) { const int pos = h == 0 ? (sp >> 6) : (sp & 63);
; #pragma unroll
;         for (int a = 0; a < 2; ++a) { const float* tb = lutg + (size_t)(pos * 32 + a * 16 + hi * 8) * 2;
; #pragma unroll
;           for (int jj = 0; jj < 4; ++jj) { const f32x4 cs = *(const f32x4*)(tb + jj * 4);
.LBB0_78:
	s_lshl_b32 s64, s58, 8
	s_and_b32 s0, s93, 4
	s_add_i32 s54, s2, s64
	s_lshl_b32 s84, s0, 6
	s_and_b32 s59, s10, 7
	s_ashr_i32 s55, s54, 31
	s_mul_i32 s1, s54, 0x2400
	v_readlane_b32 s6, v252, 6
	s_mul_hi_i32 s0, s54, 0x2400
	v_readlane_b32 s7, v252, 7
	s_add_u32 s17, s6, s1
	s_addc_u32 s18, s7, s0
	s_mul_i32 s1, s2, 0x2400
	s_mul_hi_u32 s0, s2, 0x2400
	s_add_u32 s67, s6, s1
	s_addc_u32 s65, s7, s0
	v_readlane_b32 s0, v255, 7
	s_or_b32 s0, s59, s0
	s_ashr_i32 s1, s0, 31
	v_readlane_b32 s68, v254, 41
	s_lshl_b32 s63, s59, 7
	s_lshl_b64 s[0:1], s[0:1], 2
	v_readlane_b32 s70, v254, 43
	v_readlane_b32 s71, v254, 44
	s_add_u32 s0, s70, s0
	s_addc_u32 s1, s71, s1
	global_load_dword v184, v1, s[0:1]
	s_lshl_b32 s0, s59, 8
	s_add_u32 s60, s17, s0
	v_mov_b32_e32 v188, v179
	s_addc_u32 s61, s18, 0
	s_movk_i32 s6, 0xffe0
	v_ashrrev_i32_e32 v4, 1, v188
	v_bfe_u32 v164, v188, 5, 1
	v_bfi_b32 v0, s6, v4, v188
	v_mov_b64_e32 v[2:3], s[60:61]
	s_movk_i32 s56, 0x2400
	v_mad_i64_i32 v[2:3], s[0:1], v0, s56, v[2:3]
	v_lshlrev_b32_e32 v0, 4, v164
	v_lshl_add_u64 v[2:3], v[2:3], 0, v[0:1]
	s_waitcnt lgkmcnt(0)
	s_barrier
	global_load_dwordx4 v[22:25], v[2:3], off offset:160
	global_load_dwordx4 v[48:51], v[2:3], off offset:224
	global_load_dwordx4 v[124:127], v[2:3], off offset:128
	global_load_dwordx4 v[128:131], v[2:3], off offset:192
	global_load_dwordx4 v[166:169], v[2:3], off
	global_load_dwordx4 v[170:173], v[2:3], off offset:32
	global_load_dwordx4 v[174:177], v[2:3], off offset:64
	global_load_dwordx4 v[206:209], v[2:3], off offset:96
	v_and_b32_e32 v2, 32, v188
	global_load_dwordx4 v[120:123], v2, s[12:13]
	global_load_dwordx4 v[116:119], v2, s[12:13] offset:16
	global_load_dwordx4 v[112:115], v2, s[12:13] offset:64
	global_load_dwordx4 v[108:111], v2, s[12:13] offset:80
	global_load_dwordx4 v[104:107], v2, s[12:13] offset:128
	global_load_dwordx4 v[100:103], v2, s[12:13] offset:144
	global_load_dwordx4 v[96:99], v2, s[12:13] offset:192
	global_load_dwordx4 v[92:95], v2, s[12:13] offset:208
	global_load_dwordx4 v[88:91], v2, s[12:13] offset:256
	global_load_dwordx4 v[84:87], v2, s[12:13] offset:272
	global_load_dwordx4 v[80:83], v2, s[12:13] offset:320
	global_load_dwordx4 v[76:79], v2, s[12:13] offset:336
	global_load_dwordx4 v[68:71], v2, s[12:13] offset:384
	global_load_dwordx4 v[64:67], v2, s[12:13] offset:400
	global_load_dwordx4 v[60:63], v2, s[12:13] offset:448
	global_load_dwordx4 v[52:55], v2, s[12:13] offset:464
	v_and_b32_e32 v189, 31, v188
	s_lshl_b32 s0, s10, 5
	v_and_b32_e32 v204, 0xffffffe0, v4
	v_or_b32_e32 v2, s64, v189
	s_and_b32 s62, s0, 0x80
	v_add_u32_e32 v7, v2, v204
	s_lshl_b32 s0, s62, 1
	v_lshlrev_b32_e32 v6, 3, v164
	v_ashrrev_i32_e32 v2, 1, v7
	s_add_u32 s0, s67, s0
	v_and_or_b32 v2, v2, s6, v6
	s_addc_u32 s1, s65, 0
	v_and_b32_e32 v5, 0x3fffffc0, v188
	s_add_i32 s89, 0, 0x18000
	v_ashrrev_i32_e32 v3, 31, v2
	v_lshl_add_u32 v163, v5, 2, s89
	v_lshl_add_u64 v[4:5], v[2:3], 3, s[96:97]
	global_load_dwordx4 v[30:33], v[4:5], off offset:48
	global_load_dwordx4 v[38:41], v[4:5], off offset:32
	global_load_dwordx4 v[56:59], v[4:5], off offset:16
	global_load_dwordx4 v[72:75], v[4:5], off
	v_or_b32_e32 v2, 16, v2
	v_ashrrev_i32_e32 v3, 31, v2
	v_lshl_add_u64 v[2:3], v[2:3], 3, s[96:97]
	global_load_dwordx4 v[18:21], v[2:3], off offset:48
	global_load_dwordx4 v[26:29], v[2:3], off offset:32
	global_load_dwordx4 v[34:37], v[2:3], off offset:16
	global_load_dwordx4 v[42:45], v[2:3], off
	v_lshlrev_b32_e32 v2, 5, v7
	s_movk_i32 s6, 0x7e0
	v_and_or_b32 v2, v2, s6, v6
	v_lshlrev_b32_e32 v165, 3, v2
	global_load_dwordx4 v[2:5], v165, s[96:97] offset:48
	global_load_dwordx4 v[6:9], v165, s[96:97] offset:32
	global_load_dwordx4 v[10:13], v165, s[96:97] offset:16
	global_load_dwordx4 v[14:17], v165, s[96:97]
	s_movk_i32 s57, 0x1200
	v_and_b32_e32 v162, 63, v188
	s_cmp_lg_u32 0, -1
	v_readlane_b32 s69, v254, 42
	s_mov_b32 s68, 0
	v_readlane_b32 s72, v254, 45
	v_readlane_b32 s73, v254, 46
	v_readlane_b32 s74, v254, 47
	v_readlane_b32 s75, v254, 48
	v_readlane_b32 s76, v254, 49
	v_readlane_b32 s77, v254, 50
	v_readlane_b32 s78, v254, 51
	v_readlane_b32 s79, v254, 52
	v_readlane_b32 s80, v254, 53
	v_readlane_b32 s81, v254, 54
	v_readlane_b32 s82, v254, 55
	v_readlane_b32 s83, v254, 56
	s_mov_b32 s69, s68
	s_mov_b32 s70, s68
	s_mov_b32 s71, s68
	s_mov_b32 s72, s68
	s_mov_b32 s73, s68
	s_mov_b32 s74, s68
	s_mov_b32 s75, s68
	s_mov_b32 s76, s68
	s_mov_b32 s77, s68
	s_mov_b32 s78, s68
	s_mov_b32 s79, s68
	s_mov_b32 s80, s68
	s_mov_b32 s81, s68
	s_mov_b32 s82, s68
	s_mov_b32 s83, s68
	s_mov_b32 s66, 4
	s_waitcnt vmcnt(35)
	v_and_b32_e32 v147, 0xffff0000, v22
	s_waitcnt vmcnt(31)
	v_and_b32_e32 v221, 0xffff0000, v167
	v_lshlrev_b32_e32 v220, 16, v167
	v_and_b32_e32 v167, 0xffff0000, v166
	v_lshlrev_b32_e32 v146, 16, v22
	v_lshlrev_b32_e32 v166, 16, v166
	v_mul_f32_e32 v22, v167, v167
	v_and_b32_e32 v141, 0xffff0000, v23
	v_lshlrev_b32_e32 v140, 16, v23
	v_pk_fma_f32 v[22:23], v[166:167], v[166:167], v[22:23] op_sel_hi:[1,1,0]
	v_and_b32_e32 v139, 0xffff0000, v24
	v_lshlrev_b32_e32 v138, 16, v24
	v_pk_fma_f32 v[22:23], v[220:221], v[220:221], v[22:23]
	v_mul_f32_e32 v24, v221, v221
	v_and_b32_e32 v217, 0xffff0000, v169
	v_lshlrev_b32_e32 v216, 16, v169
	v_and_b32_e32 v169, 0xffff0000, v168
	v_lshlrev_b32_e32 v168, 16, v168
	v_pk_add_f32 v[22:23], v[24:25], v[22:23] op_sel_hi:[0,1]
	v_pk_fma_f32 v[22:23], v[168:169], v[168:169], v[22:23]
	v_mul_f32_e32 v24, v169, v169
	v_pk_add_f32 v[22:23], v[24:25], v[22:23] op_sel_hi:[0,1]
	v_pk_fma_f32 v[22:23], v[216:217], v[216:217], v[22:23]
	v_mul_f32_e32 v24, v217, v217
	s_waitcnt vmcnt(30)
; template <int MODE>
; __device__ __forceinline__ void attn_body(const bf16_t* __restrict__ Qb, const bf16_t* __restrict__ Kh, const bf16_t* __restrict__ Vh, int NT, int krel0,
;                                           char* lds, const float* __restrict__ lutg, const AttnEpi& E) {
;     ...
;     float qf[ND0][8]; float ss = 0.f;
; #pragma unroll
;     for (int d0 = 0; d0 < ND0; ++d0) { const bf16x8 raw = *reinterpret_cast<const bf16x8*>(Qw + d0 * 16);
; #pragma unroll
;       for (int j = 0; j < 8; ++j) { const float v = __uint_as_float(((unsigned)(unsigned short)raw[j]) << 16); qf[d0][j] = v; ss += v * v; } }
;     { auto rr = __builtin_amdgcn_permlane32_swap(__float_as_uint(ss), __float_as_uint(ss), false, false);
;       ss = __uint_as_float(rr[0]) + __uint_as_float(rr[1]); }
;     const float rs = rsqrtf(ss * (MODE < 2 ? (1.f / 128.f) : (1.f / 64.f)) + EPS);
; #pragma unroll
;     for (int d0 = 0; d0 < ND0; ++d0) { const f32x4 g0 = *(const f32x4*)(E.gq + d0 * 16 + hi * 8), g1 = *(const f32x4*)(E.gq + d0 * 16 + hi * 8 + 4);
	v_and_b32_e32 v213, 0xffff0000, v171
	v_lshlrev_b32_e32 v212, 16, v171
	v_and_b32_e32 v171, 0xffff0000, v170
	v_lshlrev_b32_e32 v170, 16, v170
	v_pk_add_f32 v[22:23], v[24:25], v[22:23] op_sel_hi:[0,1]
	v_pk_fma_f32 v[22:23], v[170:171], v[170:171], v[22:23]
	v_mul_f32_e32 v24, v171, v171
	v_pk_add_f32 v[22:23], v[24:25], v[22:23] op_sel_hi:[0,1]
	v_pk_fma_f32 v[22:23], v[212:213], v[212:213], v[22:23]
	v_mul_f32_e32 v24, v213, v213
	v_and_b32_e32 v191, 0xffff0000, v173
	v_lshlrev_b32_e32 v190, 16, v173
	v_and_b32_e32 v173, 0xffff0000, v172
	v_lshlrev_b32_e32 v172, 16, v172
	v_pk_add_f32 v[22:23], v[24:25], v[22:23] op_sel_hi:[0,1]
	v_pk_fma_f32 v[22:23], v[172:173], v[172:173], v[22:23]
	v_mul_f32_e32 v24, v173, v173
	v_pk_add_f32 v[22:23], v[24:25], v[22:23] op_sel_hi:[0,1]
	v_pk_fma_f32 v[22:23], v[190:191], v[190:191], v[22:23]
	v_mul_f32_e32 v24, v191, v191
	s_waitcnt vmcnt(29)
	v_and_b32_e32 v223, 0xffff0000, v175
	v_lshlrev_b32_e32 v222, 16, v175
	v_and_b32_e32 v175, 0xffff0000, v174
	v_lshlrev_b32_e32 v174, 16, v174
	v_pk_add_f32 v[22:23], v[24:25], v[22:23] op_sel_hi:[0,1]
	v_pk_fma_f32 v[22:23], v[174:175], v[174:175], v[22:23]
	v_mul_f32_e32 v24, v175, v175
	v_pk_add_f32 v[22:23], v[24:25], v[22:23] op_sel_hi:[0,1]
	v_pk_fma_f32 v[22:23], v[222:223], v[222:223], v[22:23]
	v_mul_f32_e32 v24, v223, v223
	v_and_b32_e32 v219, 0xffff0000, v177
	v_lshlrev_b32_e32 v218, 16, v177
	v_and_b32_e32 v177, 0xffff0000, v176
	v_lshlrev_b32_e32 v176, 16, v176
	v_pk_add_f32 v[22:23], v[24:25], v[22:23] op_sel_hi:[0,1]
	v_pk_fma_f32 v[22:23], v[176:177], v[176:177], v[22:23]
	v_mul_f32_e32 v24, v177, v177
	v_pk_add_f32 v[22:23], v[24:25], v[22:23] op_sel_hi:[0,1]
	v_pk_fma_f32 v[22:23], v[218:219], v[218:219], v[22:23]
	v_mul_f32_e32 v24, v219, v219
	s_waitcnt vmcnt(28)
	v_and_b32_e32 v215, 0xffff0000, v207
	v_lshlrev_b32_e32 v214, 16, v207
	v_and_b32_e32 v207, 0xffff0000, v206
	v_lshlrev_b32_e32 v206, 16, v206
	v_pk_add_f32 v[22:23], v[24:25], v[22:23] op_sel_hi:[0,1]
	v_pk_fma_f32 v[22:23], v[206:207], v[206:207], v[22:23]
	v_mul_f32_e32 v24, v207, v207
	v_pk_add_f32 v[22:23], v[24:25], v[22:23] op_sel_hi:[0,1]
	v_pk_fma_f32 v[22:23], v[214:215], v[214:215], v[22:23]
	v_mul_f32_e32 v24, v215, v215
	v_and_b32_e32 v211, 0xffff0000, v209
	v_lshlrev_b32_e32 v210, 16, v209
	v_and_b32_e32 v209, 0xffff0000, v208
	v_lshlrev_b32_e32 v208, 16, v208
	v_pk_add_f32 v[22:23], v[24:25], v[22:23] op_sel_hi:[0,1]
	v_pk_fma_f32 v[22:23], v[208:209], v[208:209], v[22:23]
	v_mul_f32_e32 v24, v209, v209
	v_pk_add_f32 v[22:23], v[24:25], v[22:23] op_sel_hi:[0,1]
	v_pk_fma_f32 v[22:23], v[210:211], v[210:211], v[22:23]
	v_mul_f32_e32 v24, v211, v211
	v_and_b32_e32 v161, 0xffff0000, v124
	v_lshlrev_b32_e32 v160, 16, v124
	v_pk_add_f32 v[22:23], v[24:25], v[22:23] op_sel_hi:[0,1]
	v_pk_fma_f32 v[22:23], v[160:161], v[160:161], v[22:23]
	v_mul_f32_e32 v24, v161, v161
	v_and_b32_e32 v157, 0xffff0000, v125
	v_lshlrev_b32_e32 v156, 16, v125
	v_pk_add_f32 v[22:23], v[24:25], v[22:23] op_sel_hi:[0,1]
	v_pk_fma_f32 v[22:23], v[156:157], v[156:157], v[22:23]
	v_mul_f32_e32 v24, v157, v157
	v_and_b32_e32 v155, 0xffff0000, v126
	v_lshlrev_b32_e32 v154, 16, v126
	v_pk_add_f32 v[22:23], v[24:25], v[22:23] op_sel_hi:[0,1]
	v_pk_fma_f32 v[22:23], v[154:155], v[154:155], v[22:23]
	v_mul_f32_e32 v24, v155, v155
	v_and_b32_e32 v149, 0xffff0000, v127
	v_lshlrev_b32_e32 v148, 16, v127
	v_pk_add_f32 v[22:23], v[24:25], v[22:23] op_sel_hi:[0,1]
	v_pk_fma_f32 v[22:23], v[148:149], v[148:149], v[22:23]
	v_mul_f32_e32 v24, v149, v149
	v_pk_add_f32 v[22:23], v[24:25], v[22:23] op_sel_hi:[0,1]
	v_pk_fma_f32 v[22:23], v[146:147], v[146:147], v[22:23]
	v_mul_f32_e32 v24, v147, v147
	v_pk_add_f32 v[22:23], v[24:25], v[22:23] op_sel_hi:[0,1]
	v_pk_fma_f32 v[22:23], v[140:141], v[140:141], v[22:23]
	v_mul_f32_e32 v24, v141, v141
	v_pk_add_f32 v[22:23], v[24:25], v[22:23] op_sel_hi:[0,1]
	v_pk_fma_f32 v[22:23], v[138:139], v[138:139], v[22:23]
	v_mul_f32_e32 v24, v139, v139
	v_and_b32_e32 v133, 0xffff0000, v25
	v_lshlrev_b32_e32 v132, 16, v25
	v_pk_add_f32 v[22:23], v[24:25], v[22:23] op_sel_hi:[0,1]
	v_pk_fma_f32 v[22:23], v[132:133], v[132:133], v[22:23]
	v_mul_f32_e32 v24, v133, v133
	v_and_b32_e32 v159, 0xffff0000, v128
	v_lshlrev_b32_e32 v158, 16, v128
	v_pk_add_f32 v[22:23], v[24:25], v[22:23] op_sel_hi:[0,1]
	v_pk_fma_f32 v[22:23], v[158:159], v[158:159], v[22:23]
	v_mul_f32_e32 v24, v159, v159
	v_and_b32_e32 v153, 0xffff0000, v129
	v_lshlrev_b32_e32 v152, 16, v129
	v_pk_add_f32 v[22:23], v[24:25], v[22:23] op_sel_hi:[0,1]
	v_pk_fma_f32 v[22:23], v[152:153], v[152:153], v[22:23]
	v_mul_f32_e32 v24, v153, v153
	v_and_b32_e32 v151, 0xffff0000, v130
	v_lshlrev_b32_e32 v150, 16, v130
	v_pk_add_f32 v[22:23], v[24:25], v[22:23] op_sel_hi:[0,1]
	v_pk_fma_f32 v[22:23], v[150:151], v[150:151], v[22:23]
	v_mul_f32_e32 v24, v151, v151
	v_and_b32_e32 v145, 0xffff0000, v131
	v_lshlrev_b32_e32 v144, 16, v131
	v_pk_add_f32 v[22:23], v[24:25], v[22:23] op_sel_hi:[0,1]
	v_pk_fma_f32 v[22:23], v[144:145], v[144:145], v[22:23]
	v_mul_f32_e32 v24, v145, v145
	v_and_b32_e32 v143, 0xffff0000, v48
	v_lshlrev_b32_e32 v142, 16, v48
	v_pk_add_f32 v[22:23], v[24:25], v[22:23] op_sel_hi:[0,1]
	v_pk_fma_f32 v[22:23], v[142:143], v[142:143], v[22:23]
	v_mul_f32_e32 v24, v143, v143
	v_and_b32_e32 v137, 0xffff0000, v49
	v_lshlrev_b32_e32 v136, 16, v49
	v_pk_add_f32 v[22:23], v[24:25], v[22:23] op_sel_hi:[0,1]
	v_pk_fma_f32 v[22:23], v[136:137], v[136:137], v[22:23]
	v_mul_f32_e32 v24, v137, v137
	v_and_b32_e32 v135, 0xffff0000, v50
	v_lshlrev_b32_e32 v134, 16, v50
	v_pk_add_f32 v[22:23], v[24:25], v[22:23] op_sel_hi:[0,1]
	v_pk_fma_f32 v[22:23], v[134:135], v[134:135], v[22:23]
	v_mul_f32_e32 v24, v135, v135
	v_and_b32_e32 v47, 0xffff0000, v51
	v_lshlrev_b32_e32 v46, 16, v51
	v_pk_add_f32 v[22:23], v[24:25], v[22:23] op_sel_hi:[0,1]
	v_pk_fma_f32 v[22:23], v[46:47], v[46:47], v[22:23]
	v_mul_f32_e32 v24, v47, v47
	v_pk_add_f32 v[22:23], v[24:25], v[22:23] op_sel_hi:[0,1]
	v_mov_b32_e32 v23, v22
	s_nop 1
	v_permlane32_swap_b32_e32 v22, v23
	v_add_f32_e32 v22, v22, v23
	v_fmamk_f32 v22, v22, 0x3c000000, v178
	v_mul_f32_e32 v23, 0x4b800000, v22
	v_cmp_gt_f32_e32 vcc, s49, v22
	s_nop 1
	v_cndmask_b32_e32 v22, v22, v23, vcc
	v_rsq_f32_e32 v205, v22
	global_load_dwordx4 v[22:25], v165, s[96:97] offset:176
	global_load_dwordx4 v[48:51], v165, s[96:97] offset:160
	global_load_dwordx4 v[124:127], v165, s[96:97] offset:144
	global_load_dwordx4 v[128:131], v165, s[96:97] offset:128
	v_mul_f32_e32 v165, 0x45800000, v205
	v_cndmask_b32_e32 v224, v205, v165, vcc
	v_pk_mul_f32 v[166:167], v[224:225], v[166:167] op_sel_hi:[0,1]
	s_waitcnt vmcnt(31)
; template <int MODE>
; __device__ __forceinline__ void attn_body(const bf16_t* __restrict__ Qb, const bf16_t* __restrict__ Kh, const bf16_t* __restrict__ Vh, int NT, int krel0,
;                                           char* lds, const float* __restrict__ lutg, const AttnEpi& E) {
;     ...
; #pragma unroll
;     for (int d0 = 0; d0 < ND0; ++d0) { const f32x4 g0 = *(const f32x4*)(E.gq + d0 * 16 + hi * 8), g1 = *(const f32x4*)(E.gq + d0 * 16 + hi * 8 + 4);
; #pragma unroll
;       for (int j = 0; j < 4; ++j) { qf[d0][j] = qf[d0][j] * rs * g0[j]; qf[d0][4 + j] = qf[d0][4 + j] * rs * g1[j]; } }
;     if constexpr (MODE == 0) {
;       const int sp = krel0 + wid * 32 + r32;
; #pragma unroll
;       for (int h = 0; h < 2; ++h) { const int pos = h == 0 ? (sp >> 6) : (sp & 63);
; #pragma unroll
;         for (int a = 0; a < 2; ++a) { const float* tb = lutg + (size_t)(pos * 32 + a * 16 + hi * 8) * 2;
; #pragma unroll
;           for (int jj = 0; jj < 4; ++jj) { const f32x4 cs = *(const f32x4*)(tb + jj * 4);
; #pragma unroll
;             for (int e = 0; e < 2; ++e) { const int j = 2 * jj + e; const float c = cs[2 * e], sn = cs[2 * e + 1];
;               const float x1 = qf[4 * h + a][j], x2 = qf[4 * h + 2 + a][j];
;               qf[4 * h + a][j] = x1 * c - x2 * sn; qf[4 * h + 2 + a][j] = x2 * c + x1 * sn; } } } }
	v_pk_mul_f32 v[120:121], v[120:121], v[166:167]
	v_pk_mul_f32 v[166:167], v[224:225], v[168:169] op_sel_hi:[0,1]
	s_waitcnt vmcnt(30)
	v_pk_mul_f32 v[116:117], v[116:117], v[166:167]
	v_pk_mul_f32 v[166:167], v[224:225], v[220:221] op_sel_hi:[0,1]
	v_pk_mul_f32 v[122:123], v[122:123], v[166:167]
	v_pk_mul_f32 v[166:167], v[224:225], v[216:217] op_sel_hi:[0,1]
	v_pk_mul_f32 v[118:119], v[118:119], v[166:167]
	v_pk_mul_f32 v[166:167], v[224:225], v[170:171] op_sel_hi:[0,1]
	s_waitcnt vmcnt(29)
	v_pk_mul_f32 v[112:113], v[112:113], v[166:167]
	v_pk_mul_f32 v[166:167], v[224:225], v[172:173] op_sel_hi:[0,1]
	s_waitcnt vmcnt(28)
	v_pk_mul_f32 v[108:109], v[108:109], v[166:167]
	v_pk_mul_f32 v[166:167], v[224:225], v[212:213] op_sel_hi:[0,1]
	v_pk_mul_f32 v[114:115], v[114:115], v[166:167]
	v_pk_mul_f32 v[166:167], v[224:225], v[190:191] op_sel_hi:[0,1]
	v_pk_mul_f32 v[110:111], v[110:111], v[166:167]
	v_pk_mul_f32 v[166:167], v[224:225], v[174:175] op_sel_hi:[0,1]
	s_waitcnt vmcnt(27)
	v_pk_mul_f32 v[166:167], v[104:105], v[166:167]
	v_pk_mul_f32 v[104:105], v[224:225], v[176:177] op_sel_hi:[0,1]
	s_waitcnt vmcnt(26)
	v_pk_mul_f32 v[168:169], v[100:101], v[104:105]
	v_pk_mul_f32 v[100:101], v[224:225], v[222:223] op_sel_hi:[0,1]
	v_pk_mul_f32 v[106:107], v[106:107], v[100:101]
	v_pk_mul_f32 v[100:101], v[224:225], v[218:219] op_sel_hi:[0,1]
	v_pk_mul_f32 v[170:171], v[102:103], v[100:101]
	v_pk_mul_f32 v[100:101], v[224:225], v[206:207] op_sel_hi:[0,1]
	s_waitcnt vmcnt(25)
	v_pk_mul_f32 v[96:97], v[96:97], v[100:101]
	v_pk_mul_f32 v[100:101], v[224:225], v[208:209] op_sel_hi:[0,1]
	s_waitcnt vmcnt(24)
	v_pk_mul_f32 v[172:173], v[92:93], v[100:101]
	v_pk_mul_f32 v[92:93], v[224:225], v[214:215] op_sel_hi:[0,1]
	v_pk_mul_f32 v[174:175], v[98:99], v[92:93]
	v_pk_mul_f32 v[92:93], v[224:225], v[210:211] op_sel_hi:[0,1]
	v_pk_mul_f32 v[176:177], v[94:95], v[92:93]
	v_pk_mul_f32 v[92:93], v[224:225], v[160:161] op_sel_hi:[0,1]
	s_waitcnt vmcnt(23)
	v_pk_mul_f32 v[160:161], v[88:89], v[92:93]
	v_pk_mul_f32 v[88:89], v[224:225], v[154:155] op_sel_hi:[0,1]
	s_waitcnt vmcnt(22)
	v_pk_mul_f32 v[102:103], v[84:85], v[88:89]
	v_pk_mul_f32 v[84:85], v[224:225], v[156:157] op_sel_hi:[0,1]
	v_pk_mul_f32 v[104:105], v[90:91], v[84:85]
	v_pk_mul_f32 v[84:85], v[224:225], v[148:149] op_sel_hi:[0,1]
	v_pk_mul_f32 v[100:101], v[86:87], v[84:85]
	v_pk_mul_f32 v[84:85], v[224:225], v[146:147] op_sel_hi:[0,1]
	s_waitcnt vmcnt(21)
	v_pk_mul_f32 v[98:99], v[84:85], v[80:81]
	v_pk_mul_f32 v[80:81], v[224:225], v[138:139] op_sel_hi:[0,1]
	s_waitcnt vmcnt(20)
	v_pk_mul_f32 v[80:81], v[80:81], v[76:77]
	v_pk_mul_f32 v[76:77], v[224:225], v[140:141] op_sel_hi:[0,1]
	v_pk_mul_f32 v[86:87], v[76:77], v[82:83]
	v_pk_mul_f32 v[76:77], v[224:225], v[132:133] op_sel_hi:[0,1]
	v_pk_mul_f32 v[76:77], v[76:77], v[78:79]
	v_pk_mul_f32 v[78:79], v[224:225], v[158:159] op_sel_hi:[0,1]
	s_waitcnt vmcnt(19)
	v_pk_mul_f32 v[132:133], v[78:79], v[68:69]
	v_pk_mul_f32 v[68:69], v[224:225], v[150:151] op_sel_hi:[0,1]
	s_waitcnt vmcnt(18)
	v_pk_mul_f32 v[64:65], v[68:69], v[64:65]
	v_pk_mul_f32 v[68:69], v[224:225], v[152:153] op_sel_hi:[0,1]
	v_pk_mul_f32 v[138:139], v[68:69], v[70:71]
	v_pk_mul_f32 v[68:69], v[224:225], v[144:145] op_sel_hi:[0,1]
	v_pk_mul_f32 v[66:67], v[68:69], v[66:67]
	v_pk_mul_f32 v[68:69], v[224:225], v[142:143] op_sel_hi:[0,1]
	s_waitcnt vmcnt(17)
	v_pk_mul_f32 v[60:61], v[68:69], v[60:61]
	v_pk_mul_f32 v[68:69], v[224:225], v[134:135] op_sel_hi:[0,1]
	s_waitcnt vmcnt(16)
	v_pk_mul_f32 v[78:79], v[68:69], v[52:53]
	v_pk_mul_f32 v[52:53], v[224:225], v[136:137] op_sel_hi:[0,1]
	v_pk_mul_f32 v[90:91], v[52:53], v[62:63]
	v_pk_mul_f32 v[46:47], v[224:225], v[46:47] op_sel_hi:[0,1]
	s_waitcnt vmcnt(12)
	v_mov_b32_e32 v53, v74
	v_mov_b32_e32 v74, v73
	v_pk_mul_f32 v[70:71], v[46:47], v[54:55]
	v_mov_b32_e32 v52, v72
	v_pk_mul_f32 v[46:47], v[166:167], v[74:75]
	v_ashrrev_i32_e32 v68, 4, v188
	v_pk_fma_f32 v[46:47], v[120:121], v[52:53], v[46:47] neg_lo:[0,0,1] neg_hi:[0,0,1]
	v_pk_mul_f32 v[52:53], v[166:167], v[52:53]
	v_add_u32_e32 v69, 32, v68
	v_pk_fma_f32 v[72:73], v[120:121], v[74:75], v[52:53]
	v_mov_b32_e32 v53, v58
	v_mov_b32_e32 v58, v57
	v_mov_b32_e32 v52, v56
	v_pk_mul_f32 v[54:55], v[106:107], v[58:59]
	v_lshlrev_b32_e32 v56, 3, v188
	v_pk_fma_f32 v[94:95], v[122:123], v[52:53], v[54:55] neg_lo:[0,0,1] neg_hi:[0,0,1]
	v_pk_mul_f32 v[52:53], v[106:107], v[52:53]
	v_and_b32_e32 v144, 0x78, v56
	v_pk_fma_f32 v[74:75], v[122:123], v[58:59], v[52:53]
	v_mov_b32_e32 v53, v40
	v_mov_b32_e32 v40, v39
	v_mov_b32_e32 v52, v38
	v_pk_mul_f32 v[38:39], v[168:169], v[40:41]
	v_lshlrev_b32_e32 v145, 4, v188
	v_pk_fma_f32 v[38:39], v[116:117], v[52:53], v[38:39] neg_lo:[0,0,1] neg_hi:[0,0,1]
	v_pk_mul_f32 v[52:53], v[168:169], v[52:53]
	v_lshlrev_b32_e32 v148, 8, v189
	v_pk_fma_f32 v[82:83], v[116:117], v[40:41], v[52:53]
	v_mov_b32_e32 v53, v32
	v_mov_b32_e32 v32, v31
	v_mov_b32_e32 v52, v30
	v_pk_mul_f32 v[30:31], v[170:171], v[32:33]
	v_and_b32_e32 v149, 0xf0, v145
	v_pk_fma_f32 v[40:41], v[118:119], v[52:53], v[30:31] neg_lo:[0,0,1] neg_hi:[0,0,1]
	v_pk_mul_f32 v[30:31], v[170:171], v[52:53]
	v_bitop3_b32 v214, v0, v148, v149 bitop3:0xde
	v_pk_fma_f32 v[84:85], v[118:119], v[32:33], v[30:31]
	s_waitcnt vmcnt(8)
; __device__ __forceinline__ unsigned cvtpk(float lo, float hi) { f32x2 v = {lo, hi}; bf16v2 b = __builtin_convertvector(v, bf16v2); return __builtin_bit_cast(unsigned, b); }
; __device__ __forceinline__ int v_st(int k, int c) { const int kk = (k & ~0xC) | ((k & 4) << 1) | ((k & 8) >> 1); return ((kk >> 3) * 4 + (c >> 5)) * 512 + ((kk & 7) * 32 + (c & 31)) * 2; }
; __device__ __forceinline__ int v_rd_base(int lane) { return ((lane & 3) << 3) | (((lane >> 2) & 3) << 6) | (((lane >> 4) & 1) << 5) | (((lane >> 5) & 1) << 8); }
; #define SLOAD(i, k0) do { sr_[i].vs0 = *reinterpret_cast<const bf16x8*>(&Vh[(size_t)((k0) + sr) * LDQK + sc]); sr_[i].vs1 = *reinterpret_cast<const bf16x8*>(&Vh[(size_t)((k0) + 32 + sr) * LDQK + sc]); \
;     sr_[i].ks0 = *reinterpret_cast<const bf16x8*>(&Kh[(size_t)((k0) + sr) * LDQK + sc]); sr_[i].ks1 = *reinterpret_cast<const bf16x8*>(&Kh[(size_t)((k0) + 32 + sr) * LDQK + sc]); } while (0)
; template <int MODE>
; __device__ __forceinline__ void attn_body(const bf16_t* __restrict__ Qb, const bf16_t* __restrict__ Kh, const bf16_t* __restrict__ Vh, int NT, int krel0,
;                                           char* lds, const float* __restrict__ lutg, const AttnEpi& E) {
;     ...
;               const float x1 = qf[4 * h + a][j], x2 = qf[4 * h + 2 + a][j];
;               qf[4 * h + a][j] = x1 * c - x2 * sn; qf[4 * h + 2 + a][j] = x2 * c + x1 * sn; } } } }
;     }
; #pragma unroll
;     for (int d0 = 0; d0 < ND0; ++d0) { u32x4 w; w.x = cvtpk(qf[d0][0], qf[d0][1]); w.y = cvtpk(qf[d0][2], qf[d0][3]); w.z = cvtpk(qf[d0][4], qf[d0][5]); w.w = cvtpk(qf[d0][6], qf[d0][7]);
;       qr[d0] = *reinterpret_cast<bf16x8*>(&w); }
;   }
;   const int sr = tid >> 4, sc = (tid & 15) * 8, vst0 = v_st(sr, sc), vst1 = v_st(32 + sr, sc);
;   const int vb0 = (int)(uintptr_t)V_lds + v_rd_base(lane);
;   struct { bf16x8 vs0, vs1, ks0, ks1; } sr_[2];
;     ...
;   const int relq = krel0 - (wid * 32 + r32) + 4 * hi, relwmin = krel0 - (wid * 32 + 31), relwmax = krel0 + 63 - wid * 32;
;     ...
;   f32x16 pA0, pA1, pB0, pB1; float mnA, mnB, alA, alB; bf16x8 pa0, pa1, pa2, pa3;
;   constexpr int SE = 0, SO = 1;
;   SLOAD(SE, 0); SLOAD(SO, 64); asm volatile("s_waitcnt vmcnt(4)" ::: "memory"); SWRITE(0, SE); __syncthreads();
	v_mov_b32_e32 v31, v44
	v_mov_b32_e32 v44, v43
	v_mov_b32_e32 v30, v42
	v_pk_mul_f32 v[32:33], v[96:97], v[44:45]
	v_mad_i64_i32 v[42:43], s[6:7], v69, s57, 0
	v_pk_fma_f32 v[88:89], v[112:113], v[30:31], v[32:33] neg_lo:[0,0,1] neg_hi:[0,0,1]
	v_mov_b32_e32 v33, v36
	v_mov_b32_e32 v36, v35
	v_mov_b32_e32 v32, v34
	v_pk_mul_f32 v[34:35], v[174:175], v[36:37]
	v_pk_mul_f32 v[30:31], v[96:97], v[30:31]
	v_pk_fma_f32 v[92:93], v[114:115], v[32:33], v[34:35] neg_lo:[0,0,1] neg_hi:[0,0,1]
	v_mov_b32_e32 v35, v28
	v_mov_b32_e32 v28, v27
	v_mov_b32_e32 v34, v26
	v_pk_mul_f32 v[26:27], v[172:173], v[28:29]
	v_or_b32_e32 v42, v42, v144
	v_pk_fma_f32 v[96:97], v[108:109], v[34:35], v[26:27] neg_lo:[0,0,1] neg_hi:[0,0,1]
	v_pk_mul_f32 v[26:27], v[172:173], v[34:35]
	v_mov_b32_e32 v35, v20
	v_mov_b32_e32 v20, v19
	v_mov_b32_e32 v34, v18
	v_pk_mul_f32 v[18:19], v[176:177], v[20:21]
	v_pk_fma_f32 v[26:27], v[108:109], v[28:29], v[26:27]
	v_pk_fma_f32 v[28:29], v[110:111], v[34:35], v[18:19] neg_lo:[0,0,1] neg_hi:[0,0,1]
	v_pk_mul_f32 v[18:19], v[176:177], v[34:35]
	v_pk_mul_f32 v[32:33], v[174:175], v[32:33]
	v_pk_fma_f32 v[18:19], v[110:111], v[20:21], v[18:19]
	s_waitcnt vmcnt(4)
	v_mov_b32_e32 v20, v14
	v_mov_b32_e32 v21, v16
	v_mov_b32_e32 v16, v15
	v_mad_i64_i32 v[14:15], s[6:7], v68, s57, 0
	v_or_b32_e32 v14, v14, v144
	v_pk_mul_f32 v[54:55], v[132:133], v[16:17]
	v_lshl_add_u64 v[14:15], v[14:15], 1, s[0:1]
	v_lshl_add_u64 v[52:53], v[42:43], 1, s[0:1]
	v_pk_fma_f32 v[110:111], v[160:161], v[20:21], v[54:55] neg_lo:[0,0,1] neg_hi:[0,0,1]
	v_pk_mul_f32 v[20:21], v[132:133], v[20:21]
	v_pk_fma_f32 v[30:31], v[112:113], v[44:45], v[30:31]
	v_pk_fma_f32 v[32:33], v[114:115], v[36:37], v[32:33]
	global_load_dwordx4 v[34:37], v[14:15], off offset:2560
	global_load_dwordx4 v[42:45], v[52:53], off offset:2560
	v_pk_fma_f32 v[132:133], v[160:161], v[16:17], v[20:21]
	global_load_dwordx4 v[14:17], v[14:15], off offset:2048
	v_mov_b32_e32 v21, v12
	global_load_dwordx4 v[106:109], v[52:53], off offset:2048
	v_mov_b32_e32 v12, v11
	v_mov_b32_e32 v20, v10
	v_pk_mul_f32 v[10:11], v[138:139], v[12:13]
	v_cvt_pk_bf16_f32 v116, v38, v39
	v_pk_fma_f32 v[112:113], v[104:105], v[20:21], v[10:11] neg_lo:[0,0,1] neg_hi:[0,0,1]
	v_pk_mul_f32 v[10:11], v[138:139], v[20:21]
	v_or_b32_e32 v38, 32, v0
	v_pk_fma_f32 v[104:105], v[104:105], v[12:13], v[10:11]
	v_mov_b32_e32 v11, v8
	v_mov_b32_e32 v8, v7
	v_mov_b32_e32 v10, v6
	v_pk_mul_f32 v[6:7], v[64:65], v[8:9]
	s_waitcnt vmcnt(6)
	v_mov_b32_e32 v21, v50
	v_pk_fma_f32 v[134:135], v[102:103], v[10:11], v[6:7] neg_lo:[0,0,1] neg_hi:[0,0,1]
	v_pk_mul_f32 v[6:7], v[64:65], v[10:11]
	v_mov_b32_e32 v50, v49
	v_pk_fma_f32 v[136:137], v[102:103], v[8:9], v[6:7]
	v_mov_b32_e32 v7, v4
	v_mov_b32_e32 v4, v3
	v_mov_b32_e32 v6, v2
	v_pk_mul_f32 v[2:3], v[66:67], v[4:5]
	v_lshlrev_b32_e32 v8, 1, v144
	v_pk_fma_f32 v[102:103], v[100:101], v[6:7], v[2:3] neg_lo:[0,0,1] neg_hi:[0,0,1]
	v_pk_mul_f32 v[2:3], v[66:67], v[6:7]
	s_waitcnt vmcnt(5)
	v_mov_b32_e32 v7, v126
	v_pk_fma_f32 v[138:139], v[100:101], v[4:5], v[2:3]
	s_waitcnt vmcnt(4)
	v_mov_b32_e32 v3, v130
	v_mov_b32_e32 v130, v129
	v_mov_b32_e32 v2, v128
	v_pk_mul_f32 v[4:5], v[60:61], v[130:131]
	v_mov_b32_e32 v126, v125
	v_pk_fma_f32 v[140:141], v[98:99], v[2:3], v[4:5] neg_lo:[0,0,1] neg_hi:[0,0,1]
	v_pk_mul_f32 v[2:3], v[60:61], v[2:3]
	v_mov_b32_e32 v6, v124
	v_pk_fma_f32 v[130:131], v[98:99], v[130:131], v[2:3]
	v_pk_mul_f32 v[2:3], v[90:91], v[126:127]
	v_bfe_u32 v4, v56, 5, 2
	v_pk_fma_f32 v[142:143], v[86:87], v[6:7], v[2:3] neg_lo:[0,0,1] neg_hi:[0,0,1]
	v_and_b32_e32 v2, 0xfffff0, v68
	v_lshlrev_b32_e32 v3, 1, v68
	v_and_or_b32 v2, v3, 8, v2
	v_lshrrev_b32_e32 v3, 1, v68
	v_lshrrev_b32_e32 v2, 1, v2
	v_and_b32_e32 v5, 3, v68
	v_or_b32_e32 v2, v2, v4
	v_and_or_b32 v3, v3, 4, v5
	v_lshlrev_b32_e32 v2, 9, v2
	v_lshlrev_b32_e32 v3, 6, v3
	v_and_b32_e32 v5, 48, v8
	v_or3_b32 v210, v2, v3, v5
	v_and_b32_e32 v2, 0xfffff0, v69
	v_lshlrev_b32_e32 v9, 1, v69
	v_and_or_b32 v2, v9, 8, v2
	v_lshrrev_b32_e32 v2, 1, v2
	v_or_b32_e32 v2, v2, v4
	v_lshlrev_b32_e32 v2, 9, v2
	v_or3_b32 v211, v2, v3, v5
	v_add_u32_e32 v2, 64, v68
	v_mad_i64_i32 v[2:3], s[6:7], v2, s57, 0
	v_add_u32_e32 v4, 0x60, v68
	v_or_b32_e32 v2, v2, v144
	v_mad_i64_i32 v[4:5], s[6:7], v4, s57, 0
	v_lshl_add_u64 v[2:3], v[2:3], 1, s[0:1]
	v_or_b32_e32 v4, v4, v144
	v_lshl_add_u64 v[4:5], v[4:5], 1, s[0:1]
	global_load_dwordx4 v[60:63], v[2:3], off offset:2560
	global_load_dwordx4 v[52:55], v[2:3], off offset:2048
	global_load_dwordx4 v[64:67], v[4:5], off offset:2560
	global_load_dwordx4 v[56:59], v[4:5], off offset:2048
	v_lshlrev_b32_e32 v2, 8, v68
	v_and_b32_e32 v3, 0xf0, v188
	v_bitop3_b32 v212, v8, v2, v3 bitop3:0xde
	v_add_u32_e32 v146, 0, v210
	v_add_u32_e32 v147, 0, v211
	v_add_u32_e32 v2, 0, v212
	s_waitcnt vmcnt(4)
	s_waitcnt vmcnt(7)
	ds_write_b128 v146, v[34:37]
	s_waitcnt vmcnt(6)
	ds_write_b128 v147, v[42:45]
	s_waitcnt vmcnt(5)
	ds_write_b128 v2, v[14:17] offset:49152
	v_lshlrev_b32_e32 v2, 8, v69
	v_bitop3_b32 v213, v8, v2, v3 bitop3:0xde
	v_add_u32_e32 v2, 0, v213
	v_add_u32_e32 v8, 0, v214
	s_waitcnt vmcnt(4)
	ds_write_b128 v2, v[106:109] offset:49152
	s_waitcnt lgkmcnt(0)
	s_barrier
; template <int MODE>
; __device__ __forceinline__ void partialSM(f32x16& p0, f32x16& p1, float& m_reg, float& mn, float& alpha, int relh, int relw_min, int relw_max, const float* lut) {
;     ...
;     float pmax = p0[0];
; #pragma unroll
;     for (int r = 1; r < 16; ++r) pmax = fmaxf(pmax, p0[r]);
; #pragma unroll
;     for (int r = 0; r < 16; ++r) pmax = fmaxf(pmax, p1[r]);
; template <int ND0, int DOFF>
; __device__ __forceinline__ void qkt(f32x16& p0, f32x16& p1, const char* Ks, const bf16x8* qr, int r32, int hi) {
;   p0 = f32x16{}; p1 = f32x16{};
; #pragma unroll
;   for (int d0 = 0; d0 < ND0; ++d0) { const int cb = ((d0 + DOFF) * 16 + hi * 8) * 2;
;     bf16x8 b0 = *reinterpret_cast<const bf16x8*>(Ks + KSWZ(r32, cb));
;     bf16x8 b1 = *reinterpret_cast<const bf16x8*>(Ks + KSWZ(32 + r32, cb));
;     p0 = __builtin_amdgcn_mfma_f32_32x32x16_bf16(b0, qr[d0], p0, 0, 0, 0);
;     p1 = __builtin_amdgcn_mfma_f32_32x32x16_bf16(b1, qr[d0], p1, 0, 0, 0); }
; }
	ds_read_b128 v[2:5], v8 offset:49152
	ds_read_b128 v[34:37], v8 offset:57344
	v_pk_mul_f32 v[6:7], v[90:91], v[6:7]
	v_bitop3_b32 v218, v38, v148, v149 bitop3:0xde
	v_pk_fma_f32 v[90:91], v[86:87], v[126:127], v[6:7]
	v_mov_b32_e32 v20, v48
	v_pk_mul_f32 v[86:87], v[78:79], v[50:51]
	v_add_u32_e32 v69, 0, v218
	v_cvt_pk_bf16_f32 v114, v46, v47
	v_cvt_pk_bf16_f32 v115, v94, v95
	v_cvt_pk_bf16_f32 v117, v40, v41
	v_pk_fma_f32 v[94:95], v[80:81], v[20:21], v[86:87] neg_lo:[0,0,1] neg_hi:[0,0,1]
	v_cvt_pk_bf16_f32 v126, v88, v89
	ds_read_b128 v[86:89], v69 offset:57344
	s_waitcnt lgkmcnt(1)
	v_mfma_f32_32x32x16_bf16 v[34:49], v[34:37], v[114:117], 0
	ds_read_b128 v[98:101], v69 offset:49152
	v_mul_f32_e64 v20, v78, v20
	v_mul_f32_e64 v21, v79, v21
	v_cvt_pk_bf16_f32 v127, v92, v93
	v_cvt_pk_bf16_f32 v128, v96, v97
	v_cvt_pk_bf16_f32 v129, v28, v29
	v_pk_fma_f32 v[28:29], v[80:81], v[50:51], v[20:21]
	v_mov_b32_e32 v51, v24
	v_mfma_f32_32x32x16_bf16 v[2:17], v[2:5], v[114:117], 0
	v_mov_b32_e32 v24, v23
	v_mov_b32_e32 v50, v22
	v_or_b32_e32 v20, 64, v0
	v_cvt_pk_bf16_f32 v119, v74, v75
	v_bitop3_b32 v219, v20, v148, v149 bitop3:0xde
	v_add_u32_e32 v20, 0, v219
	ds_read_b128 v[78:81], v20 offset:49152
	s_waitcnt lgkmcnt(2)
	v_mfma_f32_32x32x16_bf16 v[34:49], v[86:89], v[126:129], v[34:49]
	v_mul_f32_e64 v86, v70, v24
	v_mul_f32_e64 v87, v71, v25
	v_cvt_pk_bf16_f32 v118, v72, v73
	v_fma_f32 v74, v76, v50, -v86
	v_fma_f32 v75, v77, v51, -v87
	v_pk_mul_f32 v[50:51], v[70:71], v[50:51]
	v_cvt_pk_bf16_f32 v120, v82, v83
	v_pk_fma_f32 v[50:51], v[76:77], v[24:25], v[50:51]
	v_or_b32_e32 v24, 0x60, v0
	v_bitop3_b32 v216, v24, v148, v149 bitop3:0xde
	v_add_u32_e32 v24, 0, v216
	ds_read_b128 v[70:73], v24 offset:49152
	ds_read_b128 v[20:23], v20 offset:57344
	s_waitcnt lgkmcnt(3)
	v_mfma_f32_32x32x16_bf16 v[2:17], v[98:101], v[126:129], v[2:17]
	v_cvt_pk_bf16_f32 v121, v84, v85
	v_cvt_pk_bf16_f32 v124, v26, v27
	v_cvt_pk_bf16_f32 v122, v30, v31
	v_cvt_pk_bf16_f32 v123, v32, v33
	v_cvt_pk_bf16_f32 v125, v18, v19
	v_cvt_pk_bf16_f32 v110, v110, v111
	v_cvt_pk_bf16_f32 v111, v112, v113
	s_waitcnt lgkmcnt(2)
	v_mfma_f32_32x32x16_bf16 v[2:17], v[78:81], v[118:121], v[2:17]
	v_cvt_pk_bf16_f32 v112, v134, v135
	v_cvt_pk_bf16_f32 v113, v102, v103
	v_cvt_pk_bf16_f32 v106, v140, v141
	v_cvt_pk_bf16_f32 v107, v142, v143
	v_cvt_pk_bf16_f32 v108, v94, v95
	v_cvt_pk_bf16_f32 v109, v74, v75
	v_cvt_pk_bf16_f32 v100, v28, v29
	s_waitcnt lgkmcnt(0)
	v_mfma_f32_32x32x16_bf16 v[34:49], v[20:23], v[118:121], v[34:49]
	v_or_b32_e32 v22, 0x80, v0
	v_bitop3_b32 v217, v22, v148, v149 bitop3:0xde
	v_add_u32_e32 v26, 0, v217
	ds_read_b128 v[18:21], v24 offset:57344
	ds_read_b128 v[22:25], v26 offset:49152
	v_lshlrev_b32_e32 v27, 3, v162
	v_lshlrev_b32_e32 v29, 1, v188
	v_mfma_f32_32x32x16_bf16 v[2:17], v[70:73], v[122:125], v[2:17]
	v_cvt_pk_bf16_f32 v102, v132, v133
	v_cvt_pk_bf16_f32 v103, v104, v105
	v_cvt_pk_bf16_f32 v104, v136, v137
	v_cvt_pk_bf16_f32 v105, v138, v139
	s_cselect_b32 s6, 0, 0
	v_cvt_pk_bf16_f32 v98, v130, v131
	v_cvt_pk_bf16_f32 v99, v90, v91
	s_waitcnt lgkmcnt(1)
	v_mfma_f32_32x32x16_bf16 v[34:49], v[18:21], v[122:125], v[34:49]
	ds_read_b128 v[18:21], v26 offset:57344
	v_cvt_pk_bf16_f32 v101, v50, v51
	v_lshlrev_b32_e32 v205, 2, v164
	v_ashrrev_i32_e32 v69, 31, v68
	v_lshl_add_u32 v206, v189, 2, v163
	v_mov_b32_e32 v207, 0
	s_waitcnt lgkmcnt(1)
	v_mfma_f32_32x32x16_bf16 v[2:17], v[22:25], v[110:113], v[2:17]
	v_or_b32_e32 v22, 0xa0, v0
	v_bitop3_b32 v215, v22, v148, v149 bitop3:0xde
	v_add_u32_e32 v26, 0, v215
	ds_read_b128 v[22:25], v26 offset:49152
	s_waitcnt lgkmcnt(1)
	v_mfma_f32_32x32x16_bf16 v[34:49], v[18:21], v[110:113], v[34:49]
	v_and_b32_e32 v18, 0xc0, v145
	v_and_or_b32 v28, v27, 24, v18
	ds_read_b128 v[18:21], v26 offset:57344
	s_waitcnt lgkmcnt(1)
	v_mfma_f32_32x32x16_bf16 v[2:17], v[22:25], v[106:109], v[2:17]
	v_and_b32_e32 v22, 32, v29
	v_and_b32_e32 v23, 0x100, v27
	v_or3_b32 v26, v28, v22, v23
	v_or_b32_e32 v22, 0xc0, v0
	v_bitop3_b32 v220, v22, v148, v149 bitop3:0xde
	v_add_u32_e32 v27, 0, v220
	ds_read_b128 v[22:25], v27 offset:49152
	s_waitcnt lgkmcnt(1)
	v_mfma_f32_32x32x16_bf16 v[34:49], v[18:21], v[106:109], v[34:49]
	ds_read_b128 v[18:21], v27 offset:57344
	v_add_u32_e32 v209, s6, v26
	s_waitcnt lgkmcnt(1)
	v_mfma_f32_32x32x16_bf16 v[2:17], v[22:25], v[102:105], v[2:17]
	v_or_b32_e32 v22, 0xe0, v0
	v_bitop3_b32 v221, v22, v148, v149 bitop3:0xde
	v_add_u32_e32 v26, 0, v221
	ds_read_b128 v[22:25], v26 offset:49152
	ds_read_b128 v[70:73], v26 offset:57344
	v_add_u32_e32 v0, v163, v0
	s_waitcnt lgkmcnt(1)
	v_mfma_f32_32x32x16_bf16 v[2:17], v[22:25], v[98:101], v[2:17]
	v_mfma_f32_32x32x16_bf16 v[34:49], v[18:21], v[102:105], v[34:49]
	s_nop 10
	v_max_f32_e32 v50, v3, v3
	v_max_f32_e32 v51, v2, v2
	v_max_f32_e32 v50, v51, v50
	v_max3_f32 v50, v50, v4, v5
	v_max3_f32 v50, v50, v6, v7
	v_max3_f32 v50, v50, v8, v9
	v_max3_f32 v50, v50, v10, v11
	s_waitcnt lgkmcnt(0)
; #define SLOAD(i, k0) do { sr_[i].vs0 = *reinterpret_cast<const bf16x8*>(&Vh[(size_t)((k0) + sr) * LDQK + sc]); sr_[i].vs1 = *reinterpret_cast<const bf16x8*>(&Vh[(size_t)((k0) + 32 + sr) * LDQK + sc]); \
;     sr_[i].ks0 = *reinterpret_cast<const bf16x8*>(&Kh[(size_t)((k0) + sr) * LDQK + sc]); sr_[i].ks1 = *reinterpret_cast<const bf16x8*>(&Kh[(size_t)((k0) + 32 + sr) * LDQK + sc]); } while (0)
; #define SWRITE(off, i) do { *(bf16x8*)(V_lds + (off) + vst0) = sr_[i].vs0;          \
;     *(bf16x8*)(V_lds + (off) + vst1) = sr_[i].vs1; int kc = sc * 2;               \
;     *(bf16x8*)(K_lds + (off) + KSWZ(sr, kc)) = sr_[i].ks0;                       \
;     *(bf16x8*)(K_lds + (off) + KSWZ(32 + sr, kc)) = sr_[i].ks1; } while (0)
; template <int MODE>
; __device__ __forceinline__ void partialSM(f32x16& p0, f32x16& p1, float& m_reg, float& mn, float& alpha, int relh, int relw_min, int relw_max, const float* lut) {
;     ...
;     float pmax = p0[0];
; #pragma unroll
;     for (int r = 1; r < 16; ++r) pmax = fmaxf(pmax, p0[r]);
; #pragma unroll
;     for (int r = 0; r < 16; ++r) pmax = fmaxf(pmax, p1[r]);
;     { auto rr = __builtin_amdgcn_permlane32_swap(__float_as_uint(pmax), __float_as_uint(pmax), false, false);
;       pmax = fmaxf(__uint_as_float(rr[0]), __uint_as_float(rr[1])); }
;     if (__builtin_expect(__all(pmax - m_reg <= THR / SCALE), 1)) { mn = m_reg; alpha = 1.f; }
;     else { mn = fmaxf(m_reg, pmax); alpha = __builtin_amdgcn_exp2f((m_reg - mn) * C); m_reg = mn; }
;     const float mnC = -mn * C;
; #pragma unroll
;     for (int r = 0; r < 16; ++r) p0[r] = fmaf(p0[r], C, mnC);
; #pragma unroll
;     for (int r = 0; r < 16; ++r) p1[r] = fmaf(p1[r], C, mnC);
; #pragma unroll
;     for (int r = 0; r < 16; ++r) p0[r] = __builtin_amdgcn_exp2f(p0[r]);
; template <int MODE>
; __device__ __forceinline__ void attn_body(const bf16_t* __restrict__ Qb, const bf16_t* __restrict__ Kh, const bf16_t* __restrict__ Vh, int NT, int krel0,
;                                           char* lds, const float* __restrict__ lutg, const AttnEpi& E) {
;     ...
;   SLOAD(SE, 0); SLOAD(SO, 64); asm volatile("s_waitcnt vmcnt(4)" ::: "memory"); SWRITE(0, SE); __syncthreads();
;   qkt<ND0, DOFF>(pA0, pA1, K_lds, qr, r32, hi); PSM(pA0, pA1, mnA, alA, 0);
;   if (2 < NT) SLOAD(SE, 2 * 64);
;   SWAIT(); SWRITE(SHM_V, SO);
;   int op = 0, oq = SHM_V, ow = 2 * SHM_V;
	v_mfma_f32_32x32x16_bf16 v[34:49], v[70:73], v[98:101], v[34:49]
	v_max3_f32 v50, v50, v12, v13
	v_max3_f32 v50, v50, v14, v15
	v_max3_f32 v50, v50, v16, v17
	v_add_u32_e32 v70, 0x80, v68
	v_mad_i64_i32 v[70:71], s[6:7], v70, s57, 0
	v_or_b32_e32 v70, v70, v144
	s_nop 5
	v_max3_f32 v50, v50, v34, v35
	v_max3_f32 v50, v50, v36, v37
	v_max3_f32 v50, v50, v38, v39
	v_max3_f32 v50, v50, v40, v41
	v_max3_f32 v50, v50, v42, v43
	v_max3_f32 v50, v50, v44, v45
	v_max3_f32 v50, v50, v46, v47
	v_max3_f32 v72, v50, v48, v49
	v_mov_b32_e32 v50, v72
	s_nop 1
	v_permlane32_swap_b32_e32 v72, v50
	v_max_f32_e32 v73, v50, v50
	v_add_u32_e32 v50, 0xa0, v68
	v_mad_i64_i32 v[50:51], s[6:7], v50, s57, 0
	v_or_b32_e32 v50, v50, v144
	v_lshl_add_u64 v[50:51], v[50:51], 1, s[0:1]
	v_lshl_add_u64 v[70:71], v[70:71], 1, s[0:1]
	global_load_dwordx4 v[134:137], v[50:51], off offset:2048
	global_load_dwordx4 v[138:141], v[50:51], off offset:2560
	global_load_dwordx4 v[142:145], v[70:71], off offset:2048
	global_load_dwordx4 v[130:133], v[70:71], off offset:2560
	v_max_f32_e32 v50, v72, v72
	v_max_f32_e32 v50, v50, v73
	v_mov_b64_e32 v[18:19], s[68:69]
	v_add_f32_e32 v51, 0x7149f2ca, v50
	v_mov_b64_e32 v[20:21], s[70:71]
	v_mov_b64_e32 v[22:23], s[72:73]
	v_mov_b64_e32 v[24:25], s[74:75]
	v_mov_b64_e32 v[26:27], s[76:77]
	v_mov_b64_e32 v[28:29], s[78:79]
	v_mov_b64_e32 v[30:31], s[80:81]
	v_mov_b64_e32 v[32:33], s[82:83]
	v_cmp_ge_f32_e32 vcc, s40, v51
	s_add_i32 s75, 0, 0x10000
	s_add_i32 s70, s11, -1
	s_cmp_eq_u64 vcc, exec
	v_add_u32_e32 v51, s75, v212
	v_max_f32_e32 v50, 0xf149f2ca, v50
	s_cselect_b64 vcc, -1, 0
	s_waitcnt vmcnt(4)
	s_waitcnt vmcnt(7)
	ds_write_b128 v146, v[60:63] offset:16384
	s_waitcnt vmcnt(5)
	ds_write_b128 v147, v[64:67] offset:16384
	ds_write_b128 v51, v[52:55]
	v_add_u32_e32 v51, s75, v213
	v_cndmask_b32_e32 v166, v50, v197, vcc
	v_readlane_b32 s19, v255, 20
	s_nop 3
	v_mov_b32_e32 v166, s19
	s_waitcnt vmcnt(4)
	ds_write_b128 v51, v[56:59]
	v_sub_f32_e32 v51, 0xf149f2ca, v50
	v_mul_f32_e32 v50, 0xbe0293ee, v166
	v_fmamk_f32 v2, v2, 0x3e0293ee, v50
	v_exp_f32_e32 v164, v2
	v_fmamk_f32 v2, v3, 0x3e0293ee, v50
	v_exp_f32_e32 v165, v2
	v_fmamk_f32 v2, v4, 0x3e0293ee, v50
	v_exp_f32_e32 v175, v2
	v_fmamk_f32 v2, v5, 0x3e0293ee, v50
	v_exp_f32_e32 v177, v2
	v_fmamk_f32 v2, v6, 0x3e0293ee, v50
	v_exp_f32_e32 v227, v2
	v_fmamk_f32 v2, v7, 0x3e0293ee, v50
	v_exp_f32_e32 v228, v2
	v_fmamk_f32 v2, v8, 0x3e0293ee, v50
	v_exp_f32_e32 v176, v2
	v_fmamk_f32 v2, v9, 0x3e0293ee, v50
	v_exp_f32_e32 v226, v2
	v_fmamk_f32 v2, v10, 0x3e0293ee, v50
	v_exp_f32_e32 v167, v2
	v_fmamk_f32 v2, v11, 0x3e0293ee, v50
	v_exp_f32_e32 v169, v2
	v_fmamk_f32 v2, v12, 0x3e0293ee, v50
	v_mul_f32_e32 v51, 0x3e0293ee, v51
	v_exp_f32_e32 v171, v2
	v_fmamk_f32 v2, v13, 0x3e0293ee, v50
	v_exp_f32_e32 v51, v51
	v_exp_f32_e32 v173, v2
	v_fmamk_f32 v2, v14, 0x3e0293ee, v50
	v_exp_f32_e32 v168, v2
	v_fmamk_f32 v2, v15, 0x3e0293ee, v50
	v_exp_f32_e32 v170, v2
	v_fmamk_f32 v2, v16, 0x3e0293ee, v50
	v_exp_f32_e32 v172, v2
	v_lshl_add_u64 v[2:3], v[68:69], 0, s[2:3]
	v_pk_fma_f32 v[146:147], v[48:49], s[38:39], v[50:51] op_sel_hi:[1,0,0]
	v_pk_fma_f32 v[148:149], v[46:47], s[38:39], v[50:51] op_sel_hi:[1,0,0]
	v_pk_fma_f32 v[150:151], v[44:45], s[38:39], v[50:51] op_sel_hi:[1,0,0]
	v_pk_fma_f32 v[152:153], v[42:43], s[38:39], v[50:51] op_sel_hi:[1,0,0]
	v_pk_fma_f32 v[154:155], v[40:41], s[38:39], v[50:51] op_sel_hi:[1,0,0]
	v_pk_fma_f32 v[156:157], v[38:39], s[38:39], v[50:51] op_sel_hi:[1,0,0]
	v_pk_fma_f32 v[158:159], v[36:37], s[38:39], v[50:51] op_sel_hi:[1,0,0]
	v_pk_fma_f32 v[160:161], v[34:35], s[38:39], v[50:51] op_sel_hi:[1,0,0]
	v_fmac_f32_e32 v50, 0x3e0293ee, v17
	v_mad_u64_u32 v[4:5], s[0:1], v2, s56, 0
	v_and_b32_e32 v2, 15, v188
	s_mov_b32 s82, s84
	v_exp_f32_e32 v174, v50
	v_lshlrev_b32_e32 v2, 4, v2
	v_readlane_b32 s0, v254, 10
	v_mad_i32_i24 v3, v3, s56, v5
	v_or3_b32 v2, v4, s82, v2
	v_readlane_b32 s1, v254, 11
	v_cndmask_b32_e64 v222, v51, 1.0, vcc
	v_mov_b64_e32 v[64:65], v[32:33]
	v_lshl_add_u64 v[190:191], s[0:1], 0, v[2:3]
	v_mov_b64_e32 v[48:49], v[32:33]
	v_mov_b64_e32 v[2:3], v[18:19]
	s_mov_b64 s[86:87], s[22:23]
	v_cmp_gt_u32_e64 s[6:7], 32, v162
	s_movk_i32 s73, 0x2400
	s_movk_i32 s71, 0x4000
	s_mov_b32 s0, 0x8000
	v_mov_b64_e32 v[62:63], v[30:31]
	v_mov_b64_e32 v[60:61], v[28:29]
	v_mov_b64_e32 v[58:59], v[26:27]
	v_mov_b64_e32 v[56:57], v[24:25]
	v_mov_b64_e32 v[54:55], v[22:23]
	v_mov_b64_e32 v[52:53], v[20:21]
	v_mov_b64_e32 v[50:51], v[18:19]
	v_mov_b64_e32 v[46:47], v[30:31]
	v_mov_b64_e32 v[44:45], v[28:29]
	v_mov_b64_e32 v[42:43], v[26:27]
	v_mov_b64_e32 v[40:41], v[24:25]
	v_mov_b64_e32 v[38:39], v[22:23]
	v_mov_b64_e32 v[36:37], v[20:21]
	v_mov_b64_e32 v[34:35], v[18:19]
	v_mov_b64_e32 v[4:5], v[20:21]
	v_mov_b64_e32 v[6:7], v[22:23]
	v_mov_b64_e32 v[8:9], v[24:25]
	v_mov_b64_e32 v[10:11], v[26:27]
	v_mov_b64_e32 v[12:13], v[28:29]
	v_mov_b64_e32 v[14:15], v[30:31]
	v_mov_b64_e32 v[16:17], v[32:33]
	s_mov_b64 s[84:85], s[20:21]
	v_readlane_b32 s74, v254, 57
; #define SBAR() __builtin_amdgcn_sched_barrier(0)
; #define SLOAD(i, k0) do { sr_[i].vs0 = *reinterpret_cast<const bf16x8*>(&Vh[(size_t)((k0) + sr) * LDQK + sc]); sr_[i].vs1 = *reinterpret_cast<const bf16x8*>(&Vh[(size_t)((k0) + 32 + sr) * LDQK + sc]); \
;     sr_[i].ks0 = *reinterpret_cast<const bf16x8*>(&Kh[(size_t)((k0) + sr) * LDQK + sc]); sr_[i].ks1 = *reinterpret_cast<const bf16x8*>(&Kh[(size_t)((k0) + 32 + sr) * LDQK + sc]); } while (0)
; #define PSM(P0, P1, MN, AL, J) partialSM<MODE>(P0, P1, m_reg, MN, AL, relq + 64 * (J), relwmin + 64 * (J), relwmax + 64 * (J), lut)
; __device__ __forceinline__ void finishSM(f32x16& p0, f32x16& p1, float alpha, float& l_reg, bf16x8& pa0, bf16x8& pa1, bf16x8& pa2, bf16x8& pa3) {
; #pragma unroll
;   for (int r = 0; r < 16; ++r) p1[r] = __builtin_amdgcn_exp2f(p1[r]);
;   float ps = 0;
; #pragma unroll
;   for (int r = 0; r < 16; ++r) ps += p0[r];
; #pragma unroll
;   for (int r = 0; r < 16; ++r) ps += p1[r];
;   { auto rr = __builtin_amdgcn_permlane32_swap(__float_as_uint(ps), __float_as_uint(ps), false, false);
;     ps = __uint_as_float(rr[0]) + __uint_as_float(rr[1]); }
;   l_reg = l_reg * alpha + ps;
;     ...
;   PK4(p0, 0, pa0); PK4(p0, 8, pa1); PK4(p1, 0, pa2); PK4(p1, 8, pa3);
; template <int MODE>
; __device__ __forceinline__ void attn_body(const bf16_t* __restrict__ Qb, const bf16_t* __restrict__ Kh, const bf16_t* __restrict__ Vh, int NT, int krel0,
;                                           char* lds, const float* __restrict__ lutg, const AttnEpi& E) {
;     ...
;   for (int j = 1; j + 1 < NT; j += 2) {
;     __syncthreads();
;     SBAR(); qkt<ND0, DOFF>(pB0, pB1, K_lds + oq, qr, r32, hi);
;     finishSM(pA0, pA1, alA, l_reg, pa0, pa1, pa2, pa3); SBAR();
;     SLOAD(SO, (j + 2) * 64); SBAR();
;     pv_d0(o, vb0 + op, pa0, pa1, pa2, pa3); PSM(pB0, pB1, mnB, alB, j);
.LBB0_79:
	s_mov_b32 s69, s0
	s_waitcnt lgkmcnt(0)
	s_barrier
	s_add_i32 s0, s71, 0
	v_add_u32_e32 v70, s0, v214
	ds_read_b128 v[66:69], v70 offset:49152
	ds_read_b128 v[70:73], v70 offset:57344
	v_add_u32_e32 v162, s0, v218
	ds_read_b128 v[230:233], v162 offset:49152
	ds_read_b128 v[234:237], v162 offset:57344
	v_add_u32_e32 v162, s0, v219
	s_waitcnt lgkmcnt(3)
	v_mfma_f32_32x32x16_bf16 v[82:97], v[66:69], v[114:117], 0
	v_exp_f32_e32 v160, v160
	v_exp_f32_e32 v161, v161
	v_exp_f32_e32 v158, v158
	v_exp_f32_e32 v159, v159
	v_exp_f32_e32 v156, v156
	v_exp_f32_e32 v157, v157
	v_exp_f32_e32 v154, v154
	s_waitcnt lgkmcnt(2)
	v_mfma_f32_32x32x16_bf16 v[66:81], v[70:73], v[114:117], 0
	v_exp_f32_e32 v155, v155
	v_exp_f32_e32 v152, v152
	v_exp_f32_e32 v153, v153
	v_exp_f32_e32 v150, v150
	v_exp_f32_e32 v151, v151
	v_exp_f32_e32 v148, v148
	v_exp_f32_e32 v149, v149
	s_waitcnt lgkmcnt(1)
	v_mfma_f32_32x32x16_bf16 v[82:97], v[230:233], v[126:129], v[82:97]
	v_exp_f32_e32 v146, v146
	v_exp_f32_e32 v147, v147
	v_cvt_pk_bf16_f32 v163, v175, v177
	v_cvt_pk_bf16_f32 v229, v172, v174
	s_waitcnt lgkmcnt(0)
	v_mfma_f32_32x32x16_bf16 v[66:81], v[234:237], v[126:129], v[66:81]
	ds_read_b128 v[230:233], v162 offset:49152
	ds_read_b128 v[234:237], v162 offset:57344
	v_add_u32_e32 v162, s0, v216
	s_waitcnt lgkmcnt(1)
	v_mfma_f32_32x32x16_bf16 v[82:97], v[230:233], v[118:121], v[82:97]
	s_waitcnt lgkmcnt(0)
	v_mfma_f32_32x32x16_bf16 v[66:81], v[234:237], v[118:121], v[66:81]
	ds_read_b128 v[230:233], v162 offset:49152
	ds_read_b128 v[234:237], v162 offset:57344
	v_add_u32_e32 v162, s0, v217
	s_waitcnt lgkmcnt(1)
	v_mfma_f32_32x32x16_bf16 v[82:97], v[230:233], v[122:125], v[82:97]
	s_waitcnt lgkmcnt(0)
	v_mfma_f32_32x32x16_bf16 v[66:81], v[234:237], v[122:125], v[66:81]
	ds_read_b128 v[230:233], v162 offset:49152
	ds_read_b128 v[234:237], v162 offset:57344
	v_add_u32_e32 v162, s0, v215
	s_waitcnt lgkmcnt(1)
	v_mfma_f32_32x32x16_bf16 v[82:97], v[230:233], v[110:113], v[82:97]
	s_waitcnt lgkmcnt(0)
	v_mfma_f32_32x32x16_bf16 v[66:81], v[234:237], v[110:113], v[66:81]
	ds_read_b128 v[230:233], v162 offset:49152
	ds_read_b128 v[234:237], v162 offset:57344
	v_add_u32_e32 v162, s0, v220
	s_waitcnt lgkmcnt(1)
	v_mfma_f32_32x32x16_bf16 v[82:97], v[230:233], v[106:109], v[82:97]
	s_waitcnt lgkmcnt(0)
	v_mfma_f32_32x32x16_bf16 v[66:81], v[234:237], v[106:109], v[66:81]
	ds_read_b128 v[230:233], v162 offset:49152
	ds_read_b128 v[234:237], v162 offset:57344
	v_add_u32_e32 v162, s0, v221
	s_waitcnt lgkmcnt(1)
	v_mfma_f32_32x32x16_bf16 v[82:97], v[230:233], v[102:105], v[82:97]
	s_waitcnt lgkmcnt(0)
	v_mfma_f32_32x32x16_bf16 v[66:81], v[234:237], v[102:105], v[66:81]
	ds_read_b128 v[230:233], v162 offset:49152
	ds_read_b128 v[234:237], v162 offset:57344
	v_add_f32_e32 v162, v165, v164
	v_add_f32_e32 v162, v175, v162
	v_add_f32_e32 v162, v177, v162
	v_add_f32_e32 v162, v227, v162
	v_add_f32_e32 v162, v228, v162
	v_add_f32_e32 v162, v176, v162
	v_add_f32_e32 v162, v226, v162
	v_add_f32_e32 v162, v167, v162
	v_add_f32_e32 v162, v169, v162
	v_add_f32_e32 v162, v171, v162
	v_add_f32_e32 v162, v173, v162
	v_add_f32_e32 v162, v168, v162
	v_add_f32_e32 v162, v170, v162
	v_add_f32_e32 v162, v172, v162
	v_add_f32_e32 v162, v174, v162
	v_add_f32_e32 v162, v160, v162
	v_add_f32_e32 v162, v161, v162
	v_add_f32_e32 v162, v158, v162
	v_add_f32_e32 v162, v159, v162
	v_add_f32_e32 v162, v156, v162
	v_add_f32_e32 v162, v157, v162
	v_add_f32_e32 v162, v154, v162
	v_add_f32_e32 v162, v155, v162
	v_add_f32_e32 v162, v152, v162
	v_add_f32_e32 v162, v153, v162
	s_waitcnt lgkmcnt(1)
	v_mfma_f32_32x32x16_bf16 v[82:97], v[230:233], v[98:101], v[82:97]
	v_add_f32_e32 v162, v150, v162
	v_add_f32_e32 v162, v151, v162
	v_add_f32_e32 v162, v148, v162
	v_add_f32_e32 v162, v149, v162
	v_add_f32_e32 v162, v146, v162
	v_add_f32_e32 v223, v147, v162
	v_mov_b32_e32 v224, v223
	s_waitcnt lgkmcnt(0)
	v_mfma_f32_32x32x16_bf16 v[66:81], v[234:237], v[98:101], v[66:81]
	v_cvt_pk_bf16_f32 v162, v164, v165
	v_cvt_pk_bf16_f32 v164, v227, v228
	v_permlane32_swap_b32_e32 v223, v224
	v_cvt_pk_bf16_f32 v165, v176, v226
	v_permlane32_swap_b32_e32 v162, v164
	v_cvt_pk_bf16_f32 v226, v167, v169
	v_cvt_pk_bf16_f32 v227, v171, v173
	v_cvt_pk_bf16_f32 v228, v168, v170
	v_cvt_pk_bf16_f32 v168, v160, v161
	v_cvt_pk_bf16_f32 v169, v158, v159
	v_cvt_pk_bf16_f32 v170, v156, v157
	v_cvt_pk_bf16_f32 v171, v154, v155
	v_cvt_pk_bf16_f32 v172, v152, v153
	v_cvt_pk_bf16_f32 v173, v150, v151
	v_cvt_pk_bf16_f32 v174, v148, v149
	v_cvt_pk_bf16_f32 v175, v146, v147
	v_permlane32_swap_b32_e32 v163, v165
	v_permlane32_swap_b32_e32 v226, v228
	v_permlane32_swap_b32_e32 v227, v229
	v_permlane32_swap_b32_e32 v168, v170
	v_permlane32_swap_b32_e32 v169, v171
	v_permlane32_swap_b32_e32 v172, v174
	v_permlane32_swap_b32_e32 v173, v175
	v_add_co_u32_e32 v150, vcc, s4, v190
	s_nop 1
	v_addc_co_u32_e32 v151, vcc, -1, v191, vcc
	v_add_co_u32_e32 v154, vcc, s5, v190
	s_nop 1
	v_addc_co_u32_e32 v155, vcc, -1, v191, vcc
	global_load_dwordx4 v[146:149], v[150:151], off
	s_nop 0
	global_load_dwordx4 v[150:153], v[150:151], off offset:-512
	s_nop 0
	global_load_dwordx4 v[158:161], v[154:155], off
	s_nop 0
	global_load_dwordx4 v[154:157], v[154:155], off offset:-512
	v_add_u32_e32 v208, s68, v209
	ds_read_b64_tr_b16 v[230:231], v208 offset:0
	ds_read_b64_tr_b16 v[232:233], v208 offset:0x800
	ds_read_b64_tr_b16 v[234:235], v208 offset:0x1000
	ds_read_b64_tr_b16 v[236:237], v208 offset:0x1800
	ds_read_b64_tr_b16 v[238:239], v208 offset:0x2000
	ds_read_b64_tr_b16 v[240:241], v208 offset:0x2800
	ds_read_b64_tr_b16 v[242:243], v208 offset:0x3000
	ds_read_b64_tr_b16 v[244:245], v208 offset:0x3800
	s_waitcnt lgkmcnt(0)
; #define SBAR() __builtin_amdgcn_sched_barrier(0)
; template <int MODE>
; __device__ __forceinline__ void partialSM(f32x16& p0, f32x16& p1, float& m_reg, float& mn, float& alpha, int relh, int relw_min, int relw_max, const float* lut) {
;     ...
;     if (__builtin_expect(__all(pmax - m_reg <= THR / SCALE), 1)) { mn = m_reg; alpha = 1.f; }
;     else { mn = fmaxf(m_reg, pmax); alpha = __builtin_amdgcn_exp2f((m_reg - mn) * C); m_reg = mn; }
;     const float mnC = -mn * C;
; #pragma unroll
;     for (int r = 0; r < 16; ++r) p0[r] = fmaf(p0[r], C, mnC);
; #pragma unroll
;     for (int r = 0; r < 16; ++r) p1[r] = fmaf(p1[r], C, mnC);
; #pragma unroll
;     for (int r = 0; r < 16; ++r) p0[r] = __builtin_amdgcn_exp2f(p0[r]);
; template <int D0> __device__ __forceinline__ void pv_one(f32x16& od, int vb, bf16x8 pa0, bf16x8 pa1, bf16x8 pa2, bf16x8 pa3) {
;   const s16x4 l0 = tr_read<v_rd_off(D0, 0, 0)>(vb), h0 = tr_read<v_rd_off(D0, 0, 1)>(vb), l1 = tr_read<v_rd_off(D0, 1, 0)>(vb), h1 = tr_read<v_rd_off(D0, 1, 1)>(vb);
;   const s16x4 l2 = tr_read<v_rd_off(D0, 2, 0)>(vb), h2 = tr_read<v_rd_off(D0, 2, 1)>(vb), l3 = tr_read<v_rd_off(D0, 3, 0)>(vb), h3 = tr_read<v_rd_off(D0, 3, 1)>(vb);
;   asm volatile("s_waitcnt lgkmcnt(0)" ::: "memory"); SBAR();
;     ...
;   od = __builtin_amdgcn_mfma_f32_32x32x16_bf16(pa0, PK(l0, h0), od, 0, 0, 0);
;   od = __builtin_amdgcn_mfma_f32_32x32x16_bf16(pa1, PK(l1, h1), od, 0, 0, 0);
;   od = __builtin_amdgcn_mfma_f32_32x32x16_bf16(pa2, PK(l2, h2), od, 0, 0, 0);
;   od = __builtin_amdgcn_mfma_f32_32x32x16_bf16(pa3, PK(l3, h3), od, 0, 0, 0);
;     ...
; }
; __device__ __forceinline__ void pv_d0(f32x16* o, int vb, bf16x8 pa0, bf16x8 pa1, bf16x8 pa2, bf16x8 pa3) {
;   pv_one<0>(o[0], vb, pa0, pa1, pa2, pa3); pv_one<1>(o[1], vb, pa0, pa1, pa2, pa3); pv_one<2>(o[2], vb, pa0, pa1, pa2, pa3); pv_one<3>(o[3], vb, pa0, pa1, pa2, pa3);
	s_nop 0
	v_mfma_f32_32x32x16_bf16 v[18:33], v[162:165], v[230:233], v[18:33]
	ds_read_b64_tr_b16 v[230:231], v208 offset:0x200
	ds_read_b64_tr_b16 v[232:233], v208 offset:0xa00
	v_mfma_f32_32x32x16_bf16 v[18:33], v[226:229], v[234:237], v[18:33]
	ds_read_b64_tr_b16 v[234:235], v208 offset:0x1200
	ds_read_b64_tr_b16 v[236:237], v208 offset:0x1a00
	v_mfma_f32_32x32x16_bf16 v[18:33], v[168:171], v[238:241], v[18:33]
	ds_read_b64_tr_b16 v[238:239], v208 offset:0x2200
	ds_read_b64_tr_b16 v[240:241], v208 offset:0x2a00
	v_mfma_f32_32x32x16_bf16 v[18:33], v[172:175], v[242:245], v[18:33]
	ds_read_b64_tr_b16 v[242:243], v208 offset:0x3200
	ds_read_b64_tr_b16 v[244:245], v208 offset:0x3a00
	s_waitcnt lgkmcnt(0)
	v_mfma_f32_32x32x16_bf16 v[50:65], v[162:165], v[230:233], v[50:65]
	ds_read_b64_tr_b16 v[230:231], v208 offset:0x400
	ds_read_b64_tr_b16 v[232:233], v208 offset:0xc00
	v_mfma_f32_32x32x16_bf16 v[50:65], v[226:229], v[234:237], v[50:65]
	ds_read_b64_tr_b16 v[234:235], v208 offset:0x1400
	ds_read_b64_tr_b16 v[236:237], v208 offset:0x1c00
	v_mfma_f32_32x32x16_bf16 v[50:65], v[168:171], v[238:241], v[50:65]
	ds_read_b64_tr_b16 v[238:239], v208 offset:0x2400
	ds_read_b64_tr_b16 v[240:241], v208 offset:0x2c00
	v_mfma_f32_32x32x16_bf16 v[50:65], v[172:175], v[242:245], v[50:65]
	ds_read_b64_tr_b16 v[242:243], v208 offset:0x3400
	ds_read_b64_tr_b16 v[244:245], v208 offset:0x3c00
	s_waitcnt lgkmcnt(0)
	v_mfma_f32_32x32x16_bf16 v[34:49], v[162:165], v[230:233], v[34:49]
	ds_read_b64_tr_b16 v[230:231], v208 offset:0x600
	ds_read_b64_tr_b16 v[232:233], v208 offset:0xe00
	v_mfma_f32_32x32x16_bf16 v[34:49], v[226:229], v[234:237], v[34:49]
	ds_read_b64_tr_b16 v[234:235], v208 offset:0x1600
	ds_read_b64_tr_b16 v[236:237], v208 offset:0x1e00
	v_mfma_f32_32x32x16_bf16 v[34:49], v[168:171], v[238:241], v[34:49]
	ds_read_b64_tr_b16 v[238:239], v208 offset:0x2600
	ds_read_b64_tr_b16 v[240:241], v208 offset:0x2e00
	v_mfma_f32_32x32x16_bf16 v[34:49], v[172:175], v[242:245], v[34:49]
	ds_read_b64_tr_b16 v[242:243], v208 offset:0x3600
	ds_read_b64_tr_b16 v[244:245], v208 offset:0x3e00
	s_waitcnt lgkmcnt(0)
	v_mfma_f32_32x32x16_bf16 v[2:17], v[162:165], v[230:233], v[2:17]
	v_mfma_f32_32x32x16_bf16 v[2:17], v[226:229], v[234:237], v[2:17]
	v_mfma_f32_32x32x16_bf16 v[2:17], v[168:171], v[238:241], v[2:17]
	v_mfma_f32_32x32x16_bf16 v[2:17], v[172:175], v[242:245], v[2:17]
	s_add_i32 s72, s69, 0
	v_add_u32_e32 v163, s72, v210
	s_waitcnt vmcnt(4)
	s_waitcnt vmcnt(4)
	ds_write_b128 v163, v[130:133]
	v_add_u32_e32 v163, s72, v211
	ds_write_b128 v163, v[138:141]
	v_add_u32_e32 v163, s72, v212
	ds_write_b128 v163, v[142:145] offset:49152
	v_add_u32_e32 v163, s72, v213
	ds_write_b128 v163, v[134:137] offset:49152
.LBB0_83:
	v_mov_b32_e32 v226, v166
	v_mul_f32_e32 v170, 0xbe0293ee, v226
	v_fmamk_f32 v82, v82, 0x3e0293ee, v170
	v_fmamk_f32 v83, v83, 0x3e0293ee, v170
	v_fmamk_f32 v84, v84, 0x3e0293ee, v170
	v_fmamk_f32 v85, v85, 0x3e0293ee, v170
	v_fmamk_f32 v86, v86, 0x3e0293ee, v170
	v_fmamk_f32 v87, v87, 0x3e0293ee, v170
	v_fmamk_f32 v88, v88, 0x3e0293ee, v170
	v_fmamk_f32 v89, v89, 0x3e0293ee, v170
	v_fmamk_f32 v90, v90, 0x3e0293ee, v170
	v_fmamk_f32 v91, v91, 0x3e0293ee, v170
	v_fmamk_f32 v92, v92, 0x3e0293ee, v170
	v_fmamk_f32 v93, v93, 0x3e0293ee, v170
	v_fmamk_f32 v94, v94, 0x3e0293ee, v170
	v_fmamk_f32 v95, v95, 0x3e0293ee, v170
	v_fmamk_f32 v96, v96, 0x3e0293ee, v170
	v_fmamk_f32 v97, v97, 0x3e0293ee, v170
	v_fmamk_f32 v171, v66, 0x3e0293ee, v170
	v_fmamk_f32 v172, v67, 0x3e0293ee, v170
	v_fmamk_f32 v173, v68, 0x3e0293ee, v170
	v_fmamk_f32 v174, v69, 0x3e0293ee, v170
	v_fmamk_f32 v175, v70, 0x3e0293ee, v170
	v_fmamk_f32 v176, v71, 0x3e0293ee, v170
	v_fmamk_f32 v177, v72, 0x3e0293ee, v170
	v_fmamk_f32 v227, v73, 0x3e0293ee, v170
	v_fmamk_f32 v228, v74, 0x3e0293ee, v170
	v_fmamk_f32 v229, v75, 0x3e0293ee, v170
	v_fmamk_f32 v230, v76, 0x3e0293ee, v170
	v_fmamk_f32 v231, v77, 0x3e0293ee, v170
	v_fmamk_f32 v232, v78, 0x3e0293ee, v170
	v_fmamk_f32 v233, v79, 0x3e0293ee, v170
	v_fmamk_f32 v234, v80, 0x3e0293ee, v170
	v_fmac_f32_e32 v170, 0x3e0293ee, v81
	v_exp_f32_e32 v235, v82
	v_exp_f32_e32 v236, v83
	v_exp_f32_e32 v237, v84
	v_exp_f32_e32 v238, v85
	v_exp_f32_e32 v239, v86
	v_exp_f32_e32 v240, v87
	v_exp_f32_e32 v241, v88
	v_exp_f32_e32 v242, v89
	v_exp_f32_e32 v243, v90
	v_exp_f32_e32 v244, v91
	v_exp_f32_e32 v245, v92
	v_exp_f32_e32 v246, v93
	v_exp_f32_e32 v247, v94
	v_exp_f32_e32 v248, v95
	v_exp_f32_e32 v249, v96
	v_exp_f32_e32 v250, v97
	s_waitcnt lgkmcnt(0)
	s_barrier
; #define SBAR() __builtin_amdgcn_sched_barrier(0)
; #define SLOAD(i, k0) do { sr_[i].vs0 = *reinterpret_cast<const bf16x8*>(&Vh[(size_t)((k0) + sr) * LDQK + sc]); sr_[i].vs1 = *reinterpret_cast<const bf16x8*>(&Vh[(size_t)((k0) + 32 + sr) * LDQK + sc]); \
;     sr_[i].ks0 = *reinterpret_cast<const bf16x8*>(&Kh[(size_t)((k0) + sr) * LDQK + sc]); sr_[i].ks1 = *reinterpret_cast<const bf16x8*>(&Kh[(size_t)((k0) + 32 + sr) * LDQK + sc]); } while (0)
; __device__ __forceinline__ void finishSM(f32x16& p0, f32x16& p1, float alpha, float& l_reg, bf16x8& pa0, bf16x8& pa1, bf16x8& pa2, bf16x8& pa3) {
; #pragma unroll
;   for (int r = 0; r < 16; ++r) p1[r] = __builtin_amdgcn_exp2f(p1[r]);
;   float ps = 0;
; #pragma unroll
;   for (int r = 0; r < 16; ++r) ps += p0[r];
; #pragma unroll
;   for (int r = 0; r < 16; ++r) ps += p1[r];
;   { auto rr = __builtin_amdgcn_permlane32_swap(__float_as_uint(ps), __float_as_uint(ps), false, false);
;     ps = __uint_as_float(rr[0]) + __uint_as_float(rr[1]); }
;   l_reg = l_reg * alpha + ps;
;     ...
;   PK4(p0, 0, pa0); PK4(p0, 8, pa1); PK4(p1, 0, pa2); PK4(p1, 8, pa3);
; template <int MODE>
; __device__ __forceinline__ void attn_body(const bf16_t* __restrict__ Qb, const bf16_t* __restrict__ Kh, const bf16_t* __restrict__ Vh, int NT, int krel0,
;                                           char* lds, const float* __restrict__ lutg, const AttnEpi& E) {
;     ...
;     __syncthreads();
;     SBAR(); qkt<ND0, DOFF>(pA0, pA1, K_lds + oq, qr, r32, hi);
;     finishSM(pB0, pB1, alB, l_reg, pa0, pa1, pa2, pa3); SBAR();
;     if (j + 3 < NT) SLOAD(SE, (j + 3) * 64); SBAR();
	v_add_u32_e32 v70, s72, v214
	ds_read_b128 v[66:69], v70 offset:49152
	ds_read_b128 v[70:73], v70 offset:57344
	v_add_u32_e32 v166, s72, v218
	ds_read_b128 v[162:165], v166 offset:49152
	ds_read_b128 v[166:169], v166 offset:57344
	v_exp_f32_e32 v171, v171
	s_waitcnt lgkmcnt(3)
	v_mfma_f32_32x32x16_bf16 v[82:97], v[66:69], v[114:117], 0
	v_exp_f32_e32 v172, v172
	v_exp_f32_e32 v173, v173
	v_exp_f32_e32 v174, v174
	v_exp_f32_e32 v175, v175
	v_exp_f32_e32 v176, v176
	v_exp_f32_e32 v177, v177
	v_exp_f32_e32 v227, v227
	s_waitcnt lgkmcnt(2)
	v_mfma_f32_32x32x16_bf16 v[66:81], v[70:73], v[114:117], 0
	v_exp_f32_e32 v228, v228
	v_exp_f32_e32 v251, v229
	v_exp_f32_e32 v195, v230
	v_exp_f32_e32 v231, v231
	v_exp_f32_e32 v232, v232
	v_exp_f32_e32 v233, v233
	v_exp_f32_e32 v234, v234
	s_waitcnt lgkmcnt(1)
	v_mfma_f32_32x32x16_bf16 v[82:97], v[162:165], v[126:129], v[82:97]
	v_exp_f32_e32 v194, v170
	v_cvt_pk_bf16_f32 v170, v171, v172
	s_waitcnt lgkmcnt(0)
	v_mfma_f32_32x32x16_bf16 v[66:81], v[166:169], v[126:129], v[66:81]
	v_add_u32_e32 v166, s72, v219
	ds_read_b128 v[162:165], v166 offset:49152
	ds_read_b128 v[166:169], v166 offset:57344
	s_waitcnt lgkmcnt(1)
	v_mfma_f32_32x32x16_bf16 v[82:97], v[162:165], v[118:121], v[82:97]
	s_waitcnt lgkmcnt(0)
	v_mfma_f32_32x32x16_bf16 v[66:81], v[166:169], v[118:121], v[66:81]
	v_add_u32_e32 v166, s72, v216
	ds_read_b128 v[162:165], v166 offset:49152
	ds_read_b128 v[166:169], v166 offset:57344
	s_waitcnt lgkmcnt(1)
	v_mfma_f32_32x32x16_bf16 v[82:97], v[162:165], v[122:125], v[82:97]
	s_waitcnt lgkmcnt(0)
	v_mfma_f32_32x32x16_bf16 v[66:81], v[166:169], v[122:125], v[66:81]
	v_add_u32_e32 v166, s72, v217
	ds_read_b128 v[162:165], v166 offset:49152
	ds_read_b128 v[166:169], v166 offset:57344
	s_waitcnt lgkmcnt(1)
	v_mfma_f32_32x32x16_bf16 v[82:97], v[162:165], v[110:113], v[82:97]
	s_waitcnt lgkmcnt(0)
	v_mfma_f32_32x32x16_bf16 v[66:81], v[166:169], v[110:113], v[66:81]
	v_add_u32_e32 v166, s72, v215
	ds_read_b128 v[162:165], v166 offset:49152
	ds_read_b128 v[166:169], v166 offset:57344
	s_waitcnt lgkmcnt(1)
	v_mfma_f32_32x32x16_bf16 v[82:97], v[162:165], v[106:109], v[82:97]
	s_waitcnt lgkmcnt(0)
	v_mfma_f32_32x32x16_bf16 v[66:81], v[166:169], v[106:109], v[66:81]
	v_add_u32_e32 v166, s72, v220
	ds_read_b128 v[162:165], v166 offset:49152
	ds_read_b128 v[166:169], v166 offset:57344
	s_waitcnt lgkmcnt(1)
	v_mfma_f32_32x32x16_bf16 v[82:97], v[162:165], v[102:105], v[82:97]
	s_waitcnt lgkmcnt(0)
	v_mfma_f32_32x32x16_bf16 v[66:81], v[166:169], v[102:105], v[66:81]
	v_add_u32_e32 v166, s72, v221
	ds_read_b128 v[162:165], v166 offset:49152
	ds_read_b128 v[166:169], v166 offset:57344
	s_waitcnt lgkmcnt(1)
	v_mfma_f32_32x32x16_bf16 v[82:97], v[162:165], v[98:101], v[82:97]
	v_add_f32_e32 v162, v236, v235
	v_add_f32_e32 v162, v237, v162
	v_add_f32_e32 v162, v238, v162
	v_add_f32_e32 v162, v239, v162
	v_add_f32_e32 v162, v240, v162
	v_add_f32_e32 v162, v241, v162
	v_add_f32_e32 v162, v242, v162
	v_add_f32_e32 v162, v243, v162
	v_add_f32_e32 v162, v244, v162
	v_add_f32_e32 v162, v245, v162
	v_add_f32_e32 v162, v246, v162
	v_add_f32_e32 v162, v247, v162
	v_add_f32_e32 v162, v248, v162
	v_add_f32_e32 v162, v249, v162
	v_add_f32_e32 v162, v250, v162
	v_add_f32_e32 v162, v171, v162
	v_add_f32_e32 v162, v172, v162
	v_add_f32_e32 v162, v173, v162
	v_add_f32_e32 v162, v174, v162
	v_add_f32_e32 v162, v175, v162
	v_add_f32_e32 v162, v176, v162
	v_add_f32_e32 v162, v177, v162
	v_add_f32_e32 v162, v227, v162
	v_add_f32_e32 v162, v228, v162
	v_add_f32_e32 v162, v251, v162
	s_waitcnt lgkmcnt(0)
	v_mfma_f32_32x32x16_bf16 v[66:81], v[166:169], v[98:101], v[66:81]
	v_add_f32_e32 v162, v195, v162
	v_add_f32_e32 v162, v231, v162
	v_add_f32_e32 v162, v232, v162
	v_add_f32_e32 v162, v233, v162
	v_add_f32_e32 v162, v234, v162
	v_add_f32_e32 v229, v194, v162
	v_mov_b32_e32 v230, v229
	v_cvt_pk_bf16_f32 v162, v235, v236
	v_cvt_pk_bf16_f32 v163, v237, v238
	v_cvt_pk_bf16_f32 v164, v239, v240
	v_cvt_pk_bf16_f32 v165, v241, v242
	v_cvt_pk_bf16_f32 v166, v243, v244
	v_cvt_pk_bf16_f32 v167, v245, v246
	v_cvt_pk_bf16_f32 v168, v247, v248
	v_cvt_pk_bf16_f32 v169, v249, v250
	v_cvt_pk_bf16_f32 v171, v173, v174
	v_cvt_pk_bf16_f32 v172, v175, v176
	v_cvt_pk_bf16_f32 v173, v177, v227
	v_cvt_pk_bf16_f32 v174, v228, v251
	v_cvt_pk_bf16_f32 v175, v195, v231
	v_cvt_pk_bf16_f32 v176, v232, v233
	v_cvt_pk_bf16_f32 v177, v234, v194
	v_permlane32_swap_b32_e32 v229, v230
	v_permlane32_swap_b32_e32 v162, v164
	v_permlane32_swap_b32_e32 v163, v165
	v_permlane32_swap_b32_e32 v166, v168
	v_permlane32_swap_b32_e32 v167, v169
	v_permlane32_swap_b32_e32 v170, v172
	v_permlane32_swap_b32_e32 v171, v173
	v_permlane32_swap_b32_e32 v174, v176
	v_permlane32_swap_b32_e32 v175, v177
	s_cmp_ge_u32 s66, s11
	s_cbranch_scc1 .LBB0_85
	v_add_co_u32_e32 v134, vcc, 0xfffb8000, v190
	s_nop 1
	v_addc_co_u32_e32 v135, vcc, -1, v191, vcc
	global_load_dwordx4 v[130:133], v[134:135], off
	global_load_dwordx4 v[142:145], v[134:135], off offset:-512
	global_load_dwordx4 v[138:141], v[190:191], off
	s_nop 0
	global_load_dwordx4 v[134:137], v[190:191], off offset:-512
; #define SWRITE(off, i) do { *(bf16x8*)(V_lds + (off) + vst0) = sr_[i].vs0;          \
;     *(bf16x8*)(V_lds + (off) + vst1) = sr_[i].vs1; int kc = sc * 2;               \
;     *(bf16x8*)(K_lds + (off) + KSWZ(sr, kc)) = sr_[i].ks0;                       \
;     *(bf16x8*)(K_lds + (off) + KSWZ(32 + sr, kc)) = sr_[i].ks1; } while (0)
; #define SWAIT() asm volatile("s_waitcnt vmcnt(4)" ::: "memory")
; #define RESC(a) do { if (__any((a) < 1.f)) { if (hi == 0) al_l[r32] = (a); asm volatile("s_waitcnt lgkmcnt(0)" ::: "memory"); \
;     _Pragma("unroll") for (int d = 0; d < 4; ++d) _Pragma("unroll") for (int r = 0; r < 16; ++r) o[d][r] *= al_l[crow(r, hi)]; } } while (0)
; #define PSM(P0, P1, MN, AL, J) partialSM<MODE>(P0, P1, m_reg, MN, AL, relq + 64 * (J), relwmin + 64 * (J), relwmax + 64 * (J), lut)
; template <int MODE>
; __device__ __forceinline__ void partialSM(f32x16& p0, f32x16& p1, float& m_reg, float& mn, float& alpha, int relh, int relw_min, int relw_max, const float* lut) {
;     ...
;     if (__builtin_expect(__all(pmax - m_reg <= THR / SCALE), 1)) { mn = m_reg; alpha = 1.f; }
;     else { mn = fmaxf(m_reg, pmax); alpha = __builtin_amdgcn_exp2f((m_reg - mn) * C); m_reg = mn; }
;     const float mnC = -mn * C;
; #pragma unroll
;     for (int r = 0; r < 16; ++r) p0[r] = fmaf(p0[r], C, mnC);
; #pragma unroll
;     for (int r = 0; r < 16; ++r) p1[r] = fmaf(p1[r], C, mnC);
; #pragma unroll
;     for (int r = 0; r < 16; ++r) p0[r] = __builtin_amdgcn_exp2f(p0[r]);
; template <int MODE>
; __device__ __forceinline__ void attn_body(const bf16_t* __restrict__ Qb, const bf16_t* __restrict__ Kh, const bf16_t* __restrict__ Vh, int NT, int krel0,
;                                           char* lds, const float* __restrict__ lutg, const AttnEpi& E) {
;     ...
;     pv_d0(o, vb0 + op, pa0, pa1, pa2, pa3); PSM(pA0, pA1, mnA, alA, j + 1);
;     SWAIT(); SWRITE(ow, SO);
;     RESC(alA);
;     { const int t = op; op = oq; oq = ow; ow = t; }
.LBB0_85:
	v_add_u32_e32 v194, s71, v209
	ds_read_b64_tr_b16 v[232:233], v194 offset:0
	ds_read_b64_tr_b16 v[234:235], v194 offset:0x800
	ds_read_b64_tr_b16 v[236:237], v194 offset:0x1000
	ds_read_b64_tr_b16 v[238:239], v194 offset:0x1800
	ds_read_b64_tr_b16 v[240:241], v194 offset:0x2000
	ds_read_b64_tr_b16 v[242:243], v194 offset:0x2800
	ds_read_b64_tr_b16 v[244:245], v194 offset:0x3000
	ds_read_b64_tr_b16 v[246:247], v194 offset:0x3800
	s_waitcnt lgkmcnt(0)
	s_nop 0
	v_mfma_f32_32x32x16_bf16 v[18:33], v[162:165], v[232:235], v[18:33]
	ds_read_b64_tr_b16 v[232:233], v194 offset:0x200
	ds_read_b64_tr_b16 v[234:235], v194 offset:0xa00
	v_mfma_f32_32x32x16_bf16 v[18:33], v[166:169], v[236:239], v[18:33]
	ds_read_b64_tr_b16 v[236:237], v194 offset:0x1200
	ds_read_b64_tr_b16 v[238:239], v194 offset:0x1a00
	v_mfma_f32_32x32x16_bf16 v[18:33], v[170:173], v[240:243], v[18:33]
	ds_read_b64_tr_b16 v[240:241], v194 offset:0x2200
	ds_read_b64_tr_b16 v[242:243], v194 offset:0x2a00
	v_mfma_f32_32x32x16_bf16 v[18:33], v[174:177], v[244:247], v[18:33]
	ds_read_b64_tr_b16 v[244:245], v194 offset:0x3200
	ds_read_b64_tr_b16 v[246:247], v194 offset:0x3a00
	s_waitcnt lgkmcnt(0)
	v_mfma_f32_32x32x16_bf16 v[50:65], v[162:165], v[232:235], v[50:65]
	ds_read_b64_tr_b16 v[232:233], v194 offset:0x400
	ds_read_b64_tr_b16 v[234:235], v194 offset:0xc00
	v_mfma_f32_32x32x16_bf16 v[50:65], v[166:169], v[236:239], v[50:65]
	ds_read_b64_tr_b16 v[236:237], v194 offset:0x1400
	ds_read_b64_tr_b16 v[238:239], v194 offset:0x1c00
	v_mfma_f32_32x32x16_bf16 v[50:65], v[170:173], v[240:243], v[50:65]
	ds_read_b64_tr_b16 v[240:241], v194 offset:0x2400
	ds_read_b64_tr_b16 v[242:243], v194 offset:0x2c00
	v_mfma_f32_32x32x16_bf16 v[50:65], v[174:177], v[244:247], v[50:65]
	ds_read_b64_tr_b16 v[244:245], v194 offset:0x3400
	ds_read_b64_tr_b16 v[246:247], v194 offset:0x3c00
	s_waitcnt lgkmcnt(0)
	v_mfma_f32_32x32x16_bf16 v[34:49], v[162:165], v[232:235], v[34:49]
	ds_read_b64_tr_b16 v[232:233], v194 offset:0x600
	ds_read_b64_tr_b16 v[234:235], v194 offset:0xe00
	v_mfma_f32_32x32x16_bf16 v[34:49], v[166:169], v[236:239], v[34:49]
	ds_read_b64_tr_b16 v[236:237], v194 offset:0x1600
	ds_read_b64_tr_b16 v[238:239], v194 offset:0x1e00
	v_mfma_f32_32x32x16_bf16 v[34:49], v[170:173], v[240:243], v[34:49]
	ds_read_b64_tr_b16 v[240:241], v194 offset:0x2600
	ds_read_b64_tr_b16 v[242:243], v194 offset:0x2e00
	v_mfma_f32_32x32x16_bf16 v[34:49], v[174:177], v[244:247], v[34:49]
	ds_read_b64_tr_b16 v[244:245], v194 offset:0x3600
	ds_read_b64_tr_b16 v[246:247], v194 offset:0x3e00
	s_waitcnt lgkmcnt(0)
	v_mfma_f32_32x32x16_bf16 v[2:17], v[162:165], v[232:235], v[2:17]
	v_mfma_f32_32x32x16_bf16 v[2:17], v[166:169], v[236:239], v[2:17]
	v_mfma_f32_32x32x16_bf16 v[2:17], v[170:173], v[240:243], v[2:17]
	v_mfma_f32_32x32x16_bf16 v[2:17], v[174:177], v[244:247], v[2:17]
	s_add_i32 s72, s68, 0
	v_add_u32_e32 v164, s72, v210
	s_waitcnt vmcnt(4)
	s_waitcnt vmcnt(3)
	ds_write_b128 v164, v[146:149]
	v_add_u32_e32 v146, s72, v211
	s_waitcnt vmcnt(1)
	ds_write_b128 v146, v[158:161]
	v_add_u32_e32 v146, s72, v212
	ds_write_b128 v146, v[150:153] offset:49152
	v_add_u32_e32 v146, s72, v213
	s_waitcnt vmcnt(0)
	ds_write_b128 v146, v[154:157] offset:49152
.LBB0_89:
	v_mov_b32_e32 v166, v226
	v_mul_f32_e32 v146, 0xbe0293ee, v166
	v_mov_b32_e32 v163, v146
	v_fmamk_f32 v82, v82, 0x3e0293ee, v146
	v_fmamk_f32 v83, v83, 0x3e0293ee, v146
	v_fmamk_f32 v84, v84, 0x3e0293ee, v146
	v_fmamk_f32 v85, v85, 0x3e0293ee, v146
	v_fmamk_f32 v86, v86, 0x3e0293ee, v146
	v_fmamk_f32 v87, v87, 0x3e0293ee, v146
	v_fmamk_f32 v88, v88, 0x3e0293ee, v146
	v_fmamk_f32 v89, v89, 0x3e0293ee, v146
	v_fmamk_f32 v90, v90, 0x3e0293ee, v146
	v_fmamk_f32 v91, v91, 0x3e0293ee, v146
	v_fmamk_f32 v92, v92, 0x3e0293ee, v146
	v_fmamk_f32 v93, v93, 0x3e0293ee, v146
	v_fmamk_f32 v94, v94, 0x3e0293ee, v146
	v_fmamk_f32 v95, v95, 0x3e0293ee, v146
	v_fmamk_f32 v96, v96, 0x3e0293ee, v146
	v_fmac_f32_e32 v163, 0x3e0293ee, v97
	v_exp_f32_e32 v164, v82
	v_exp_f32_e32 v165, v83
	v_exp_f32_e32 v175, v84
	v_exp_f32_e32 v177, v85
	v_exp_f32_e32 v227, v86
	v_exp_f32_e32 v228, v87
	v_exp_f32_e32 v176, v88
	v_exp_f32_e32 v226, v89
	v_exp_f32_e32 v167, v90
	v_exp_f32_e32 v169, v91
	v_exp_f32_e32 v171, v92
	v_exp_f32_e32 v173, v93
	v_exp_f32_e32 v168, v94
	v_exp_f32_e32 v170, v95
	v_exp_f32_e32 v172, v96
	v_exp_f32_e32 v174, v163
	v_fmamk_f32 v161, v67, 0x3e0293ee, v146
	v_fmamk_f32 v160, v66, 0x3e0293ee, v146
	v_add_f32_e32 v66, v223, v224
	v_add_f32_e32 v66, v207, v66
	v_add_f32_e32 v207, v229, v230
	s_add_i32 s0, s66, 2
	s_add_i32 s1, s66, -1
	v_fmamk_f32 v159, v69, 0x3e0293ee, v146
	v_fmamk_f32 v158, v68, 0x3e0293ee, v146
	v_fmamk_f32 v157, v71, 0x3e0293ee, v146
	v_fmamk_f32 v156, v70, 0x3e0293ee, v146
	v_fmamk_f32 v155, v73, 0x3e0293ee, v146
	v_fmamk_f32 v154, v72, 0x3e0293ee, v146
	v_fmamk_f32 v153, v75, 0x3e0293ee, v146
	v_fmamk_f32 v152, v74, 0x3e0293ee, v146
	v_fmamk_f32 v151, v77, 0x3e0293ee, v146
	v_fmamk_f32 v150, v76, 0x3e0293ee, v146
	v_fmamk_f32 v149, v79, 0x3e0293ee, v146
	v_fmamk_f32 v148, v78, 0x3e0293ee, v146
	v_fmamk_f32 v147, v81, 0x3e0293ee, v146
	v_fmamk_f32 v146, v80, 0x3e0293ee, v146
	v_add_f32_e32 v207, v66, v207
	s_cmp_ge_u32 s1, s70
	v_lshl_add_u64 v[190:191], v[190:191], 0, s[44:45]
	s_cbranch_scc1 .LBB0_91
	s_mov_b32 s66, s0
	s_mov_b32 s0, s71
	s_mov_b32 s71, s68
	s_mov_b32 s68, s69
	s_branch .LBB0_79
; #define SBAR() __builtin_amdgcn_sched_barrier(0)
; #define PSM(P0, P1, MN, AL, J) partialSM<MODE>(P0, P1, m_reg, MN, AL, relq + 64 * (J), relwmin + 64 * (J), relwmax + 64 * (J), lut)
; __device__ __forceinline__ void finishSM(f32x16& p0, f32x16& p1, float alpha, float& l_reg, bf16x8& pa0, bf16x8& pa1, bf16x8& pa2, bf16x8& pa3) {
; #pragma unroll
;   for (int r = 0; r < 16; ++r) p1[r] = __builtin_amdgcn_exp2f(p1[r]);
;   float ps = 0;
; #pragma unroll
;   for (int r = 0; r < 16; ++r) ps += p0[r];
; #pragma unroll
;   for (int r = 0; r < 16; ++r) ps += p1[r];
;   { auto rr = __builtin_amdgcn_permlane32_swap(__float_as_uint(ps), __float_as_uint(ps), false, false);
;     ps = __uint_as_float(rr[0]) + __uint_as_float(rr[1]); }
;   l_reg = l_reg * alpha + ps;
;     ...
;   PK4(p0, 0, pa0); PK4(p0, 8, pa1); PK4(p1, 0, pa2); PK4(p1, 8, pa3);
; template <int MODE>
; __device__ __forceinline__ void attn_body(const bf16_t* __restrict__ Qb, const bf16_t* __restrict__ Kh, const bf16_t* __restrict__ Vh, int NT, int krel0,
;                                           char* lds, const float* __restrict__ lutg, const AttnEpi& E) {
;     ...
;   __syncthreads();
;   SBAR(); qkt<ND0, DOFF>(pB0, pB1, K_lds + oq, qr, r32, hi);
;   finishSM(pA0, pA1, alA, l_reg, pa0, pa1, pa2, pa3); SBAR();
;   pv_d0(o, vb0 + op, pa0, pa1, pa2, pa3); PSM(pB0, pB1, mnB, alB, NT - 1);
.LBB0_91:
	v_mov_b32_e32 v162, 1.0
	s_waitcnt lgkmcnt(0)
	s_barrier
	v_add_u32_e32 v70, s72, v214
	ds_read_b128 v[66:69], v70 offset:49152
	ds_read_b128 v[70:73], v70 offset:57344
	v_add_u32_e32 v130, s72, v218
	s_waitcnt lgkmcnt(1)
	v_mfma_f32_32x32x16_bf16 v[82:97], v[66:69], v[114:117], 0
	s_waitcnt lgkmcnt(0)
	v_mfma_f32_32x32x16_bf16 v[66:81], v[70:73], v[114:117], 0
	ds_read_b128 v[114:117], v130 offset:49152
	ds_read_b128 v[130:133], v130 offset:57344
	s_waitcnt lgkmcnt(1)
	v_mfma_f32_32x32x16_bf16 v[82:97], v[114:117], v[126:129], v[82:97]
	s_waitcnt lgkmcnt(0)
	v_mfma_f32_32x32x16_bf16 v[66:81], v[130:133], v[126:129], v[66:81]
	v_add_u32_e32 v126, s72, v219
	ds_read_b128 v[114:117], v126 offset:49152
	ds_read_b128 v[126:129], v126 offset:57344
	s_waitcnt lgkmcnt(1)
	v_mfma_f32_32x32x16_bf16 v[82:97], v[114:117], v[118:121], v[82:97]
	s_waitcnt lgkmcnt(0)
	v_mfma_f32_32x32x16_bf16 v[66:81], v[126:129], v[118:121], v[66:81]
	v_add_u32_e32 v118, s72, v216
	ds_read_b128 v[114:117], v118 offset:49152
	ds_read_b128 v[118:121], v118 offset:57344
	s_waitcnt lgkmcnt(1)
	v_mfma_f32_32x32x16_bf16 v[82:97], v[114:117], v[122:125], v[82:97]
	s_waitcnt lgkmcnt(0)
	v_mfma_f32_32x32x16_bf16 v[66:81], v[118:121], v[122:125], v[66:81]
	v_add_u32_e32 v118, s72, v217
	ds_read_b128 v[114:117], v118 offset:49152
	ds_read_b128 v[118:121], v118 offset:57344
	v_exp_f32_e32 v122, v146
	v_exp_f32_e32 v123, v147
	s_waitcnt lgkmcnt(1)
	v_mfma_f32_32x32x16_bf16 v[82:97], v[114:117], v[110:113], v[82:97]
	v_add_u32_e32 v114, s72, v215
	s_waitcnt lgkmcnt(0)
	v_mfma_f32_32x32x16_bf16 v[66:81], v[118:121], v[110:113], v[66:81]
	ds_read_b128 v[110:113], v114 offset:49152
	ds_read_b128 v[114:117], v114 offset:57344
	v_exp_f32_e32 v118, v150
	v_exp_f32_e32 v119, v151
	v_exp_f32_e32 v120, v148
	v_exp_f32_e32 v121, v149
	s_waitcnt lgkmcnt(1)
	v_mfma_f32_32x32x16_bf16 v[82:97], v[110:113], v[106:109], v[82:97]
	v_add_u32_e32 v110, s72, v220
	s_waitcnt lgkmcnt(0)
	v_mfma_f32_32x32x16_bf16 v[66:81], v[114:117], v[106:109], v[66:81]
	ds_read_b128 v[106:109], v110 offset:49152
	ds_read_b128 v[110:113], v110 offset:57344
	v_exp_f32_e32 v114, v154
	v_exp_f32_e32 v115, v155
	v_exp_f32_e32 v116, v152
	v_exp_f32_e32 v117, v153
	s_waitcnt lgkmcnt(1)
	v_mfma_f32_32x32x16_bf16 v[82:97], v[106:109], v[102:105], v[82:97]
	v_add_u32_e32 v106, s72, v221
	s_waitcnt lgkmcnt(0)
	v_mfma_f32_32x32x16_bf16 v[66:81], v[110:113], v[102:105], v[66:81]
	ds_read_b128 v[102:105], v106 offset:49152
	ds_read_b128 v[106:109], v106 offset:57344
	v_exp_f32_e32 v110, v158
	v_exp_f32_e32 v111, v159
	v_exp_f32_e32 v112, v156
	v_exp_f32_e32 v113, v157
	s_waitcnt lgkmcnt(1)
	v_mfma_f32_32x32x16_bf16 v[82:97], v[102:105], v[98:101], v[82:97]
	v_cvt_pk_bf16_f32 v102, v227, v228
	v_cvt_pk_bf16_f32 v103, v176, v226
	v_cvt_pk_bf16_f32 v104, v167, v169
	v_cvt_pk_bf16_f32 v105, v171, v173
	s_waitcnt lgkmcnt(0)
	v_mfma_f32_32x32x16_bf16 v[66:81], v[106:109], v[98:101], v[66:81]
	v_add_f32_e32 v98, 0, v164
	v_add_f32_e32 v98, v165, v98
	v_add_f32_e32 v98, v175, v98
	v_add_f32_e32 v98, v177, v98
	v_add_f32_e32 v98, v227, v98
	v_add_f32_e32 v98, v228, v98
	v_add_f32_e32 v98, v176, v98
	v_add_f32_e32 v98, v226, v98
	v_add_f32_e32 v98, v167, v98
	v_add_f32_e32 v98, v169, v98
	v_add_f32_e32 v98, v171, v98
	v_add_f32_e32 v98, v173, v98
	v_exp_f32_e32 v108, v160
	v_add_f32_e32 v98, v168, v98
	v_exp_f32_e32 v109, v161
	v_add_f32_e32 v98, v170, v98
	v_add_f32_e32 v98, v172, v98
	v_add_f32_e32 v98, v174, v98
	v_add_f32_e32 v98, v108, v98
	v_add_f32_e32 v98, v109, v98
	v_add_f32_e32 v98, v110, v98
	v_add_f32_e32 v98, v111, v98
	v_add_f32_e32 v98, v112, v98
	v_add_f32_e32 v98, v113, v98
	v_add_f32_e32 v98, v114, v98
	v_add_f32_e32 v98, v115, v98
	v_add_f32_e32 v98, v116, v98
	v_add_f32_e32 v98, v117, v98
	v_add_f32_e32 v98, v118, v98
	v_add_f32_e32 v98, v119, v98
	v_add_f32_e32 v98, v120, v98
	v_add_f32_e32 v98, v121, v98
	v_add_f32_e32 v98, v122, v98
	v_add_f32_e32 v98, v123, v98
	v_mov_b32_e32 v99, v98
	v_cvt_pk_bf16_f32 v100, v164, v165
	v_cvt_pk_bf16_f32 v101, v175, v177
	v_permlane32_swap_b32_e32 v98, v99
	v_permlane32_swap_b32_e32 v100, v102
	v_permlane32_swap_b32_e32 v101, v103
	v_cvt_pk_bf16_f32 v106, v168, v170
	v_cvt_pk_bf16_f32 v107, v172, v174
	v_cvt_pk_bf16_f32 v108, v108, v109
	v_cvt_pk_bf16_f32 v109, v110, v111
	v_cvt_pk_bf16_f32 v110, v112, v113
	v_cvt_pk_bf16_f32 v111, v114, v115
	v_cvt_pk_bf16_f32 v112, v116, v117
	v_cvt_pk_bf16_f32 v113, v118, v119
	v_cvt_pk_bf16_f32 v114, v120, v121
	v_cvt_pk_bf16_f32 v115, v122, v123
	v_permlane32_swap_b32_e32 v104, v106
	v_permlane32_swap_b32_e32 v105, v107
	v_permlane32_swap_b32_e32 v108, v110
	v_permlane32_swap_b32_e32 v109, v111
	v_permlane32_swap_b32_e32 v112, v114
	v_permlane32_swap_b32_e32 v113, v115
	v_add_u32_e32 v132, s69, v209
	ds_read_b64_tr_b16 v[116:117], v132 offset:0
	ds_read_b64_tr_b16 v[118:119], v132 offset:0x800
	ds_read_b64_tr_b16 v[120:121], v132 offset:0x1000
	ds_read_b64_tr_b16 v[122:123], v132 offset:0x1800
	ds_read_b64_tr_b16 v[124:125], v132 offset:0x2000
	ds_read_b64_tr_b16 v[126:127], v132 offset:0x2800
	ds_read_b64_tr_b16 v[128:129], v132 offset:0x3000
	ds_read_b64_tr_b16 v[130:131], v132 offset:0x3800
	s_waitcnt lgkmcnt(0)
; #define RESC(a) do { if (__any((a) < 1.f)) { if (hi == 0) al_l[r32] = (a); asm volatile("s_waitcnt lgkmcnt(0)" ::: "memory"); \
;     _Pragma("unroll") for (int d = 0; d < 4; ++d) _Pragma("unroll") for (int r = 0; r < 16; ++r) o[d][r] *= al_l[crow(r, hi)]; } } while (0)
; #define PSM(P0, P1, MN, AL, J) partialSM<MODE>(P0, P1, m_reg, MN, AL, relq + 64 * (J), relwmin + 64 * (J), relwmax + 64 * (J), lut)
; template <int MODE>
; __device__ __forceinline__ void partialSM(f32x16& p0, f32x16& p1, float& m_reg, float& mn, float& alpha, int relh, int relw_min, int relw_max, const float* lut) {
;     ...
;     float pmax = p0[0];
; #pragma unroll
;     for (int r = 1; r < 16; ++r) pmax = fmaxf(pmax, p0[r]);
; #pragma unroll
;     for (int r = 0; r < 16; ++r) pmax = fmaxf(pmax, p1[r]);
;     { auto rr = __builtin_amdgcn_permlane32_swap(__float_as_uint(pmax), __float_as_uint(pmax), false, false);
;       pmax = fmaxf(__uint_as_float(rr[0]), __uint_as_float(rr[1])); }
;     if (__builtin_expect(__all(pmax - m_reg <= THR / SCALE), 1)) { mn = m_reg; alpha = 1.f; }
;     else { mn = fmaxf(m_reg, pmax); alpha = __builtin_amdgcn_exp2f((m_reg - mn) * C); m_reg = mn; }
;     const float mnC = -mn * C;
; #pragma unroll
; template <int MODE>
; __device__ __forceinline__ void attn_body(const bf16_t* __restrict__ Qb, const bf16_t* __restrict__ Kh, const bf16_t* __restrict__ Vh, int NT, int krel0,
;                                           char* lds, const float* __restrict__ lutg, const AttnEpi& E) {
;     ...
;   pv_d0(o, vb0 + op, pa0, pa1, pa2, pa3); PSM(pB0, pB1, mnB, alB, NT - 1);
;   RESC(alB);
	s_nop 0
	v_mfma_f32_32x32x16_bf16 v[18:33], v[100:103], v[116:119], v[18:33]
	ds_read_b64_tr_b16 v[116:117], v132 offset:0x200
	ds_read_b64_tr_b16 v[118:119], v132 offset:0xa00
	v_mfma_f32_32x32x16_bf16 v[18:33], v[104:107], v[120:123], v[18:33]
	ds_read_b64_tr_b16 v[120:121], v132 offset:0x1200
	ds_read_b64_tr_b16 v[122:123], v132 offset:0x1a00
	v_mfma_f32_32x32x16_bf16 v[18:33], v[108:111], v[124:127], v[18:33]
	ds_read_b64_tr_b16 v[124:125], v132 offset:0x2200
	ds_read_b64_tr_b16 v[126:127], v132 offset:0x2a00
	v_mfma_f32_32x32x16_bf16 v[18:33], v[112:115], v[128:131], v[18:33]
	ds_read_b64_tr_b16 v[128:129], v132 offset:0x3200
	ds_read_b64_tr_b16 v[130:131], v132 offset:0x3a00
	s_waitcnt lgkmcnt(0)
	v_mfma_f32_32x32x16_bf16 v[50:65], v[100:103], v[116:119], v[50:65]
	ds_read_b64_tr_b16 v[116:117], v132 offset:0x400
	ds_read_b64_tr_b16 v[118:119], v132 offset:0xc00
	v_mfma_f32_32x32x16_bf16 v[50:65], v[104:107], v[120:123], v[50:65]
	ds_read_b64_tr_b16 v[120:121], v132 offset:0x1400
	ds_read_b64_tr_b16 v[122:123], v132 offset:0x1c00
	v_mfma_f32_32x32x16_bf16 v[50:65], v[108:111], v[124:127], v[50:65]
	ds_read_b64_tr_b16 v[124:125], v132 offset:0x2400
	ds_read_b64_tr_b16 v[126:127], v132 offset:0x2c00
	v_mfma_f32_32x32x16_bf16 v[50:65], v[112:115], v[128:131], v[50:65]
	ds_read_b64_tr_b16 v[128:129], v132 offset:0x3400
	ds_read_b64_tr_b16 v[130:131], v132 offset:0x3c00
	s_waitcnt lgkmcnt(0)
	v_mfma_f32_32x32x16_bf16 v[34:49], v[100:103], v[116:119], v[34:49]
	ds_read_b64_tr_b16 v[116:117], v132 offset:0x600
	ds_read_b64_tr_b16 v[118:119], v132 offset:0xe00
	v_mfma_f32_32x32x16_bf16 v[34:49], v[104:107], v[120:123], v[34:49]
	ds_read_b64_tr_b16 v[120:121], v132 offset:0x1600
	ds_read_b64_tr_b16 v[122:123], v132 offset:0x1e00
	v_mfma_f32_32x32x16_bf16 v[34:49], v[108:111], v[124:127], v[34:49]
	ds_read_b64_tr_b16 v[124:125], v132 offset:0x2600
	ds_read_b64_tr_b16 v[126:127], v132 offset:0x2e00
	v_mfma_f32_32x32x16_bf16 v[34:49], v[112:115], v[128:131], v[34:49]
	ds_read_b64_tr_b16 v[128:129], v132 offset:0x3600
	ds_read_b64_tr_b16 v[130:131], v132 offset:0x3e00
	s_waitcnt lgkmcnt(0)
	v_mfma_f32_32x32x16_bf16 v[2:17], v[100:103], v[116:119], v[2:17]
	v_max_f32_e32 v100, v83, v83
	v_max_f32_e32 v101, v82, v82
	v_max_f32_e32 v100, v101, v100
	v_max3_f32 v100, v100, v84, v85
	v_max3_f32 v100, v100, v86, v87
	v_max3_f32 v100, v100, v88, v89
	v_max3_f32 v100, v100, v90, v91
	v_max3_f32 v100, v100, v92, v93
	v_max3_f32 v100, v100, v94, v95
	v_mfma_f32_32x32x16_bf16 v[2:17], v[104:107], v[120:123], v[2:17]
	v_max3_f32 v100, v100, v96, v97
	v_max3_f32 v100, v100, v66, v67
	v_max3_f32 v100, v100, v68, v69
	v_max3_f32 v100, v100, v70, v71
	v_max3_f32 v100, v100, v72, v73
	v_max3_f32 v100, v100, v74, v75
	v_max3_f32 v100, v100, v76, v77
	v_max3_f32 v100, v100, v78, v79
	v_mfma_f32_32x32x16_bf16 v[2:17], v[108:111], v[124:127], v[2:17]
	v_max3_f32 v100, v100, v80, v81
	v_mov_b32_e32 v101, v100
	s_nop 1
	v_permlane32_swap_b32_e32 v100, v101
	v_max_f32_e32 v101, v101, v101
	v_max_f32_e32 v100, v100, v100
	v_max_f32_e32 v100, v100, v101
	v_sub_f32_e32 v101, v100, v166
	v_cmp_ge_f32_e32 vcc, s40, v101
	v_max_f32_e32 v101, v166, v166
	v_max_f32_e32 v101, v101, v100
	v_mfma_f32_32x32x16_bf16 v[2:17], v[112:115], v[128:131], v[2:17]
	v_sub_f32_e32 v100, v166, v101
	v_mul_f32_e32 v100, 0x3e0293ee, v100
	v_exp_f32_e32 v100, v100
	s_cmp_eq_u64 vcc, exec
	s_cselect_b64 s[0:1], -1, 0
	v_cndmask_b32_e64 v100, v100, 1.0, s[0:1]
	v_cmp_gt_f32_e32 vcc, 1.0, v100
	s_cbranch_vccz .LBB0_95
	s_and_saveexec_b64 s[56:57], s[6:7]
	ds_write_b32 v206, v100 offset:128
	s_or_b64 exec, exec, s[56:57]
	s_waitcnt lgkmcnt(0)
	ds_read_b128 v[102:105], v0 offset:224
	ds_read_b128 v[106:109], v0 offset:192
	ds_read_b128 v[110:113], v0 offset:160
	ds_read_b128 v[114:117], v0 offset:128
	s_waitcnt lgkmcnt(3)
	v_pk_mul_f32 v[32:33], v[32:33], v[104:105]
	s_waitcnt lgkmcnt(2)
	v_pk_mul_f32 v[28:29], v[28:29], v[108:109]
	s_waitcnt lgkmcnt(1)
	v_pk_mul_f32 v[24:25], v[24:25], v[112:113]
	s_waitcnt lgkmcnt(0)
	v_pk_mul_f32 v[20:21], v[20:21], v[116:117]
	v_pk_mul_f32 v[30:31], v[30:31], v[102:103]
	v_pk_mul_f32 v[26:27], v[26:27], v[106:107]
	v_pk_mul_f32 v[22:23], v[22:23], v[110:111]
	v_pk_mul_f32 v[18:19], v[18:19], v[114:115]
	v_pk_mul_f32 v[64:65], v[64:65], v[104:105]
	v_pk_mul_f32 v[60:61], v[60:61], v[108:109]
	v_pk_mul_f32 v[56:57], v[56:57], v[112:113]
	v_pk_mul_f32 v[52:53], v[52:53], v[116:117]
	v_pk_mul_f32 v[62:63], v[62:63], v[102:103]
	v_pk_mul_f32 v[58:59], v[58:59], v[106:107]
	v_pk_mul_f32 v[54:55], v[54:55], v[110:111]
	v_pk_mul_f32 v[50:51], v[50:51], v[114:115]
	v_pk_mul_f32 v[48:49], v[48:49], v[104:105]
	v_pk_mul_f32 v[44:45], v[44:45], v[108:109]
	v_pk_mul_f32 v[40:41], v[40:41], v[112:113]
	v_pk_mul_f32 v[36:37], v[36:37], v[116:117]
	v_pk_mul_f32 v[46:47], v[46:47], v[102:103]
	v_pk_mul_f32 v[42:43], v[42:43], v[106:107]
	v_pk_mul_f32 v[38:39], v[38:39], v[110:111]
	v_pk_mul_f32 v[34:35], v[34:35], v[114:115]
	v_pk_mul_f32 v[16:17], v[16:17], v[104:105]
	v_pk_mul_f32 v[12:13], v[12:13], v[108:109]
	v_pk_mul_f32 v[8:9], v[8:9], v[112:113]
	v_pk_mul_f32 v[4:5], v[4:5], v[116:117]
	v_pk_mul_f32 v[14:15], v[14:15], v[102:103]
	v_pk_mul_f32 v[10:11], v[10:11], v[106:107]
	v_pk_mul_f32 v[6:7], v[6:7], v[110:111]
	v_pk_mul_f32 v[2:3], v[2:3], v[114:115]

; template <int MODE>
; __device__ __forceinline__ void attn_body(const bf16_t* __restrict__ Qb, const bf16_t* __restrict__ Kh, const bf16_t* __restrict__ Vh, int NT, int krel0,
;                                           char* lds, const float* __restrict__ lutg, const AttnEpi& E) {
;     ...
;   const bf16_t* Qw = Qb + (size_t)(wid * 32 + r32) * LDQK + hi * 8;
;   {
;     float qf[ND0][8]; float ss = 0.f;
; #pragma unroll
;     for (int d0 = 0; d0 < ND0; ++d0) { const bf16x8 raw = *reinterpret_cast<const bf16x8*>(Qw + d0 * 16);
; #pragma unroll
;       for (int j = 0; j < 8; ++j) { const float v = __uint_as_float(((unsigned)(unsigned short)raw[j]) << 16); qf[d0][j] = v; ss += v * v; } }
;     { auto rr = __builtin_amdgcn_permlane32_swap(__float_as_uint(ss), __float_as_uint(ss), false, false);
;       ss = __uint_as_float(rr[0]) + __uint_as_float(rr[1]); }
;     const float rs = rsqrtf(ss * (MODE < 2 ? (1.f / 128.f) : (1.f / 64.f)) + EPS);
; #pragma unroll
;     for (int d0 = 0; d0 < ND0; ++d0) { const f32x4 g0 = *(const f32x4*)(E.gq + d0 * 16 + hi * 8), g1 = *(const f32x4*)(E.gq + d0 * 16 + hi * 8 + 4);
; #pragma unroll
;       for (int j = 0; j < 4; ++j) { qf[d0][j] = qf[d0][j] * rs * g0[j]; qf[d0][4 + j] = qf[d0][4 + j] * rs * g1[j]; } }
.LBB0_125:
	s_or_b64 exec, exec, s[0:1]
	s_add_u32 s0, s17, s16
	s_addc_u32 s1, s18, 0
	s_add_u32 s62, s0, 0x1800
	s_addc_u32 s63, s1, 0
	v_ashrrev_i32_e32 v3, 1, v188
	s_movk_i32 s6, 0xffe0
	v_bfe_u32 v2, v188, 5, 1
	v_bfi_b32 v4, s6, v3, v188
	v_mov_b64_e32 v[6:7], s[62:63]
	v_mad_i64_i32 v[6:7], s[6:7], v4, s73, v[6:7]
	v_lshlrev_b32_e32 v0, 4, v2
	v_lshl_add_u64 v[18:19], v[6:7], 0, v[0:1]
	global_load_dwordx4 v[6:9], v[18:19], off
	global_load_dwordx4 v[10:13], v[18:19], off offset:32
	global_load_dwordx4 v[14:17], v[18:19], off offset:64
	s_nop 0
	global_load_dwordx4 v[18:21], v[18:19], off offset:96
	v_and_b32_e32 v5, 32, v188
	global_load_dwordx4 v[22:25], v5, s[52:53] offset:16
	global_load_dwordx4 v[26:29], v5, s[52:53]
	global_load_dwordx4 v[30:33], v5, s[52:53] offset:80
	global_load_dwordx4 v[34:37], v5, s[52:53] offset:64
	global_load_dwordx4 v[38:41], v5, s[52:53] offset:144
	global_load_dwordx4 v[42:45], v5, s[52:53] offset:128
	global_load_dwordx4 v[46:49], v5, s[52:53] offset:208
	global_load_dwordx4 v[54:57], v5, s[52:53] offset:192
	s_add_u32 s0, s67, s68
	s_addc_u32 s1, s65, 0
	s_add_u32 s58, s0, 0x2000
	s_addc_u32 s59, s1, 0
	s_add_u32 s0, s0, 0x2200
	s_addc_u32 s1, s1, 0
	s_sub_i32 s77, 0, s64
	s_sub_i32 s78, 63, s64
	s_movk_i32 s64, 0x1200
	v_and_b32_e32 v53, 0xffffffe0, v3
	v_sub_u32_e32 v4, s77, v4
	v_and_b32_e32 v52, 31, v188
	v_sub_u32_e32 v205, s78, v53
	s_waitcnt vmcnt(11)
	v_and_b32_e32 v71, 0xffff0000, v7
	v_lshlrev_b32_e32 v70, 16, v7
	v_and_b32_e32 v7, 0xffff0000, v6
	v_lshlrev_b32_e32 v6, 16, v6
	v_mul_f32_e32 v72, v7, v7
	v_pk_fma_f32 v[72:73], v[6:7], v[6:7], v[72:73] op_sel_hi:[1,1,0]
	v_mul_f32_e32 v74, v71, v71
	v_pk_fma_f32 v[72:73], v[70:71], v[70:71], v[72:73]
	v_and_b32_e32 v69, 0xffff0000, v9
	v_lshlrev_b32_e32 v68, 16, v9
	v_and_b32_e32 v9, 0xffff0000, v8
	v_lshlrev_b32_e32 v8, 16, v8
	v_pk_add_f32 v[72:73], v[74:75], v[72:73] op_sel_hi:[0,1]
	v_pk_fma_f32 v[72:73], v[8:9], v[8:9], v[72:73]
	v_mul_f32_e32 v74, v9, v9
	v_pk_add_f32 v[72:73], v[74:75], v[72:73] op_sel_hi:[0,1]
	v_pk_fma_f32 v[72:73], v[68:69], v[68:69], v[72:73]
	v_mul_f32_e32 v74, v69, v69
	s_waitcnt vmcnt(10)
	v_and_b32_e32 v67, 0xffff0000, v11
	v_lshlrev_b32_e32 v66, 16, v11
	v_and_b32_e32 v11, 0xffff0000, v10
	v_lshlrev_b32_e32 v10, 16, v10
	v_pk_add_f32 v[72:73], v[74:75], v[72:73] op_sel_hi:[0,1]
	v_pk_fma_f32 v[72:73], v[10:11], v[10:11], v[72:73]
	v_mul_f32_e32 v74, v11, v11
	v_pk_add_f32 v[72:73], v[74:75], v[72:73] op_sel_hi:[0,1]
	v_pk_fma_f32 v[72:73], v[66:67], v[66:67], v[72:73]
	v_mul_f32_e32 v74, v67, v67
	v_and_b32_e32 v65, 0xffff0000, v13
	v_lshlrev_b32_e32 v64, 16, v13
	v_and_b32_e32 v13, 0xffff0000, v12
	v_lshlrev_b32_e32 v12, 16, v12
	v_pk_add_f32 v[72:73], v[74:75], v[72:73] op_sel_hi:[0,1]
	v_pk_fma_f32 v[72:73], v[12:13], v[12:13], v[72:73]
	v_mul_f32_e32 v74, v13, v13
	v_pk_add_f32 v[72:73], v[74:75], v[72:73] op_sel_hi:[0,1]
	v_pk_fma_f32 v[72:73], v[64:65], v[64:65], v[72:73]
	v_mul_f32_e32 v74, v65, v65
	s_waitcnt vmcnt(9)
	v_and_b32_e32 v63, 0xffff0000, v15
	v_lshlrev_b32_e32 v62, 16, v15
	v_and_b32_e32 v15, 0xffff0000, v14
	v_lshlrev_b32_e32 v14, 16, v14
	v_pk_add_f32 v[72:73], v[74:75], v[72:73] op_sel_hi:[0,1]
	v_pk_fma_f32 v[72:73], v[14:15], v[14:15], v[72:73]
	v_mul_f32_e32 v74, v15, v15
	v_pk_add_f32 v[72:73], v[74:75], v[72:73] op_sel_hi:[0,1]
	v_pk_fma_f32 v[72:73], v[62:63], v[62:63], v[72:73]
	v_mul_f32_e32 v74, v63, v63
	v_and_b32_e32 v61, 0xffff0000, v17
	v_lshlrev_b32_e32 v60, 16, v17
	v_and_b32_e32 v17, 0xffff0000, v16
	v_lshlrev_b32_e32 v16, 16, v16
	v_pk_add_f32 v[72:73], v[74:75], v[72:73] op_sel_hi:[0,1]
	v_pk_fma_f32 v[72:73], v[16:17], v[16:17], v[72:73]
	v_mul_f32_e32 v74, v17, v17
	v_pk_add_f32 v[72:73], v[74:75], v[72:73] op_sel_hi:[0,1]
	v_pk_fma_f32 v[72:73], v[60:61], v[60:61], v[72:73]
	v_mul_f32_e32 v74, v61, v61
	s_waitcnt vmcnt(8)
	v_and_b32_e32 v59, 0xffff0000, v19
	v_lshlrev_b32_e32 v58, 16, v19
	v_and_b32_e32 v19, 0xffff0000, v18
	v_lshlrev_b32_e32 v18, 16, v18
	v_pk_add_f32 v[72:73], v[74:75], v[72:73] op_sel_hi:[0,1]
	v_pk_fma_f32 v[72:73], v[18:19], v[18:19], v[72:73]
	v_mul_f32_e32 v74, v19, v19
	v_pk_add_f32 v[72:73], v[74:75], v[72:73] op_sel_hi:[0,1]
	v_pk_fma_f32 v[72:73], v[58:59], v[58:59], v[72:73]
	v_mul_f32_e32 v74, v59, v59
	v_and_b32_e32 v51, 0xffff0000, v21
	v_lshlrev_b32_e32 v50, 16, v21
	v_and_b32_e32 v21, 0xffff0000, v20
	v_lshlrev_b32_e32 v20, 16, v20
	v_pk_add_f32 v[72:73], v[74:75], v[72:73] op_sel_hi:[0,1]
	v_pk_fma_f32 v[72:73], v[20:21], v[20:21], v[72:73]
	v_mul_f32_e32 v74, v21, v21
	v_pk_add_f32 v[72:73], v[74:75], v[72:73] op_sel_hi:[0,1]
	v_pk_fma_f32 v[72:73], v[50:51], v[50:51], v[72:73]
	v_mul_f32_e32 v74, v51, v51
	v_pk_add_f32 v[72:73], v[74:75], v[72:73] op_sel_hi:[0,1]
	v_mov_b32_e32 v5, v72
	s_nop 1
	v_permlane32_swap_b32_e32 v72, v5
	v_add_f32_e32 v5, v72, v5
	v_fmamk_f32 v5, v5, 0x3c800000, v178
	v_cmp_gt_f32_e32 vcc, s49, v5
	v_mul_f32_e32 v72, 0x4b800000, v5
	s_nop 0
	v_cndmask_b32_e32 v5, v5, v72, vcc
	v_rsq_f32_e32 v5, v5
	s_nop 0
	v_mul_f32_e32 v72, 0x45800000, v5
	v_cndmask_b32_e32 v72, v5, v72, vcc
	v_pk_mul_f32 v[6:7], v[72:73], v[6:7] op_sel_hi:[0,1]
	s_waitcnt vmcnt(6)
	v_pk_mul_f32 v[6:7], v[26:27], v[6:7]
	v_pk_mul_f32 v[26:27], v[72:73], v[68:69] op_sel_hi:[0,1]
	v_pk_mul_f32 v[24:25], v[24:25], v[26:27]
	v_pk_mul_f32 v[26:27], v[72:73], v[66:67] op_sel_hi:[0,1]
	s_waitcnt vmcnt(4)
; __device__ __forceinline__ unsigned cvtpk(float lo, float hi) { f32x2 v = {lo, hi}; bf16v2 b = __builtin_convertvector(v, bf16v2); return __builtin_bit_cast(unsigned, b); }
; __device__ __forceinline__ int v_st(int k, int c) { const int kk = (k & ~0xC) | ((k & 4) << 1) | ((k & 8) >> 1); return ((kk >> 3) * 4 + (c >> 5)) * 512 + ((kk & 7) * 32 + (c & 31)) * 2; }
; __device__ __forceinline__ int v_rd_base(int lane) { return ((lane & 3) << 3) | (((lane >> 2) & 3) << 6) | (((lane >> 4) & 1) << 5) | (((lane >> 5) & 1) << 8); }
; #define SLOAD(i, k0) do { sr_[i].vs0 = *reinterpret_cast<const bf16x8*>(&Vh[(size_t)((k0) + sr) * LDQK + sc]); sr_[i].vs1 = *reinterpret_cast<const bf16x8*>(&Vh[(size_t)((k0) + 32 + sr) * LDQK + sc]); \
;     sr_[i].ks0 = *reinterpret_cast<const bf16x8*>(&Kh[(size_t)((k0) + sr) * LDQK + sc]); sr_[i].ks1 = *reinterpret_cast<const bf16x8*>(&Kh[(size_t)((k0) + 32 + sr) * LDQK + sc]); } while (0)
; #define PSM(P0, P1, MN, AL, J) partialSM<MODE>(P0, P1, m_reg, MN, AL, relq + 64 * (J), relwmin + 64 * (J), relwmax + 64 * (J), lut)
; template <int MODE>
; __device__ __forceinline__ void attn_body(const bf16_t* __restrict__ Qb, const bf16_t* __restrict__ Kh, const bf16_t* __restrict__ Vh, int NT, int krel0,
;                                           char* lds, const float* __restrict__ lutg, const AttnEpi& E) {
;     ...
;     for (int d0 = 0; d0 < ND0; ++d0) { u32x4 w; w.x = cvtpk(qf[d0][0], qf[d0][1]); w.y = cvtpk(qf[d0][2], qf[d0][3]); w.z = cvtpk(qf[d0][4], qf[d0][5]); w.w = cvtpk(qf[d0][6], qf[d0][7]);
;       qr[d0] = *reinterpret_cast<bf16x8*>(&w); }
;   }
;   const int sr = tid >> 4, sc = (tid & 15) * 8, vst0 = v_st(sr, sc), vst1 = v_st(32 + sr, sc);
;   const int vb0 = (int)(uintptr_t)V_lds + v_rd_base(lane);
;   struct { bf16x8 vs0, vs1, ks0, ks1; } sr_[2];
;     ...
;   const int relq = krel0 - (wid * 32 + r32) + 4 * hi, relwmin = krel0 - (wid * 32 + 31), relwmax = krel0 + 63 - wid * 32;
;     ...
;   f32x16 pA0, pA1, pB0, pB1; float mnA, mnB, alA, alB; bf16x8 pa0, pa1, pa2, pa3;
;   constexpr int SE = 0, SO = 1;
;   SLOAD(SE, 0); SLOAD(SO, 64); asm volatile("s_waitcnt vmcnt(4)" ::: "memory"); SWRITE(0, SE); __syncthreads();
;   qkt<ND0, DOFF>(pA0, pA1, K_lds, qr, r32, hi); PSM(pA0, pA1, mnA, alA, 0);
	v_pk_mul_f32 v[26:27], v[36:37], v[26:27]
	v_pk_mul_f32 v[36:37], v[72:73], v[50:51] op_sel_hi:[0,1]
	v_ashrrev_i32_e32 v50, 4, v188
	v_pk_mul_f32 v[8:9], v[72:73], v[8:9] op_sel_hi:[0,1]
	v_cvt_pk_bf16_f32 v142, v6, v7
	v_and_b32_e32 v6, 0xfffff0, v50
	v_lshlrev_b32_e32 v7, 1, v50
	v_pk_mul_f32 v[8:9], v[22:23], v[8:9]
	v_pk_mul_f32 v[10:11], v[72:73], v[10:11] op_sel_hi:[0,1]
	v_lshlrev_b32_e32 v5, 3, v188
	v_and_or_b32 v6, v7, 8, v6
	v_pk_mul_f32 v[10:11], v[34:35], v[10:11]
	v_cvt_pk_bf16_f32 v144, v8, v9
	v_and_b32_e32 v51, 0x78, v5
	v_lshrrev_b32_e32 v7, 1, v50
	v_lshrrev_b32_e32 v6, 1, v6
	v_bfe_u32 v5, v5, 5, 2
	v_and_b32_e32 v8, 3, v50
	v_cvt_pk_bf16_f32 v138, v10, v11
	v_or_b32_e32 v6, v6, v5
	v_and_or_b32 v7, v7, 4, v8
	v_lshlrev_b32_e32 v10, 1, v51
	v_lshlrev_b32_e32 v6, 9, v6
	v_lshlrev_b32_e32 v7, 6, v7
	v_and_b32_e32 v8, 48, v10
	v_add_u32_e32 v11, 32, v50
	v_or3_b32 v206, v6, v7, v8
	v_and_b32_e32 v6, 0xfffff0, v11
	v_lshlrev_b32_e32 v9, 1, v11
	v_and_or_b32 v6, v9, 8, v6
	v_pk_mul_f32 v[18:19], v[72:73], v[18:19] op_sel_hi:[0,1]
	v_lshrrev_b32_e32 v6, 1, v6
	s_waitcnt vmcnt(0)
	v_pk_mul_f32 v[18:19], v[54:55], v[18:19]
	v_or_b32_e32 v5, v6, v5
	v_lshlrev_b32_e32 v54, 2, v2
	v_or_b32_e32 v55, 31, v3
	v_mad_i64_i32 v[2:3], s[6:7], v50, s64, 0
	v_lshlrev_b32_e32 v5, 9, v5
	v_or_b32_e32 v2, v2, v51
	v_or3_b32 v207, v5, v7, v8
	v_lshlrev_b64 v[6:7], 1, v[2:3]
	v_pk_mul_f32 v[16:17], v[72:73], v[16:17] op_sel_hi:[0,1]
	v_lshl_add_u64 v[2:3], s[0:1], 0, v[6:7]
	v_mad_i64_i32 v[8:9], s[6:7], v11, s64, 0
	v_pk_mul_f32 v[16:17], v[38:39], v[16:17]
	v_add_u32_e32 v184, v4, v54
	global_load_dwordx4 v[2:5], v[2:3], off
	v_or_b32_e32 v8, v8, v51
	v_pk_mul_f32 v[12:13], v[72:73], v[12:13] op_sel_hi:[0,1]
	v_pk_mul_f32 v[14:15], v[72:73], v[14:15] op_sel_hi:[0,1]
	v_cvt_pk_bf16_f32 v136, v16, v17
	v_lshlrev_b64 v[16:17], 1, v[8:9]
	v_pk_mul_f32 v[12:13], v[30:31], v[12:13]
	v_pk_mul_f32 v[14:15], v[42:43], v[14:15]
	v_lshl_add_u64 v[8:9], s[0:1], 0, v[16:17]
	v_lshl_add_u64 v[6:7], s[58:59], 0, v[6:7]
	v_lshl_add_u64 v[16:17], s[58:59], 0, v[16:17]
	v_cvt_pk_bf16_f32 v140, v12, v13
	v_cvt_pk_bf16_f32 v134, v14, v15
	v_cvt_pk_bf16_f32 v130, v18, v19
	global_load_dwordx4 v[12:15], v[8:9], off
	v_pk_mul_f32 v[20:21], v[72:73], v[20:21] op_sel_hi:[0,1]
	global_load_dwordx4 v[16:19], v[16:17], off
	v_pk_mul_f32 v[20:21], v[46:47], v[20:21]
	global_load_dwordx4 v[6:9], v[6:7], off
	v_cvt_pk_bf16_f32 v132, v20, v21
	v_add_u32_e32 v20, 64, v50
	v_mad_i64_i32 v[20:21], s[6:7], v20, s64, 0
	v_pk_mul_f32 v[22:23], v[72:73], v[70:71] op_sel_hi:[0,1]
	v_or_b32_e32 v20, v20, v51
	v_pk_mul_f32 v[22:23], v[28:29], v[22:23]
	v_pk_mul_f32 v[34:35], v[72:73], v[58:59] op_sel_hi:[0,1]
	v_lshlrev_b64 v[20:21], 1, v[20:21]
	v_pk_mul_f32 v[30:31], v[72:73], v[62:63] op_sel_hi:[0,1]
	v_pk_mul_f32 v[34:35], v[56:57], v[34:35]
	v_pk_mul_f32 v[36:37], v[48:49], v[36:37]
	v_cvt_pk_bf16_f32 v143, v22, v23
	v_lshl_add_u64 v[22:23], s[0:1], 0, v[20:21]
	v_lshl_add_u64 v[20:21], s[58:59], 0, v[20:21]
	v_pk_mul_f32 v[30:31], v[44:45], v[30:31]
	v_cvt_pk_bf16_f32 v131, v34, v35
	v_cvt_pk_bf16_f32 v133, v36, v37
	global_load_dwordx4 v[34:37], v[22:23], off
	global_load_dwordx4 v[42:45], v[20:21], off
	v_add_u32_e32 v22, 0x60, v50
	v_mad_i64_i32 v[22:23], s[6:7], v22, s64, 0
	v_or_b32_e32 v22, v22, v51
	v_pk_mul_f32 v[28:29], v[72:73], v[64:65] op_sel_hi:[0,1]
	v_lshlrev_b64 v[22:23], 1, v[22:23]
	v_pk_mul_f32 v[28:29], v[32:33], v[28:29]
	v_pk_mul_f32 v[32:33], v[72:73], v[60:61] op_sel_hi:[0,1]
	v_cvt_pk_bf16_f32 v145, v24, v25
	v_lshl_add_u64 v[24:25], s[0:1], 0, v[22:23]
	v_lshl_add_u64 v[20:21], s[58:59], 0, v[22:23]
	v_pk_mul_f32 v[32:33], v[40:41], v[32:33]
	global_load_dwordx4 v[38:41], v[24:25], off
	global_load_dwordx4 v[46:49], v[20:21], off
	v_add_u32_e32 v56, 0, v206
	s_waitcnt vmcnt(4)
	v_add_u32_e32 v57, 0, v207
	v_lshlrev_b32_e32 v66, 8, v52
	v_cvt_pk_bf16_f32 v139, v26, v27
	v_cvt_pk_bf16_f32 v141, v28, v29
	v_cvt_pk_bf16_f32 v135, v30, v31
	v_cvt_pk_bf16_f32 v137, v32, v33
	v_or_b32_e32 v58, 32, v0
	v_sub_u32_e32 v204, s77, v55
	v_cmp_gt_i32_e64 s[6:7], s95, v205
	v_cmp_lt_i32_e32 vcc, s15, v205
	s_waitcnt vmcnt(7)
	ds_write_b128 v56, v[2:5]
	v_lshlrev_b32_e32 v2, 8, v50
	v_and_b32_e32 v3, 0xf0, v188
	v_bitop3_b32 v211, v10, v2, v3 bitop3:0xde
	v_add_u32_e32 v2, 0, v211
	s_waitcnt vmcnt(6)
	ds_write_b128 v57, v[12:15]
	s_waitcnt vmcnt(4)
	ds_write_b128 v2, v[6:9] offset:49152
	v_lshlrev_b32_e32 v2, 8, v11
	v_bitop3_b32 v212, v10, v2, v3 bitop3:0xde
	v_add_u32_e32 v2, 0, v212
	ds_write_b128 v2, v[16:19] offset:49152
	v_lshlrev_b32_e32 v2, 4, v188
	v_and_b32_e32 v67, 0xf0, v2
	v_bitop3_b32 v213, v0, v66, v67 bitop3:0xde
	v_add_u32_e32 v6, 0, v213
	s_waitcnt lgkmcnt(0)
	s_barrier
	ds_read_b128 v[2:5], v6 offset:49152
	ds_read_b128 v[6:9], v6 offset:57344
	s_waitcnt lgkmcnt(1)
	v_mfma_f32_32x32x16_bf16 v[18:33], v[2:5], v[142:145], 0
	v_bitop3_b32 v214, v58, v66, v67 bitop3:0xde
	v_add_u32_e32 v62, 0, v214
	ds_read_b128 v[58:61], v62 offset:49152
	ds_read_b128 v[62:65], v62 offset:57344
	s_waitcnt lgkmcnt(2)
	v_mfma_f32_32x32x16_bf16 v[2:17], v[6:9], v[142:145], 0
	s_waitcnt lgkmcnt(1)
	v_mfma_f32_32x32x16_bf16 v[18:33], v[58:61], v[138:141], v[18:33]
	v_or_b32_e32 v58, 64, v0
	v_bitop3_b32 v215, v58, v66, v67 bitop3:0xde
	v_or_b32_e32 v0, 0x60, v0
	v_bitop3_b32 v216, v0, v66, v67 bitop3:0xde
	v_add_u32_e32 v0, 0, v216
	s_waitcnt lgkmcnt(0)
	v_mfma_f32_32x32x16_bf16 v[2:17], v[62:65], v[138:141], v[2:17]
	v_add_u32_e32 v62, 0, v215
	ds_read_b128 v[58:61], v62 offset:49152
	ds_read_b128 v[62:65], v62 offset:57344
	s_waitcnt lgkmcnt(1)
	v_mfma_f32_32x32x16_bf16 v[18:33], v[58:61], v[134:137], v[18:33]
	s_waitcnt lgkmcnt(0)
	v_mfma_f32_32x32x16_bf16 v[2:17], v[62:65], v[134:137], v[2:17]
	ds_read_b128 v[58:61], v0 offset:49152
	ds_read_b128 v[62:65], v0 offset:57344
	v_mov_b32_e32 v0, s76
	s_waitcnt lgkmcnt(1)
	v_mfma_f32_32x32x16_bf16 v[18:33], v[58:61], v[130:133], v[18:33]
	s_waitcnt lgkmcnt(0)
	v_mfma_f32_32x32x16_bf16 v[2:17], v[62:65], v[130:133], v[2:17]
	s_and_saveexec_b64 s[64:65], vcc
	s_cbranch_execz .LBB0_129
; template <int MODE>
; __device__ __forceinline__ void partialSM(f32x16& p0, f32x16& p1, float& m_reg, float& mn, float& alpha, int relh, int relw_min, int relw_max, const float* lut) {
;     ...
;     if (nearT) {
; #pragma unroll
;       for (int r = 0; r < 16; ++r) { const int i0 = relh + (r & 3) + 8 * (r >> 2);
;         const int a0 = min(max(i0, -129), 129) + 129, a1 = min(max(i0 + 32, -129), 129) + 129;
;         p0[r] = fmaf(p0[r], C, lut[a0]); p1[r] = fmaf(p1[r], C, lut[a1]); }
	v_cmp_gt_i32_e32 vcc, s91, v204
	s_mov_b64 s[68:69], -1
	s_and_saveexec_b64 s[66:67], vcc
	s_cbranch_execz .LBB0_128
	v_add_u32_e32 v59, 1, v184
	v_add_u32_e32 v61, 2, v184
	v_add_u32_e32 v63, 3, v184
	v_med3_i32 v0, v184, s39, v198
	v_med3_i32 v58, v184, s33, v199
	v_med3_i32 v60, v59, s39, v198
	v_med3_i32 v59, v59, s33, v199
	v_med3_i32 v62, v61, s39, v198
	v_med3_i32 v61, v61, s33, v199
	v_med3_i32 v64, v63, s39, v198
	v_lshl_add_u32 v0, v0, 2, s76
	v_lshl_add_u32 v58, v58, 2, s76
	v_lshl_add_u32 v60, v60, 2, s76
	v_lshl_add_u32 v59, v59, 2, s76
	v_lshl_add_u32 v62, v62, 2, s76
	v_lshl_add_u32 v61, v61, 2, s76
	v_med3_i32 v63, v63, s33, v199
	v_lshl_add_u32 v64, v64, 2, s76
	v_lshl_add_u32 v63, v63, 2, s76
	ds_read_b32 v0, v0 offset:516
	ds_read_b32 v58, v58 offset:644
	ds_read_b32 v74, v60 offset:516
	ds_read_b32 v59, v59 offset:644
	ds_read_b32 v75, v62 offset:516
	ds_read_b32 v60, v61 offset:644
	ds_read_b32 v76, v64 offset:516
	ds_read_b32 v61, v63 offset:644
	v_add_u32_e32 v62, 8, v184
	v_add_u32_e32 v64, 9, v184
	v_add_u32_e32 v66, 10, v184
	v_add_u32_e32 v68, 11, v184
	v_med3_i32 v63, v62, s39, v198
	v_med3_i32 v62, v62, s33, v199
	v_med3_i32 v65, v64, s39, v198
	v_med3_i32 v64, v64, s33, v199
	v_med3_i32 v67, v66, s39, v198
	v_med3_i32 v66, v66, s33, v199
	v_med3_i32 v69, v68, s39, v198
	v_med3_i32 v68, v68, s33, v199
	v_lshl_add_u32 v63, v63, 2, s76
	v_lshl_add_u32 v62, v62, 2, s76
	v_lshl_add_u32 v65, v65, 2, s76
	v_lshl_add_u32 v64, v64, 2, s76
	v_lshl_add_u32 v66, v66, 2, s76
	v_lshl_add_u32 v68, v68, 2, s76
	v_lshl_add_u32 v67, v67, 2, s76
	v_lshl_add_u32 v69, v69, 2, s76
	ds_read_b32 v77, v63 offset:516
	ds_read_b32 v62, v62 offset:644
	ds_read_b32 v78, v65 offset:516
	ds_read_b32 v63, v64 offset:644
	ds_read_b32 v79, v67 offset:516
	ds_read_b32 v64, v66 offset:644
	ds_read_b32 v80, v69 offset:516
	ds_read_b32 v65, v68 offset:644
	v_add_u32_e32 v66, 16, v184
	v_add_u32_e32 v68, 17, v184
	v_add_u32_e32 v70, 18, v184
	v_add_u32_e32 v72, 19, v184
	v_med3_i32 v67, v66, s39, v198
	v_med3_i32 v66, v66, s33, v199
	v_med3_i32 v69, v68, s39, v198
	v_med3_i32 v68, v68, s33, v199
	v_med3_i32 v71, v70, s39, v198
	v_med3_i32 v70, v70, s33, v199
	v_med3_i32 v73, v72, s39, v198
	v_med3_i32 v72, v72, s33, v199
	v_lshl_add_u32 v67, v67, 2, s76
	v_lshl_add_u32 v66, v66, 2, s76
	v_lshl_add_u32 v69, v69, 2, s76
	v_lshl_add_u32 v68, v68, 2, s76
	v_lshl_add_u32 v70, v70, 2, s76
	v_lshl_add_u32 v72, v72, 2, s76
	v_lshl_add_u32 v71, v71, 2, s76
	v_lshl_add_u32 v73, v73, 2, s76
	ds_read_b32 v81, v67 offset:516
	ds_read_b32 v66, v66 offset:644
	ds_read_b32 v90, v69 offset:516
	ds_read_b32 v67, v68 offset:644
	ds_read_b32 v91, v71 offset:516
	ds_read_b32 v68, v70 offset:644
	ds_read_b32 v92, v73 offset:516
	ds_read_b32 v69, v72 offset:644
	v_add_u32_e32 v70, 24, v184
	v_add_u32_e32 v72, 25, v184
	v_add_u32_e32 v82, 26, v184
	v_med3_i32 v71, v70, s39, v198
	v_med3_i32 v70, v70, s33, v199
	v_med3_i32 v73, v72, s39, v198
	v_med3_i32 v72, v72, s33, v199
	v_med3_i32 v83, v82, s39, v198
	v_med3_i32 v82, v82, s33, v199
	v_add_u32_e32 v84, 27, v184
	s_waitcnt lgkmcnt(14)
	v_fmac_f32_e32 v0, 0x3e38aa3b, v18
	v_fmac_f32_e32 v74, 0x3e38aa3b, v19
	v_lshl_add_u32 v71, v71, 2, s76
	v_lshl_add_u32 v70, v70, 2, s76
	v_lshl_add_u32 v73, v73, 2, s76
	v_lshl_add_u32 v72, v72, 2, s76
	v_lshl_add_u32 v82, v82, 2, s76
	v_med3_i32 v85, v84, s39, v198
	v_med3_i32 v84, v84, s33, v199
	v_fmac_f32_e32 v75, 0x3e38aa3b, v20
	v_fmac_f32_e32 v76, 0x3e38aa3b, v21
	v_lshl_add_u32 v83, v83, 2, s76
	v_lshl_add_u32 v85, v85, 2, s76
	v_lshl_add_u32 v84, v84, 2, s76
	ds_read_b32 v93, v71 offset:516
	ds_read_b32 v70, v70 offset:644
	ds_read_b32 v94, v73 offset:516
	ds_read_b32 v71, v72 offset:644
	ds_read_b32 v95, v83 offset:516
	ds_read_b32 v72, v82 offset:644
	ds_read_b32 v96, v85 offset:516
	ds_read_b32 v73, v84 offset:644
	v_max_f32_e32 v82, v0, v74
	v_fmac_f32_e32 v77, 0x3e38aa3b, v22
	s_waitcnt lgkmcnt(14)
; template <int MODE>
; __device__ __forceinline__ void partialSM(f32x16& p0, f32x16& p1, float& m_reg, float& mn, float& alpha, int relh, int relw_min, int relw_max, const float* lut) {
;     ...
;     if (nearT) {
; #pragma unroll
;       for (int r = 0; r < 16; ++r) { const int i0 = relh + (r & 3) + 8 * (r >> 2);
;         const int a0 = min(max(i0, -129), 129) + 129, a1 = min(max(i0 + 32, -129), 129) + 129;
;         p0[r] = fmaf(p0[r], C, lut[a0]); p1[r] = fmaf(p1[r], C, lut[a1]); }
;     } else {
; #pragma unroll
;       for (int r = 0; r < 16; ++r) { p0[r] = fmaf(p0[r], C, cfar); p1[r] = fmaf(p1[r], C, cfar); }
;     }
;     float pmax = p0[0];
; #pragma unroll
;     for (int r = 1; r < 16; ++r) pmax = fmaxf(pmax, p0[r]);
; #pragma unroll
;     for (int r = 0; r < 16; ++r) pmax = fmaxf(pmax, p1[r]);
;     { auto rr = __builtin_amdgcn_permlane32_swap(__float_as_uint(pmax), __float_as_uint(pmax), false, false);
;       pmax = fmaxf(__uint_as_float(rr[0]), __uint_as_float(rr[1])); }
;     if (__builtin_expect(__all(pmax - m_reg <= THR2), 1)) { mn = m_reg; alpha = 1.f; }
;     else { mn = fmaxf(m_reg, pmax); alpha = __builtin_amdgcn_exp2f(m_reg - mn); m_reg = mn; }
; #pragma unroll
;     for (int r = 0; r < 16; ++r) p0[r] = __builtin_amdgcn_exp2f(p0[r] - mn);
; #pragma unroll
;     for (int r = 0; r < 16; ++r) p1[r] = p1[r] - mn;
	v_fmac_f32_e32 v78, 0x3e38aa3b, v23
	v_max3_f32 v82, v82, v75, v76
	v_fmac_f32_e32 v79, 0x3e38aa3b, v24
	v_fmac_f32_e32 v80, 0x3e38aa3b, v25
	v_max3_f32 v82, v82, v77, v78
	v_fmac_f32_e32 v81, 0x3e38aa3b, v26
	s_waitcnt lgkmcnt(13)
	v_fmac_f32_e32 v90, 0x3e38aa3b, v27
	v_max3_f32 v82, v82, v79, v80
	s_waitcnt lgkmcnt(11)
	v_fmac_f32_e32 v91, 0x3e38aa3b, v28
	s_waitcnt lgkmcnt(9)
	v_fmac_f32_e32 v92, 0x3e38aa3b, v29
	v_max3_f32 v82, v82, v81, v90
	s_waitcnt lgkmcnt(7)
	v_fmac_f32_e32 v93, 0x3e38aa3b, v30
	s_waitcnt lgkmcnt(5)
	v_fmac_f32_e32 v94, 0x3e38aa3b, v31
	v_max3_f32 v82, v82, v91, v92
	s_waitcnt lgkmcnt(3)
	v_fmac_f32_e32 v95, 0x3e38aa3b, v32
	s_waitcnt lgkmcnt(1)
	v_fmac_f32_e32 v96, 0x3e38aa3b, v33
	v_max3_f32 v82, v82, v93, v94
	v_max3_f32 v82, v82, v95, v96
	v_pk_fma_f32 v[58:59], v[2:3], s[48:49], v[58:59] op_sel_hi:[1,0,1]
	v_pk_fma_f32 v[60:61], v[4:5], s[48:49], v[60:61] op_sel_hi:[1,0,1]
	v_max3_f32 v82, v82, v58, v59
	v_max3_f32 v82, v82, v60, v61
	v_pk_fma_f32 v[62:63], v[6:7], s[48:49], v[62:63] op_sel_hi:[1,0,1]
	v_pk_fma_f32 v[64:65], v[8:9], s[48:49], v[64:65] op_sel_hi:[1,0,1]
	v_max3_f32 v82, v82, v62, v63
	v_max3_f32 v84, v82, v64, v65
	v_pk_fma_f32 v[82:83], v[10:11], s[48:49], v[66:67] op_sel_hi:[1,0,1]
	v_pk_fma_f32 v[86:87], v[14:15], s[48:49], v[70:71] op_sel_hi:[1,0,1]
	v_max3_f32 v66, v84, v82, v83
	v_pk_fma_f32 v[84:85], v[12:13], s[48:49], v[68:69] op_sel_hi:[1,0,1]
	s_waitcnt lgkmcnt(0)
	v_pk_fma_f32 v[88:89], v[16:17], s[48:49], v[72:73] op_sel_hi:[1,0,1]
	v_max3_f32 v66, v66, v84, v85
	v_max3_f32 v66, v66, v86, v87
	v_max3_f32 v66, v66, v88, v89
	v_mov_b32_e32 v67, v66
	s_nop 1
	v_permlane32_swap_b32_e32 v66, v67
	v_max_f32_e32 v67, v67, v67
	v_max_f32_e32 v66, v66, v66
	v_max_f32_e32 v66, v66, v67
	v_add_f32_e32 v67, 0x7149f2ca, v66
	v_cmp_ge_f32_e32 vcc, s94, v67
	v_max_f32_e32 v66, 0xf149f2ca, v66
	v_sub_f32_e32 v67, 0xf149f2ca, v66
	s_cmp_eq_u64 vcc, exec
	v_exp_f32_e32 v67, v67
	s_cselect_b64 vcc, -1, 0
	v_cndmask_b32_e32 v219, v66, v197, vcc
	v_mov_b32_e32 v100, s76
	ds_read_b32 v101, v100
	ds_read_b32 v100, v100 offset:1032
	v_readlane_b32 s19, v255, 21
	s_waitcnt lgkmcnt(0)
	v_max_f32_e32 v101, v101, v100
	v_add_f32_e32 v219, s19, v101
	v_sub_f32_e32 v0, v0, v219
	v_exp_f32_e32 v66, v0
	v_sub_f32_e32 v0, v74, v219
	v_cndmask_b32_e64 v217, v67, 1.0, vcc
	v_exp_f32_e32 v67, v0
	v_sub_f32_e32 v0, v75, v219
	v_exp_f32_e32 v68, v0
	v_sub_f32_e32 v0, v76, v219
	v_exp_f32_e32 v69, v0
	v_sub_f32_e32 v0, v77, v219
	v_exp_f32_e32 v70, v0
	v_sub_f32_e32 v0, v78, v219
	v_exp_f32_e32 v71, v0
	v_sub_f32_e32 v0, v79, v219
	v_exp_f32_e32 v72, v0
	v_sub_f32_e32 v0, v80, v219
	v_exp_f32_e32 v73, v0
	v_sub_f32_e32 v0, v81, v219
	v_exp_f32_e32 v74, v0
	v_sub_f32_e32 v0, v90, v219
	v_exp_f32_e32 v75, v0
	v_sub_f32_e32 v0, v91, v219
	v_exp_f32_e32 v76, v0
	v_sub_f32_e32 v0, v92, v219
	v_exp_f32_e32 v77, v0
	v_sub_f32_e32 v0, v93, v219
	v_exp_f32_e32 v78, v0
	v_sub_f32_e32 v0, v94, v219
	v_exp_f32_e32 v79, v0
	v_sub_f32_e32 v0, v95, v219
	v_exp_f32_e32 v80, v0
	v_sub_f32_e32 v0, v96, v219
	v_exp_f32_e32 v81, v0
	v_sub_f32_e32 v97, v89, v219
	v_sub_f32_e32 v96, v88, v219
	v_sub_f32_e32 v95, v87, v219
	v_sub_f32_e32 v94, v86, v219
	v_sub_f32_e32 v93, v85, v219
	v_sub_f32_e32 v92, v84, v219
	v_sub_f32_e32 v91, v83, v219
	v_sub_f32_e32 v90, v82, v219
	v_sub_f32_e32 v89, v65, v219
	v_sub_f32_e32 v88, v64, v219
	v_sub_f32_e32 v87, v63, v219
	v_sub_f32_e32 v86, v62, v219
	v_sub_f32_e32 v85, v61, v219
	v_sub_f32_e32 v84, v60, v219
	v_sub_f32_e32 v83, v59, v219
	v_sub_f32_e32 v82, v58, v219
	s_xor_b64 s[68:69], exec, -1

; template <int MODE>
; __device__ __forceinline__ void partialSM(f32x16& p0, f32x16& p1, float& m_reg, float& mn, float& alpha, int relh, int relw_min, int relw_max, const float* lut) {
;     ...
;       if (relw_max <= -128) { nearT = false; cfar = lut[0]; }
;       else if (relw_min >= 128) { nearT = false; cfar = lut[258]; }
;       if (!nearT) {
;         float pmax = p0[0];
; #pragma unroll
;         for (int r = 1; r < 16; ++r) pmax = fmaxf(pmax, p0[r]);
; #pragma unroll
;         for (int r = 0; r < 16; ++r) pmax = fmaxf(pmax, p1[r]);
;         { auto rr = __builtin_amdgcn_permlane32_swap(__float_as_uint(pmax), __float_as_uint(pmax), false, false);
;           pmax = fmaxf(__uint_as_float(rr[0]), __uint_as_float(rr[1])); }
;         const float tmax = fmaf(pmax, C, cfar);
;         if (__builtin_expect(__all(tmax - m_reg <= THR2), 1)) { mn = m_reg; alpha = 1.f; }
;         else { mn = fmaxf(m_reg, tmax); alpha = __builtin_amdgcn_exp2f(m_reg - mn); m_reg = mn; }
;         const float off = cfar - mn;
; #pragma unroll
;         for (int r = 0; r < 16; ++r) p0[r] = fmaf(p0[r], C, off);
; #pragma unroll
;         for (int r = 0; r < 16; ++r) p1[r] = fmaf(p1[r], C, off);
; #pragma unroll
;         for (int r = 0; r < 16; ++r) p0[r] = __builtin_amdgcn_exp2f(p0[r]);
.LBB0_129:
	s_or_b64 exec, exec, s[64:65]
	s_and_saveexec_b64 s[64:65], s[6:7]
	s_cbranch_execz .LBB0_131
	s_nop 4
	v_max_f32_e32 v58, v19, v19
	v_max_f32_e32 v59, v18, v18
	v_max_f32_e32 v58, v59, v58
	v_max3_f32 v58, v58, v20, v21
	v_max3_f32 v58, v58, v22, v23
	v_max3_f32 v58, v58, v24, v25
	v_max3_f32 v58, v58, v26, v27
	v_max3_f32 v58, v58, v28, v29
	v_max3_f32 v58, v58, v30, v31
	v_max3_f32 v58, v58, v32, v33
	v_max3_f32 v58, v58, v2, v3
	v_max3_f32 v58, v58, v4, v5
	v_max3_f32 v58, v58, v6, v7
	v_max3_f32 v58, v58, v8, v9
	v_max3_f32 v58, v58, v10, v11
	v_max3_f32 v58, v58, v12, v13
	v_max3_f32 v58, v58, v14, v15
	ds_read_b32 v0, v0
	v_max3_f32 v58, v58, v16, v17
	v_mov_b32_e32 v59, v58
	s_nop 1
	v_permlane32_swap_b32_e32 v58, v59
	v_max_f32_e32 v59, v59, v59
	v_max_f32_e32 v58, v58, v58
	v_max_f32_e32 v58, v58, v59
	s_waitcnt lgkmcnt(0)
	v_fmamk_f32 v58, v58, 0x3e38aa3b, v0
	v_add_f32_e32 v59, 0x7149f2ca, v58
	v_cmp_ge_f32_e32 vcc, s94, v59
	s_cmp_eq_u64 vcc, exec
	s_cselect_b64 vcc, -1, 0
	v_max_f32_e32 v58, 0xf149f2ca, v58
	v_cndmask_b32_e32 v219, v58, v197, vcc
	v_mov_b32_e32 v100, s76
	ds_read_b32 v101, v100
	ds_read_b32 v100, v100 offset:1032
	v_readlane_b32 s19, v255, 21
	s_waitcnt lgkmcnt(0)
	v_max_f32_e32 v101, v101, v100
	v_add_f32_e32 v219, s19, v101
	v_sub_f32_e32 v0, v0, v219
	v_sub_f32_e32 v59, 0xf149f2ca, v58
	v_mov_b32_e32 v58, v0
	v_exp_f32_e32 v59, v59
	v_fmamk_f32 v18, v18, 0x3e38aa3b, v0
	v_fmamk_f32 v19, v19, 0x3e38aa3b, v0
	v_fmamk_f32 v20, v20, 0x3e38aa3b, v0
	v_fmamk_f32 v21, v21, 0x3e38aa3b, v0
	v_fmamk_f32 v22, v22, 0x3e38aa3b, v0
	v_fmamk_f32 v23, v23, 0x3e38aa3b, v0
	v_fmamk_f32 v24, v24, 0x3e38aa3b, v0
	v_fmamk_f32 v25, v25, 0x3e38aa3b, v0
	v_fmamk_f32 v26, v26, 0x3e38aa3b, v0
	v_fmamk_f32 v27, v27, 0x3e38aa3b, v0
	v_fmamk_f32 v28, v28, 0x3e38aa3b, v0
	v_fmamk_f32 v29, v29, 0x3e38aa3b, v0
	v_fmamk_f32 v30, v30, 0x3e38aa3b, v0
	v_fmamk_f32 v31, v31, 0x3e38aa3b, v0
	v_fmamk_f32 v32, v32, 0x3e38aa3b, v0
	v_fmac_f32_e32 v58, 0x3e38aa3b, v33
	v_exp_f32_e32 v66, v18
	v_exp_f32_e32 v67, v19
	v_exp_f32_e32 v68, v20
	v_exp_f32_e32 v69, v21
	v_exp_f32_e32 v70, v22
	v_exp_f32_e32 v71, v23
	v_exp_f32_e32 v72, v24
	v_exp_f32_e32 v73, v25
	v_exp_f32_e32 v74, v26
	v_exp_f32_e32 v75, v27
	v_exp_f32_e32 v76, v28
	v_exp_f32_e32 v77, v29
	v_exp_f32_e32 v78, v30
	v_exp_f32_e32 v79, v31
	v_exp_f32_e32 v80, v32
	v_exp_f32_e32 v81, v58
	v_cndmask_b32_e64 v217, v59, 1.0, vcc
	v_pk_fma_f32 v[96:97], v[16:17], s[48:49], v[0:1] op_sel_hi:[1,0,0]
	v_pk_fma_f32 v[94:95], v[14:15], s[48:49], v[0:1] op_sel_hi:[1,0,0]
	v_pk_fma_f32 v[92:93], v[12:13], s[48:49], v[0:1] op_sel_hi:[1,0,0]
	v_pk_fma_f32 v[90:91], v[10:11], s[48:49], v[0:1] op_sel_hi:[1,0,0]
	v_pk_fma_f32 v[88:89], v[8:9], s[48:49], v[0:1] op_sel_hi:[1,0,0]
	v_pk_fma_f32 v[86:87], v[6:7], s[48:49], v[0:1] op_sel_hi:[1,0,0]
	v_pk_fma_f32 v[84:85], v[4:5], s[48:49], v[0:1] op_sel_hi:[1,0,0]
	v_pk_fma_f32 v[82:83], v[2:3], s[48:49], v[0:1] op_sel_hi:[1,0,0]

; template <int MODE>
; __device__ __forceinline__ void partialSM(f32x16& p0, f32x16& p1, float& m_reg, float& mn, float& alpha, int relh, int relw_min, int relw_max, const float* lut) {
;     ...
;       if (relw_max <= -128) { nearT = false; cfar = lut[0]; }
;       else if (relw_min >= 128) { nearT = false; cfar = lut[258]; }
;       if (!nearT) {
;         float pmax = p0[0];
; #pragma unroll
;         for (int r = 1; r < 16; ++r) pmax = fmaxf(pmax, p0[r]);
; #pragma unroll
;         for (int r = 0; r < 16; ++r) pmax = fmaxf(pmax, p1[r]);
;         { auto rr = __builtin_amdgcn_permlane32_swap(__float_as_uint(pmax), __float_as_uint(pmax), false, false);
;           pmax = fmaxf(__uint_as_float(rr[0]), __uint_as_float(rr[1])); }
;         const float tmax = fmaf(pmax, C, cfar);
;         if (__builtin_expect(__all(tmax - m_reg <= THR2), 1)) { mn = m_reg; alpha = 1.f; }
;         else { mn = fmaxf(m_reg, tmax); alpha = __builtin_amdgcn_exp2f(m_reg - mn); m_reg = mn; }
;         const float off = cfar - mn;
; #pragma unroll
;         for (int r = 0; r < 16; ++r) p0[r] = fmaf(p0[r], C, off);
; #pragma unroll
;         for (int r = 0; r < 16; ++r) p1[r] = fmaf(p1[r], C, off);
; #pragma unroll
;         for (int r = 0; r < 16; ++r) p0[r] = __builtin_amdgcn_exp2f(p0[r]);
.LBB0_136:
	s_or_b64 exec, exec, s[66:67]
	s_and_saveexec_b64 s[66:67], s[64:65]
	s_cbranch_execz .LBB0_138
	ds_read_b32 v66, v229
	s_waitcnt lgkmcnt(0)
	v_mov_b32_e32 v228, v219
	v_sub_f32_e32 v66, v66, v228
	v_fmamk_f32 v67, v114, 0x3e38aa3b, v66
	v_mov_b32_e32 v114, v66
	v_mov_b32_e32 v226, 1.0
	v_fmamk_f32 v68, v115, 0x3e38aa3b, v66
	v_fmamk_f32 v69, v116, 0x3e38aa3b, v66
	v_fmamk_f32 v70, v117, 0x3e38aa3b, v66
	v_fmamk_f32 v71, v118, 0x3e38aa3b, v66
	v_fmamk_f32 v72, v119, 0x3e38aa3b, v66
	v_fmamk_f32 v73, v120, 0x3e38aa3b, v66
	v_fmamk_f32 v74, v121, 0x3e38aa3b, v66
	v_fmamk_f32 v75, v122, 0x3e38aa3b, v66
	v_fmamk_f32 v76, v123, 0x3e38aa3b, v66
	v_fmamk_f32 v77, v124, 0x3e38aa3b, v66
	v_fmamk_f32 v78, v125, 0x3e38aa3b, v66
	v_fmamk_f32 v79, v126, 0x3e38aa3b, v66
	v_fmamk_f32 v80, v127, 0x3e38aa3b, v66
	v_fmamk_f32 v81, v128, 0x3e38aa3b, v66
	v_fmac_f32_e32 v114, 0x3e38aa3b, v129
	v_fmamk_f32 v97, v113, 0x3e38aa3b, v66
	v_fmamk_f32 v96, v112, 0x3e38aa3b, v66
	v_fmamk_f32 v95, v111, 0x3e38aa3b, v66
	v_fmamk_f32 v94, v110, 0x3e38aa3b, v66
	v_fmamk_f32 v93, v109, 0x3e38aa3b, v66
	v_fmamk_f32 v92, v108, 0x3e38aa3b, v66
	v_fmamk_f32 v91, v107, 0x3e38aa3b, v66
	v_fmamk_f32 v90, v106, 0x3e38aa3b, v66
	v_fmamk_f32 v89, v105, 0x3e38aa3b, v66
	v_fmamk_f32 v88, v104, 0x3e38aa3b, v66
	v_fmamk_f32 v87, v103, 0x3e38aa3b, v66
	v_fmamk_f32 v86, v102, 0x3e38aa3b, v66
	v_fmamk_f32 v85, v101, 0x3e38aa3b, v66
	v_fmamk_f32 v84, v100, 0x3e38aa3b, v66
	v_fmamk_f32 v83, v99, 0x3e38aa3b, v66
	v_fmamk_f32 v82, v98, 0x3e38aa3b, v66
	v_exp_f32_e32 v66, v67
	v_exp_f32_e32 v67, v68
	v_exp_f32_e32 v68, v69
	v_exp_f32_e32 v69, v70
	v_exp_f32_e32 v70, v71
	v_exp_f32_e32 v71, v72
	v_exp_f32_e32 v72, v73
	v_exp_f32_e32 v73, v74
	v_exp_f32_e32 v74, v75
	v_exp_f32_e32 v75, v76
	v_exp_f32_e32 v76, v77
	v_exp_f32_e32 v77, v78
	v_exp_f32_e32 v78, v79
	v_exp_f32_e32 v79, v80
	v_exp_f32_e32 v80, v81
	v_exp_f32_e32 v81, v114

; template <int MODE>
; __device__ __forceinline__ void partialSM(f32x16& p0, f32x16& p1, float& m_reg, float& mn, float& alpha, int relh, int relw_min, int relw_max, const float* lut) {
;     ...
;       if (relw_max <= -128) { nearT = false; cfar = lut[0]; }
;       else if (relw_min >= 128) { nearT = false; cfar = lut[258]; }
;       if (!nearT) {
;         float pmax = p0[0];
; #pragma unroll
;         for (int r = 1; r < 16; ++r) pmax = fmaxf(pmax, p0[r]);
; #pragma unroll
;         for (int r = 0; r < 16; ++r) pmax = fmaxf(pmax, p1[r]);
;         { auto rr = __builtin_amdgcn_permlane32_swap(__float_as_uint(pmax), __float_as_uint(pmax), false, false);
;           pmax = fmaxf(__uint_as_float(rr[0]), __uint_as_float(rr[1])); }
;         const float tmax = fmaf(pmax, C, cfar);
;         if (__builtin_expect(__all(tmax - m_reg <= THR2), 1)) { mn = m_reg; alpha = 1.f; }
;         else { mn = fmaxf(m_reg, tmax); alpha = __builtin_amdgcn_exp2f(m_reg - mn); m_reg = mn; }
;         const float off = cfar - mn;
; #pragma unroll
;         for (int r = 0; r < 16; ++r) p0[r] = fmaf(p0[r], C, off);
; #pragma unroll
;         for (int r = 0; r < 16; ++r) p1[r] = fmaf(p1[r], C, off);
; #pragma unroll
;         for (int r = 0; r < 16; ++r) p0[r] = __builtin_amdgcn_exp2f(p0[r]);
.LBB0_148:
	s_or_b64 exec, exec, s[68:69]
	s_and_saveexec_b64 s[68:69], s[66:67]
	s_cbranch_execz .LBB0_150
	ds_read_b32 v66, v231
	s_waitcnt lgkmcnt(0)
	v_mov_b32_e32 v219, v228
	v_sub_f32_e32 v66, v66, v219
	v_fmamk_f32 v67, v114, 0x3e38aa3b, v66
	v_mov_b32_e32 v114, v66
	v_mov_b32_e32 v225, 1.0
	v_fmamk_f32 v68, v115, 0x3e38aa3b, v66
	v_fmamk_f32 v69, v116, 0x3e38aa3b, v66
	v_fmamk_f32 v70, v117, 0x3e38aa3b, v66
	v_fmamk_f32 v71, v118, 0x3e38aa3b, v66
	v_fmamk_f32 v72, v119, 0x3e38aa3b, v66
	v_fmamk_f32 v73, v120, 0x3e38aa3b, v66
	v_fmamk_f32 v74, v121, 0x3e38aa3b, v66
	v_fmamk_f32 v75, v122, 0x3e38aa3b, v66
	v_fmamk_f32 v76, v123, 0x3e38aa3b, v66
	v_fmamk_f32 v77, v124, 0x3e38aa3b, v66
	v_fmamk_f32 v78, v125, 0x3e38aa3b, v66
	v_fmamk_f32 v79, v126, 0x3e38aa3b, v66
	v_fmamk_f32 v80, v127, 0x3e38aa3b, v66
	v_fmamk_f32 v81, v128, 0x3e38aa3b, v66
	v_fmac_f32_e32 v114, 0x3e38aa3b, v129
	v_fmamk_f32 v97, v113, 0x3e38aa3b, v66
	v_fmamk_f32 v96, v112, 0x3e38aa3b, v66
	v_fmamk_f32 v95, v111, 0x3e38aa3b, v66
	v_fmamk_f32 v94, v110, 0x3e38aa3b, v66
	v_fmamk_f32 v93, v109, 0x3e38aa3b, v66
	v_fmamk_f32 v92, v108, 0x3e38aa3b, v66
	v_fmamk_f32 v91, v107, 0x3e38aa3b, v66
	v_fmamk_f32 v90, v106, 0x3e38aa3b, v66
	v_fmamk_f32 v89, v105, 0x3e38aa3b, v66
	v_fmamk_f32 v88, v104, 0x3e38aa3b, v66
	v_fmamk_f32 v87, v103, 0x3e38aa3b, v66
	v_fmamk_f32 v86, v102, 0x3e38aa3b, v66
	v_fmamk_f32 v85, v101, 0x3e38aa3b, v66
	v_fmamk_f32 v84, v100, 0x3e38aa3b, v66
	v_fmamk_f32 v83, v99, 0x3e38aa3b, v66
	v_fmamk_f32 v82, v98, 0x3e38aa3b, v66
	v_exp_f32_e32 v66, v67
	v_exp_f32_e32 v67, v68
	v_exp_f32_e32 v68, v69
	v_exp_f32_e32 v69, v70
	v_exp_f32_e32 v70, v71
	v_exp_f32_e32 v71, v72
	v_exp_f32_e32 v72, v73
	v_exp_f32_e32 v73, v74
	v_exp_f32_e32 v74, v75
	v_exp_f32_e32 v75, v76
	v_exp_f32_e32 v76, v77
	v_exp_f32_e32 v77, v78
	v_exp_f32_e32 v78, v79
	v_exp_f32_e32 v79, v80
	v_exp_f32_e32 v80, v81
	v_exp_f32_e32 v81, v114

; template <int MODE>
; __device__ __forceinline__ void attn_body(const bf16_t* __restrict__ Qb, const bf16_t* __restrict__ Kh, const bf16_t* __restrict__ Vh, int NT, int krel0,
;                                           char* lds, const float* __restrict__ lutg, const AttnEpi& E) {
;     ...
;   const bf16_t* Qw = Qb + (size_t)(wid * 32 + r32) * LDQK + hi * 8;
;   {
;     float qf[ND0][8]; float ss = 0.f;
; #pragma unroll
;     for (int d0 = 0; d0 < ND0; ++d0) { const bf16x8 raw = *reinterpret_cast<const bf16x8*>(Qw + d0 * 16);
; #pragma unroll
;       for (int j = 0; j < 8; ++j) { const float v = __uint_as_float(((unsigned)(unsigned short)raw[j]) << 16); qf[d0][j] = v; ss += v * v; } }
;     { auto rr = __builtin_amdgcn_permlane32_swap(__float_as_uint(ss), __float_as_uint(ss), false, false);
;       ss = __uint_as_float(rr[0]) + __uint_as_float(rr[1]); }
;     const float rs = rsqrtf(ss * (MODE < 2 ? (1.f / 128.f) : (1.f / 64.f)) + EPS);
; #pragma unroll
;     for (int d0 = 0; d0 < ND0; ++d0) { const f32x4 g0 = *(const f32x4*)(E.gq + d0 * 16 + hi * 8), g1 = *(const f32x4*)(E.gq + d0 * 16 + hi * 8 + 4);
; #pragma unroll
;       for (int j = 0; j < 4; ++j) { qf[d0][j] = qf[d0][j] * rs * g0[j]; qf[d0][4 + j] = qf[d0][4 + j] * rs * g1[j]; } }
.LBB0_170:
	s_or_b64 exec, exec, s[6:7]
	v_ashrrev_i32_e32 v2, 1, v188
	s_movk_i32 s6, 0xffe0
	v_bfe_u32 v3, v188, 5, 1
	v_bfi_b32 v4, s6, v2, v188
	v_mov_b64_e32 v[6:7], s[62:63]
	v_mad_i64_i32 v[6:7], s[6:7], v4, s83, v[6:7]
	v_lshlrev_b32_e32 v0, 4, v3
	v_lshl_add_u64 v[18:19], v[6:7], 0, v[0:1]
	global_load_dwordx4 v[6:9], v[18:19], off offset:128
	global_load_dwordx4 v[10:13], v[18:19], off offset:160
	global_load_dwordx4 v[14:17], v[18:19], off offset:192
	s_nop 0
	global_load_dwordx4 v[18:21], v[18:19], off offset:224
	v_and_b32_e32 v5, 32, v188
	global_load_dwordx4 v[22:25], v5, s[52:53] offset:16
	global_load_dwordx4 v[26:29], v5, s[52:53]
	global_load_dwordx4 v[30:33], v5, s[52:53] offset:80
	global_load_dwordx4 v[34:37], v5, s[52:53] offset:64
	global_load_dwordx4 v[38:41], v5, s[52:53] offset:144
	global_load_dwordx4 v[42:45], v5, s[52:53] offset:128
	global_load_dwordx4 v[46:49], v5, s[52:53] offset:208
	global_load_dwordx4 v[50:53], v5, s[52:53] offset:192
	s_movk_i32 s60, 0x1200
	v_and_b32_e32 v204, 0xffffffe0, v2
	v_lshlrev_b32_e32 v205, 2, v3
	v_sub_u32_e32 v4, s77, v4
	v_add_u32_e32 v206, v4, v205
	v_and_b32_e32 v184, 31, v188
	v_sub_u32_e32 v208, s78, v204
	s_waitcnt vmcnt(11)
	v_and_b32_e32 v69, 0xffff0000, v7
	v_lshlrev_b32_e32 v68, 16, v7
	v_and_b32_e32 v7, 0xffff0000, v6
	v_lshlrev_b32_e32 v6, 16, v6
	v_mul_f32_e32 v70, v7, v7
	v_pk_fma_f32 v[70:71], v[6:7], v[6:7], v[70:71] op_sel_hi:[1,1,0]
	v_mul_f32_e32 v72, v69, v69
	v_pk_fma_f32 v[70:71], v[68:69], v[68:69], v[70:71]
	v_and_b32_e32 v67, 0xffff0000, v9
	v_lshlrev_b32_e32 v66, 16, v9
	v_and_b32_e32 v9, 0xffff0000, v8
	v_lshlrev_b32_e32 v8, 16, v8
	v_pk_add_f32 v[70:71], v[72:73], v[70:71] op_sel_hi:[0,1]
	v_pk_fma_f32 v[70:71], v[8:9], v[8:9], v[70:71]
	v_mul_f32_e32 v72, v9, v9
	v_pk_add_f32 v[70:71], v[72:73], v[70:71] op_sel_hi:[0,1]
	v_pk_fma_f32 v[70:71], v[66:67], v[66:67], v[70:71]
	v_mul_f32_e32 v72, v67, v67
	s_waitcnt vmcnt(10)
	v_and_b32_e32 v65, 0xffff0000, v11
	v_lshlrev_b32_e32 v64, 16, v11
	v_and_b32_e32 v11, 0xffff0000, v10
	v_lshlrev_b32_e32 v10, 16, v10
	v_pk_add_f32 v[70:71], v[72:73], v[70:71] op_sel_hi:[0,1]
	v_pk_fma_f32 v[70:71], v[10:11], v[10:11], v[70:71]
	v_mul_f32_e32 v72, v11, v11
	v_pk_add_f32 v[70:71], v[72:73], v[70:71] op_sel_hi:[0,1]
	v_pk_fma_f32 v[70:71], v[64:65], v[64:65], v[70:71]
	v_mul_f32_e32 v72, v65, v65
	v_and_b32_e32 v63, 0xffff0000, v13
	v_lshlrev_b32_e32 v62, 16, v13
	v_and_b32_e32 v13, 0xffff0000, v12
	v_lshlrev_b32_e32 v12, 16, v12
	v_pk_add_f32 v[70:71], v[72:73], v[70:71] op_sel_hi:[0,1]
	v_pk_fma_f32 v[70:71], v[12:13], v[12:13], v[70:71]
	v_mul_f32_e32 v72, v13, v13
	v_pk_add_f32 v[70:71], v[72:73], v[70:71] op_sel_hi:[0,1]
	v_pk_fma_f32 v[70:71], v[62:63], v[62:63], v[70:71]
	v_mul_f32_e32 v72, v63, v63
	s_waitcnt vmcnt(9)
	v_and_b32_e32 v61, 0xffff0000, v15
	v_lshlrev_b32_e32 v60, 16, v15
	v_and_b32_e32 v15, 0xffff0000, v14
	v_lshlrev_b32_e32 v14, 16, v14
	v_pk_add_f32 v[70:71], v[72:73], v[70:71] op_sel_hi:[0,1]
	v_pk_fma_f32 v[70:71], v[14:15], v[14:15], v[70:71]
	v_mul_f32_e32 v72, v15, v15
	v_pk_add_f32 v[70:71], v[72:73], v[70:71] op_sel_hi:[0,1]
	v_pk_fma_f32 v[70:71], v[60:61], v[60:61], v[70:71]
	v_mul_f32_e32 v72, v61, v61
	v_and_b32_e32 v59, 0xffff0000, v17
	v_lshlrev_b32_e32 v58, 16, v17
	v_and_b32_e32 v17, 0xffff0000, v16
	v_lshlrev_b32_e32 v16, 16, v16
	v_pk_add_f32 v[70:71], v[72:73], v[70:71] op_sel_hi:[0,1]
	v_pk_fma_f32 v[70:71], v[16:17], v[16:17], v[70:71]
	v_mul_f32_e32 v72, v17, v17
	v_pk_add_f32 v[70:71], v[72:73], v[70:71] op_sel_hi:[0,1]
	v_pk_fma_f32 v[70:71], v[58:59], v[58:59], v[70:71]
	v_mul_f32_e32 v72, v59, v59
	s_waitcnt vmcnt(8)
	v_and_b32_e32 v57, 0xffff0000, v19
	v_lshlrev_b32_e32 v56, 16, v19
	v_and_b32_e32 v19, 0xffff0000, v18
	v_lshlrev_b32_e32 v18, 16, v18
	v_pk_add_f32 v[70:71], v[72:73], v[70:71] op_sel_hi:[0,1]
	v_pk_fma_f32 v[70:71], v[18:19], v[18:19], v[70:71]
	v_mul_f32_e32 v72, v19, v19
	v_pk_add_f32 v[70:71], v[72:73], v[70:71] op_sel_hi:[0,1]
	v_pk_fma_f32 v[70:71], v[56:57], v[56:57], v[70:71]
	v_mul_f32_e32 v72, v57, v57
	v_and_b32_e32 v55, 0xffff0000, v21
	v_lshlrev_b32_e32 v54, 16, v21
	v_and_b32_e32 v21, 0xffff0000, v20
	v_lshlrev_b32_e32 v20, 16, v20
	v_pk_add_f32 v[70:71], v[72:73], v[70:71] op_sel_hi:[0,1]
	v_pk_fma_f32 v[70:71], v[20:21], v[20:21], v[70:71]
	v_mul_f32_e32 v72, v21, v21
	v_pk_add_f32 v[70:71], v[72:73], v[70:71] op_sel_hi:[0,1]
	v_pk_fma_f32 v[70:71], v[54:55], v[54:55], v[70:71]
	v_mul_f32_e32 v72, v55, v55
	v_pk_add_f32 v[70:71], v[72:73], v[70:71] op_sel_hi:[0,1]
	v_mov_b32_e32 v5, v70
	s_nop 1
	v_permlane32_swap_b32_e32 v70, v5
	v_add_f32_e32 v5, v70, v5
	v_fmamk_f32 v5, v5, 0x3c800000, v178
	v_cmp_gt_f32_e32 vcc, s49, v5
	v_mul_f32_e32 v70, 0x4b800000, v5
	s_nop 0
	v_cndmask_b32_e32 v5, v5, v70, vcc
	v_rsq_f32_e32 v5, v5
	s_nop 0
	v_mul_f32_e32 v70, 0x45800000, v5
	v_cndmask_b32_e32 v70, v5, v70, vcc
	v_pk_mul_f32 v[6:7], v[70:71], v[6:7] op_sel_hi:[0,1]
	v_pk_mul_f32 v[18:19], v[70:71], v[18:19] op_sel_hi:[0,1]
	s_waitcnt vmcnt(6)
	v_pk_mul_f32 v[6:7], v[26:27], v[6:7]
	s_waitcnt vmcnt(0)
; __device__ __forceinline__ unsigned cvtpk(float lo, float hi) { f32x2 v = {lo, hi}; bf16v2 b = __builtin_convertvector(v, bf16v2); return __builtin_bit_cast(unsigned, b); }
; __device__ __forceinline__ int v_st(int k, int c) { const int kk = (k & ~0xC) | ((k & 4) << 1) | ((k & 8) >> 1); return ((kk >> 3) * 4 + (c >> 5)) * 512 + ((kk & 7) * 32 + (c & 31)) * 2; }
; __device__ __forceinline__ int v_rd_base(int lane) { return ((lane & 3) << 3) | (((lane >> 2) & 3) << 6) | (((lane >> 4) & 1) << 5) | (((lane >> 5) & 1) << 8); }
; template <int ND0, int DOFF>
; __device__ __forceinline__ void qkt(f32x16& p0, f32x16& p1, const char* Ks, const bf16x8* qr, int r32, int hi) {
;   p0 = f32x16{}; p1 = f32x16{};
; #pragma unroll
;   for (int d0 = 0; d0 < ND0; ++d0) { const int cb = ((d0 + DOFF) * 16 + hi * 8) * 2;
;     bf16x8 b0 = *reinterpret_cast<const bf16x8*>(Ks + KSWZ(r32, cb));
;     bf16x8 b1 = *reinterpret_cast<const bf16x8*>(Ks + KSWZ(32 + r32, cb));
;     p0 = __builtin_amdgcn_mfma_f32_32x32x16_bf16(b0, qr[d0], p0, 0, 0, 0);
;     p1 = __builtin_amdgcn_mfma_f32_32x32x16_bf16(b1, qr[d0], p1, 0, 0, 0); }
; template <int MODE>
; __device__ __forceinline__ void attn_body(const bf16_t* __restrict__ Qb, const bf16_t* __restrict__ Kh, const bf16_t* __restrict__ Vh, int NT, int krel0,
;                                           char* lds, const float* __restrict__ lutg, const AttnEpi& E) {
;     ...
;     for (int d0 = 0; d0 < ND0; ++d0) { u32x4 w; w.x = cvtpk(qf[d0][0], qf[d0][1]); w.y = cvtpk(qf[d0][2], qf[d0][3]); w.z = cvtpk(qf[d0][4], qf[d0][5]); w.w = cvtpk(qf[d0][6], qf[d0][7]);
;       qr[d0] = *reinterpret_cast<bf16x8*>(&w); }
;   }
;   const int sr = tid >> 4, sc = (tid & 15) * 8, vst0 = v_st(sr, sc), vst1 = v_st(32 + sr, sc);
;   const int vb0 = (int)(uintptr_t)V_lds + v_rd_base(lane);
;   struct { bf16x8 vs0, vs1, ks0, ks1; } sr_[2];
;     ...
;   const int relq = krel0 - (wid * 32 + r32) + 4 * hi, relwmin = krel0 - (wid * 32 + 31), relwmax = krel0 + 63 - wid * 32;
;     ...
;   f32x16 pA0, pA1, pB0, pB1; float mnA, mnB, alA, alB; bf16x8 pa0, pa1, pa2, pa3;
;   constexpr int SE = 0, SO = 1;
;   SLOAD(SE, 0); SLOAD(SO, 64); asm volatile("s_waitcnt vmcnt(4)" ::: "memory"); SWRITE(0, SE); __syncthreads();
;   qkt<ND0, DOFF>(pA0, pA1, K_lds, qr, r32, hi); PSM(pA0, pA1, mnA, alA, 0);
	v_pk_mul_f32 v[18:19], v[50:51], v[18:19]
	v_ashrrev_i32_e32 v50, 4, v188
	v_pk_mul_f32 v[8:9], v[70:71], v[8:9] op_sel_hi:[0,1]
	v_cvt_pk_bf16_f32 v142, v6, v7
	v_and_b32_e32 v6, 0xfffff0, v50
	v_lshlrev_b32_e32 v7, 1, v50
	v_pk_mul_f32 v[8:9], v[22:23], v[8:9]
	v_lshlrev_b32_e32 v5, 3, v188
	v_and_or_b32 v6, v7, 8, v6
	v_cvt_pk_bf16_f32 v144, v8, v9
	v_and_b32_e32 v51, 0x78, v5
	v_lshrrev_b32_e32 v7, 1, v50
	v_lshrrev_b32_e32 v6, 1, v6
	v_bfe_u32 v5, v5, 5, 2
	v_and_b32_e32 v8, 3, v50
	v_cvt_pk_bf16_f32 v130, v18, v19
	v_or_b32_e32 v6, v6, v5
	v_and_or_b32 v7, v7, 4, v8
	v_lshlrev_b32_e32 v18, 1, v51
	v_lshlrev_b32_e32 v6, 9, v6
	v_lshlrev_b32_e32 v7, 6, v7
	v_and_b32_e32 v8, 48, v18
	v_add_u32_e32 v19, 32, v50
	v_pk_mul_f32 v[10:11], v[70:71], v[10:11] op_sel_hi:[0,1]
	v_or3_b32 v209, v6, v7, v8
	v_and_b32_e32 v6, 0xfffff0, v19
	v_lshlrev_b32_e32 v9, 1, v19
	v_pk_mul_f32 v[10:11], v[34:35], v[10:11]
	v_pk_mul_f32 v[34:35], v[70:71], v[56:57] op_sel_hi:[0,1]
	v_and_or_b32 v6, v9, 8, v6
	v_pk_mul_f32 v[34:35], v[52:53], v[34:35]
	v_lshrrev_b32_e32 v6, 1, v6
	v_or_b32_e32 v52, 31, v2
	v_mad_i64_i32 v[2:3], s[6:7], v50, s60, 0
	v_or_b32_e32 v5, v6, v5
	v_or_b32_e32 v2, v2, v51
	v_cvt_pk_bf16_f32 v138, v10, v11
	v_lshlrev_b32_e32 v5, 9, v5
	v_lshlrev_b64 v[10:11], 1, v[2:3]
	v_pk_mul_f32 v[14:15], v[70:71], v[14:15] op_sel_hi:[0,1]
	v_or3_b32 v211, v5, v7, v8
	v_lshl_add_u64 v[2:3], s[0:1], 0, v[10:11]
	v_mad_i64_i32 v[6:7], s[6:7], v19, s60, 0
	v_pk_mul_f32 v[14:15], v[42:43], v[14:15]
	global_load_dwordx4 v[2:5], v[2:3], off
	v_or_b32_e32 v6, v6, v51
	v_pk_mul_f32 v[12:13], v[70:71], v[12:13] op_sel_hi:[0,1]
	v_cvt_pk_bf16_f32 v134, v14, v15
	v_lshlrev_b64 v[14:15], 1, v[6:7]
	v_pk_mul_f32 v[12:13], v[30:31], v[12:13]
	v_lshl_add_u64 v[6:7], s[0:1], 0, v[14:15]
	v_lshl_add_u64 v[10:11], s[58:59], 0, v[10:11]
	v_cvt_pk_bf16_f32 v140, v12, v13
	global_load_dwordx4 v[6:9], v[6:7], off
	v_pk_mul_f32 v[16:17], v[70:71], v[16:17] op_sel_hi:[0,1]
	global_load_dwordx4 v[10:13], v[10:11], off
	v_pk_mul_f32 v[16:17], v[38:39], v[16:17]
	v_lshl_add_u64 v[14:15], s[58:59], 0, v[14:15]
	v_cvt_pk_bf16_f32 v136, v16, v17
	global_load_dwordx4 v[14:17], v[14:15], off
	v_pk_mul_f32 v[20:21], v[70:71], v[20:21] op_sel_hi:[0,1]
	v_pk_mul_f32 v[20:21], v[46:47], v[20:21]
	v_pk_mul_f32 v[26:27], v[70:71], v[66:67] op_sel_hi:[0,1]
	v_cvt_pk_bf16_f32 v132, v20, v21
	v_add_u32_e32 v20, 64, v50
	v_mad_i64_i32 v[20:21], s[6:7], v20, s60, 0
	v_pk_mul_f32 v[22:23], v[70:71], v[68:69] op_sel_hi:[0,1]
	v_pk_mul_f32 v[24:25], v[24:25], v[26:27]
	v_pk_mul_f32 v[26:27], v[70:71], v[64:65] op_sel_hi:[0,1]
	v_or_b32_e32 v20, v20, v51
	v_pk_mul_f32 v[22:23], v[28:29], v[22:23]
	v_pk_mul_f32 v[26:27], v[36:37], v[26:27]
	v_pk_mul_f32 v[36:37], v[70:71], v[54:55] op_sel_hi:[0,1]
	v_lshlrev_b64 v[20:21], 1, v[20:21]
	v_pk_mul_f32 v[30:31], v[70:71], v[60:61] op_sel_hi:[0,1]
	v_pk_mul_f32 v[36:37], v[48:49], v[36:37]
	v_cvt_pk_bf16_f32 v143, v22, v23
	v_lshl_add_u64 v[22:23], s[0:1], 0, v[20:21]
	v_lshl_add_u64 v[20:21], s[58:59], 0, v[20:21]
	v_pk_mul_f32 v[30:31], v[44:45], v[30:31]
	v_cvt_pk_bf16_f32 v131, v34, v35
	v_cvt_pk_bf16_f32 v133, v36, v37
	global_load_dwordx4 v[34:37], v[22:23], off
	global_load_dwordx4 v[42:45], v[20:21], off
	v_add_u32_e32 v22, 0x60, v50
	v_mad_i64_i32 v[22:23], s[6:7], v22, s60, 0
	v_or_b32_e32 v22, v22, v51
	v_pk_mul_f32 v[28:29], v[70:71], v[62:63] op_sel_hi:[0,1]
	v_lshlrev_b64 v[22:23], 1, v[22:23]
	v_pk_mul_f32 v[28:29], v[32:33], v[28:29]
	v_pk_mul_f32 v[32:33], v[70:71], v[58:59] op_sel_hi:[0,1]
	v_cvt_pk_bf16_f32 v145, v24, v25
	v_lshl_add_u64 v[24:25], s[0:1], 0, v[22:23]
	v_lshl_add_u64 v[20:21], s[58:59], 0, v[22:23]
	v_pk_mul_f32 v[32:33], v[40:41], v[32:33]
	global_load_dwordx4 v[38:41], v[24:25], off
	global_load_dwordx4 v[46:49], v[20:21], off
	v_add_u32_e32 v53, 0, v209
	s_waitcnt vmcnt(4)
	v_add_u32_e32 v54, 0, v211
	v_lshlrev_b32_e32 v55, 8, v184
	v_cvt_pk_bf16_f32 v139, v26, v27
	v_cvt_pk_bf16_f32 v141, v28, v29
	v_cvt_pk_bf16_f32 v135, v30, v31
	v_cvt_pk_bf16_f32 v137, v32, v33
	v_or_b32_e32 v56, 0xa0, v0
	v_sub_u32_e32 v207, s77, v52
	v_cmp_gt_i32_e64 s[6:7], s95, v208
	v_cmp_lt_i32_e32 vcc, s15, v208
	s_waitcnt vmcnt(7)
	ds_write_b128 v53, v[2:5]
	v_lshlrev_b32_e32 v2, 8, v50
	v_and_b32_e32 v3, 0xf0, v188
	v_bitop3_b32 v214, v18, v2, v3 bitop3:0xde
	v_add_u32_e32 v2, 0, v214
	s_waitcnt vmcnt(6)
	ds_write_b128 v54, v[6:9]
	s_waitcnt vmcnt(5)
	ds_write_b128 v2, v[10:13] offset:49152
	v_lshlrev_b32_e32 v2, 8, v19
	v_bitop3_b32 v215, v18, v2, v3 bitop3:0xde
	v_add_u32_e32 v2, 0, v215
	v_lshlrev_b32_e32 v3, 4, v188
	s_waitcnt vmcnt(4)
	ds_write_b128 v2, v[14:17] offset:49152
	v_or_b32_e32 v2, 0x80, v0
	v_and_b32_e32 v64, 0xf0, v3
	v_bitop3_b32 v216, v2, v55, v64 bitop3:0xde
	v_add_u32_e32 v6, 0, v216
	s_waitcnt lgkmcnt(0)
	s_barrier
	ds_read_b128 v[2:5], v6 offset:49152
	ds_read_b128 v[6:9], v6 offset:57344
	s_waitcnt lgkmcnt(1)
	v_mfma_f32_32x32x16_bf16 v[18:33], v[2:5], v[142:145], 0
	v_bitop3_b32 v217, v56, v55, v64 bitop3:0xde
	v_add_u32_e32 v60, 0, v217
	ds_read_b128 v[56:59], v60 offset:49152
	ds_read_b128 v[60:63], v60 offset:57344
	s_waitcnt lgkmcnt(2)
	v_mfma_f32_32x32x16_bf16 v[2:17], v[6:9], v[142:145], 0
	s_waitcnt lgkmcnt(1)
	v_mfma_f32_32x32x16_bf16 v[18:33], v[56:59], v[138:141], v[18:33]
	v_or_b32_e32 v56, 0xc0, v0
	v_bitop3_b32 v218, v56, v55, v64 bitop3:0xde
	v_or_b32_e32 v0, 0xe0, v0
	v_bitop3_b32 v219, v0, v55, v64 bitop3:0xde
	v_add_u32_e32 v0, 0, v219
	s_waitcnt lgkmcnt(0)
	v_mfma_f32_32x32x16_bf16 v[2:17], v[60:63], v[138:141], v[2:17]
	v_add_u32_e32 v60, 0, v218
	ds_read_b128 v[56:59], v60 offset:49152
	ds_read_b128 v[60:63], v60 offset:57344
	s_waitcnt lgkmcnt(1)
	v_mfma_f32_32x32x16_bf16 v[18:33], v[56:59], v[134:137], v[18:33]
	s_waitcnt lgkmcnt(0)
	v_mfma_f32_32x32x16_bf16 v[2:17], v[60:63], v[134:137], v[2:17]
	ds_read_b128 v[56:59], v0 offset:49152
	ds_read_b128 v[60:63], v0 offset:57344
	v_mov_b32_e32 v0, s76
	s_waitcnt lgkmcnt(1)
	v_mfma_f32_32x32x16_bf16 v[18:33], v[56:59], v[130:133], v[18:33]
	s_waitcnt lgkmcnt(0)
	v_mfma_f32_32x32x16_bf16 v[2:17], v[60:63], v[130:133], v[2:17]
	s_and_saveexec_b64 s[60:61], vcc
	s_cbranch_execz .LBB0_174
; template <int MODE>
; __device__ __forceinline__ void partialSM(f32x16& p0, f32x16& p1, float& m_reg, float& mn, float& alpha, int relh, int relw_min, int relw_max, const float* lut) {
;     ...
;     if (nearT) {
; #pragma unroll
;       for (int r = 0; r < 16; ++r) { const int i0 = relh + (r & 3) + 8 * (r >> 2);
;         const int a0 = min(max(i0, -129), 129) + 129, a1 = min(max(i0 + 32, -129), 129) + 129;
;         p0[r] = fmaf(p0[r], C, lut[a0]); p1[r] = fmaf(p1[r], C, lut[a1]); }
	v_cmp_gt_i32_e32 vcc, s91, v207
	s_mov_b64 s[64:65], -1
	s_and_saveexec_b64 s[62:63], vcc
	s_cbranch_execz .LBB0_173
	v_add_u32_e32 v56, 1, v206
	v_med3_i32 v57, v56, s39, v198
	v_med3_i32 v56, v56, s33, v199
	v_lshl_add_u32 v58, v56, 2, s76
	v_add_u32_e32 v56, 2, v206
	v_med3_i32 v59, v56, s39, v198
	v_med3_i32 v56, v56, s33, v199
	v_lshl_add_u32 v60, v56, 2, s76
	v_add_u32_e32 v56, 3, v206
	v_med3_i32 v0, v206, s39, v198
	v_med3_i32 v55, v206, s33, v199
	v_med3_i32 v61, v56, s39, v198
	v_med3_i32 v56, v56, s33, v199
	v_lshl_add_u32 v0, v0, 2, s76
	v_lshl_add_u32 v55, v55, 2, s76
	v_lshl_add_u32 v57, v57, 2, s76
	v_lshl_add_u32 v59, v59, 2, s76
	v_lshl_add_u32 v62, v56, 2, s76
	v_lshl_add_u32 v61, v61, 2, s76
	ds_read_b32 v0, v0 offset:516
	ds_read_b32 v56, v55 offset:644
	ds_read_b32 v55, v57 offset:516
	ds_read_b32 v57, v58 offset:644
	ds_read_b32 v72, v59 offset:516
	ds_read_b32 v58, v60 offset:644
	ds_read_b32 v73, v61 offset:516
	ds_read_b32 v59, v62 offset:644
	v_add_u32_e32 v60, 8, v206
	v_add_u32_e32 v62, 9, v206
	v_add_u32_e32 v64, 10, v206
	v_add_u32_e32 v66, 11, v206
	v_med3_i32 v61, v60, s39, v198
	v_med3_i32 v60, v60, s33, v199
	v_med3_i32 v63, v62, s39, v198
	v_med3_i32 v62, v62, s33, v199
	v_med3_i32 v65, v64, s39, v198
	v_med3_i32 v64, v64, s33, v199
	v_med3_i32 v67, v66, s39, v198
	v_med3_i32 v66, v66, s33, v199
	v_lshl_add_u32 v61, v61, 2, s76
	v_lshl_add_u32 v60, v60, 2, s76
	v_lshl_add_u32 v63, v63, 2, s76
	v_lshl_add_u32 v62, v62, 2, s76
	v_lshl_add_u32 v64, v64, 2, s76
	v_lshl_add_u32 v66, v66, 2, s76
	v_lshl_add_u32 v65, v65, 2, s76
	v_lshl_add_u32 v67, v67, 2, s76
	ds_read_b32 v74, v61 offset:516
	ds_read_b32 v60, v60 offset:644
	ds_read_b32 v75, v63 offset:516
	ds_read_b32 v61, v62 offset:644
	ds_read_b32 v76, v65 offset:516
	ds_read_b32 v62, v64 offset:644
	ds_read_b32 v77, v67 offset:516
	ds_read_b32 v63, v66 offset:644
	v_add_u32_e32 v64, 16, v206
	v_add_u32_e32 v66, 17, v206
	v_add_u32_e32 v68, 18, v206
	v_add_u32_e32 v70, 19, v206
	v_med3_i32 v65, v64, s39, v198
	v_med3_i32 v64, v64, s33, v199
	v_med3_i32 v67, v66, s39, v198
	v_med3_i32 v66, v66, s33, v199
	v_med3_i32 v69, v68, s39, v198
	v_med3_i32 v68, v68, s33, v199
	v_med3_i32 v71, v70, s39, v198
	v_med3_i32 v70, v70, s33, v199
	v_lshl_add_u32 v65, v65, 2, s76
	v_lshl_add_u32 v64, v64, 2, s76
	v_lshl_add_u32 v67, v67, 2, s76
	v_lshl_add_u32 v66, v66, 2, s76
	v_lshl_add_u32 v68, v68, 2, s76
	v_lshl_add_u32 v70, v70, 2, s76
	v_lshl_add_u32 v69, v69, 2, s76
	v_lshl_add_u32 v71, v71, 2, s76
	ds_read_b32 v78, v65 offset:516
	ds_read_b32 v64, v64 offset:644
	ds_read_b32 v79, v67 offset:516
	ds_read_b32 v65, v66 offset:644
	ds_read_b32 v80, v69 offset:516
	ds_read_b32 v66, v68 offset:644
	ds_read_b32 v81, v71 offset:516
	ds_read_b32 v67, v70 offset:644
	v_add_u32_e32 v68, 24, v206
	v_add_u32_e32 v70, 25, v206
	v_add_u32_e32 v82, 26, v206
	v_med3_i32 v69, v68, s39, v198
	v_med3_i32 v68, v68, s33, v199
	v_med3_i32 v71, v70, s39, v198
	v_med3_i32 v70, v70, s33, v199
	v_med3_i32 v83, v82, s39, v198
	v_med3_i32 v82, v82, s33, v199
	v_add_u32_e32 v84, 27, v206
	s_waitcnt lgkmcnt(14)
	v_fmac_f32_e32 v0, 0x3e38aa3b, v18
	v_fmac_f32_e32 v55, 0x3e38aa3b, v19
	v_lshl_add_u32 v69, v69, 2, s76
	v_lshl_add_u32 v68, v68, 2, s76
	v_lshl_add_u32 v71, v71, 2, s76
	v_lshl_add_u32 v70, v70, 2, s76
	v_lshl_add_u32 v82, v82, 2, s76
	v_med3_i32 v85, v84, s39, v198
	v_med3_i32 v84, v84, s33, v199
	v_fmac_f32_e32 v72, 0x3e38aa3b, v20
	v_fmac_f32_e32 v73, 0x3e38aa3b, v21
	v_lshl_add_u32 v83, v83, 2, s76
	v_lshl_add_u32 v85, v85, 2, s76
	v_lshl_add_u32 v84, v84, 2, s76
	ds_read_b32 v88, v69 offset:516
	ds_read_b32 v68, v68 offset:644
	ds_read_b32 v89, v71 offset:516
	ds_read_b32 v69, v70 offset:644
	ds_read_b32 v90, v83 offset:516
	ds_read_b32 v70, v82 offset:644
	ds_read_b32 v91, v85 offset:516
	ds_read_b32 v71, v84 offset:644
	v_max_f32_e32 v82, v0, v55
	v_fmac_f32_e32 v74, 0x3e38aa3b, v22
	s_waitcnt lgkmcnt(14)
; template <int MODE>
; __device__ __forceinline__ void partialSM(f32x16& p0, f32x16& p1, float& m_reg, float& mn, float& alpha, int relh, int relw_min, int relw_max, const float* lut) {
;     ...
;     if (nearT) {
; #pragma unroll
;       for (int r = 0; r < 16; ++r) { const int i0 = relh + (r & 3) + 8 * (r >> 2);
;         const int a0 = min(max(i0, -129), 129) + 129, a1 = min(max(i0 + 32, -129), 129) + 129;
;         p0[r] = fmaf(p0[r], C, lut[a0]); p1[r] = fmaf(p1[r], C, lut[a1]); }
;     } else {
; #pragma unroll
;       for (int r = 0; r < 16; ++r) { p0[r] = fmaf(p0[r], C, cfar); p1[r] = fmaf(p1[r], C, cfar); }
;     }
;     float pmax = p0[0];
; #pragma unroll
;     for (int r = 1; r < 16; ++r) pmax = fmaxf(pmax, p0[r]);
; #pragma unroll
;     for (int r = 0; r < 16; ++r) pmax = fmaxf(pmax, p1[r]);
;     { auto rr = __builtin_amdgcn_permlane32_swap(__float_as_uint(pmax), __float_as_uint(pmax), false, false);
;       pmax = fmaxf(__uint_as_float(rr[0]), __uint_as_float(rr[1])); }
;     if (__builtin_expect(__all(pmax - m_reg <= THR2), 1)) { mn = m_reg; alpha = 1.f; }
;     else { mn = fmaxf(m_reg, pmax); alpha = __builtin_amdgcn_exp2f(m_reg - mn); m_reg = mn; }
; #pragma unroll
;     for (int r = 0; r < 16; ++r) p0[r] = __builtin_amdgcn_exp2f(p0[r] - mn);
; #pragma unroll
;     for (int r = 0; r < 16; ++r) p1[r] = p1[r] - mn;
	v_fmac_f32_e32 v75, 0x3e38aa3b, v23
	v_max3_f32 v82, v82, v72, v73
	v_fmac_f32_e32 v76, 0x3e38aa3b, v24
	v_fmac_f32_e32 v77, 0x3e38aa3b, v25
	v_max3_f32 v82, v82, v74, v75
	v_fmac_f32_e32 v78, 0x3e38aa3b, v26
	s_waitcnt lgkmcnt(13)
	v_fmac_f32_e32 v79, 0x3e38aa3b, v27
	v_max3_f32 v82, v82, v76, v77
	s_waitcnt lgkmcnt(11)
	v_fmac_f32_e32 v80, 0x3e38aa3b, v28
	s_waitcnt lgkmcnt(9)
	v_fmac_f32_e32 v81, 0x3e38aa3b, v29
	v_max3_f32 v82, v82, v78, v79
	s_waitcnt lgkmcnt(7)
	v_fmac_f32_e32 v88, 0x3e38aa3b, v30
	s_waitcnt lgkmcnt(5)
	v_fmac_f32_e32 v89, 0x3e38aa3b, v31
	v_max3_f32 v82, v82, v80, v81
	s_waitcnt lgkmcnt(3)
	v_fmac_f32_e32 v90, 0x3e38aa3b, v32
	s_waitcnt lgkmcnt(1)
	v_fmac_f32_e32 v91, 0x3e38aa3b, v33
	v_max3_f32 v82, v82, v88, v89
	v_max3_f32 v82, v82, v90, v91
	v_pk_fma_f32 v[56:57], v[2:3], s[48:49], v[56:57] op_sel_hi:[1,0,1]
	v_pk_fma_f32 v[58:59], v[4:5], s[48:49], v[58:59] op_sel_hi:[1,0,1]
	v_max3_f32 v82, v82, v56, v57
	v_max3_f32 v82, v82, v58, v59
	v_pk_fma_f32 v[60:61], v[6:7], s[48:49], v[60:61] op_sel_hi:[1,0,1]
	v_pk_fma_f32 v[62:63], v[8:9], s[48:49], v[62:63] op_sel_hi:[1,0,1]
	v_max3_f32 v82, v82, v60, v61
	v_max3_f32 v82, v82, v62, v63
	v_pk_fma_f32 v[64:65], v[10:11], s[48:49], v[64:65] op_sel_hi:[1,0,1]
	s_waitcnt lgkmcnt(0)
	v_pk_fma_f32 v[86:87], v[16:17], s[48:49], v[70:71] op_sel_hi:[1,0,1]
	v_max3_f32 v84, v82, v64, v65
	v_pk_fma_f32 v[82:83], v[12:13], s[48:49], v[66:67] op_sel_hi:[1,0,1]
	s_nop 0
	v_max3_f32 v66, v84, v82, v83
	v_pk_fma_f32 v[84:85], v[14:15], s[48:49], v[68:69] op_sel_hi:[1,0,1]
	s_nop 0
	v_max3_f32 v66, v66, v84, v85
	v_max3_f32 v66, v66, v86, v87
	v_mov_b32_e32 v67, v66
	s_nop 1
	v_permlane32_swap_b32_e32 v66, v67
	v_max_f32_e32 v67, v67, v67
	v_max_f32_e32 v66, v66, v66
	v_max_f32_e32 v66, v66, v67
	v_add_f32_e32 v67, 0x7149f2ca, v66
	v_cmp_ge_f32_e32 vcc, s94, v67
	v_max_f32_e32 v66, 0xf149f2ca, v66
	v_sub_f32_e32 v67, 0xf149f2ca, v66
	s_cmp_eq_u64 vcc, exec
	v_exp_f32_e32 v67, v67
	s_cselect_b64 vcc, -1, 0
	v_cndmask_b32_e32 v222, v66, v197, vcc
	v_mov_b32_e32 v100, s76
	ds_read_b32 v101, v100
	ds_read_b32 v100, v100 offset:1032
	v_readlane_b32 s19, v255, 21
	s_waitcnt lgkmcnt(0)
	v_max_f32_e32 v101, v101, v100
	v_add_f32_e32 v222, s19, v101
	v_sub_f32_e32 v0, v0, v222
	v_exp_f32_e32 v66, v0
	v_sub_f32_e32 v0, v55, v222
	v_cndmask_b32_e64 v220, v67, 1.0, vcc
	v_exp_f32_e32 v67, v0
	v_sub_f32_e32 v0, v72, v222
	v_exp_f32_e32 v68, v0
	v_sub_f32_e32 v0, v73, v222
	v_exp_f32_e32 v69, v0
	v_sub_f32_e32 v0, v74, v222
	v_exp_f32_e32 v70, v0
	v_sub_f32_e32 v0, v75, v222
	v_exp_f32_e32 v71, v0
	v_sub_f32_e32 v0, v76, v222
	v_exp_f32_e32 v72, v0
	v_sub_f32_e32 v0, v77, v222
	v_exp_f32_e32 v73, v0
	v_sub_f32_e32 v0, v78, v222
	v_exp_f32_e32 v74, v0
	v_sub_f32_e32 v0, v79, v222
	v_exp_f32_e32 v75, v0
	v_sub_f32_e32 v0, v80, v222
	v_exp_f32_e32 v76, v0
	v_sub_f32_e32 v0, v81, v222
	v_exp_f32_e32 v77, v0
	v_sub_f32_e32 v0, v88, v222
	v_exp_f32_e32 v78, v0
	v_sub_f32_e32 v0, v89, v222
	v_exp_f32_e32 v79, v0
	v_sub_f32_e32 v0, v90, v222
	v_exp_f32_e32 v80, v0
	v_sub_f32_e32 v0, v91, v222
	v_exp_f32_e32 v81, v0
	v_sub_f32_e32 v97, v87, v222
	v_sub_f32_e32 v96, v86, v222
	v_sub_f32_e32 v95, v85, v222
	v_sub_f32_e32 v94, v84, v222
	v_sub_f32_e32 v93, v83, v222
	v_sub_f32_e32 v92, v82, v222
	v_sub_f32_e32 v91, v65, v222
	v_sub_f32_e32 v90, v64, v222
	v_sub_f32_e32 v89, v63, v222
	v_sub_f32_e32 v88, v62, v222
	v_sub_f32_e32 v87, v61, v222
	v_sub_f32_e32 v86, v60, v222
	v_sub_f32_e32 v85, v59, v222
	v_sub_f32_e32 v84, v58, v222
	v_sub_f32_e32 v83, v57, v222
	v_sub_f32_e32 v82, v56, v222
	s_xor_b64 s[64:65], exec, -1

; template <int MODE>
; __device__ __forceinline__ void partialSM(f32x16& p0, f32x16& p1, float& m_reg, float& mn, float& alpha, int relh, int relw_min, int relw_max, const float* lut) {
;     ...
;       if (!nearT) {
;         float pmax = p0[0];
; #pragma unroll
;         for (int r = 1; r < 16; ++r) pmax = fmaxf(pmax, p0[r]);
; #pragma unroll
;         for (int r = 0; r < 16; ++r) pmax = fmaxf(pmax, p1[r]);
;         { auto rr = __builtin_amdgcn_permlane32_swap(__float_as_uint(pmax), __float_as_uint(pmax), false, false);
;           pmax = fmaxf(__uint_as_float(rr[0]), __uint_as_float(rr[1])); }
;         const float tmax = fmaf(pmax, C, cfar);
;         if (__builtin_expect(__all(tmax - m_reg <= THR2), 1)) { mn = m_reg; alpha = 1.f; }
;         else { mn = fmaxf(m_reg, tmax); alpha = __builtin_amdgcn_exp2f(m_reg - mn); m_reg = mn; }
;         const float off = cfar - mn;
; #pragma unroll
;         for (int r = 0; r < 16; ++r) p0[r] = fmaf(p0[r], C, off);
; #pragma unroll
;         for (int r = 0; r < 16; ++r) p1[r] = fmaf(p1[r], C, off);
; #pragma unroll
;         for (int r = 0; r < 16; ++r) p0[r] = __builtin_amdgcn_exp2f(p0[r]);
;         return;
.LBB0_174:
	s_or_b64 exec, exec, s[60:61]
	s_and_saveexec_b64 s[60:61], s[6:7]
	s_cbranch_execz .LBB0_176
	s_nop 4
	v_max_f32_e32 v55, v19, v19
	v_max_f32_e32 v56, v18, v18
	v_max_f32_e32 v55, v56, v55
	v_max3_f32 v55, v55, v20, v21
	v_max3_f32 v55, v55, v22, v23
	v_max3_f32 v55, v55, v24, v25
	v_max3_f32 v55, v55, v26, v27
	v_max3_f32 v55, v55, v28, v29
	v_max3_f32 v55, v55, v30, v31
	v_max3_f32 v55, v55, v32, v33
	v_max3_f32 v55, v55, v2, v3
	v_max3_f32 v55, v55, v4, v5
	v_max3_f32 v55, v55, v6, v7
	v_max3_f32 v55, v55, v8, v9
	v_max3_f32 v55, v55, v10, v11
	v_max3_f32 v55, v55, v12, v13
	v_max3_f32 v55, v55, v14, v15
	ds_read_b32 v0, v0
	v_max3_f32 v55, v55, v16, v17
	v_mov_b32_e32 v56, v55
	s_nop 1
	v_permlane32_swap_b32_e32 v55, v56
	v_max_f32_e32 v56, v56, v56
	v_max_f32_e32 v55, v55, v55
	v_max_f32_e32 v55, v55, v56
	s_waitcnt lgkmcnt(0)
	v_fmamk_f32 v55, v55, 0x3e38aa3b, v0
	v_add_f32_e32 v56, 0x7149f2ca, v55
	v_cmp_ge_f32_e32 vcc, s94, v56
	s_cmp_eq_u64 vcc, exec
	s_cselect_b64 vcc, -1, 0
	v_max_f32_e32 v55, 0xf149f2ca, v55
	v_cndmask_b32_e32 v222, v55, v197, vcc
	v_mov_b32_e32 v100, s76
	ds_read_b32 v101, v100
	ds_read_b32 v100, v100 offset:1032
	v_readlane_b32 s19, v255, 21
	s_waitcnt lgkmcnt(0)
	v_max_f32_e32 v101, v101, v100
	v_add_f32_e32 v222, s19, v101
	v_sub_f32_e32 v0, v0, v222
	v_sub_f32_e32 v56, 0xf149f2ca, v55
	v_mov_b32_e32 v55, v0
	v_exp_f32_e32 v56, v56
	v_fmamk_f32 v18, v18, 0x3e38aa3b, v0
	v_fmamk_f32 v19, v19, 0x3e38aa3b, v0
	v_fmamk_f32 v20, v20, 0x3e38aa3b, v0
	v_fmamk_f32 v21, v21, 0x3e38aa3b, v0
	v_fmamk_f32 v22, v22, 0x3e38aa3b, v0
	v_fmamk_f32 v23, v23, 0x3e38aa3b, v0
	v_fmamk_f32 v24, v24, 0x3e38aa3b, v0
	v_fmamk_f32 v25, v25, 0x3e38aa3b, v0
	v_fmamk_f32 v26, v26, 0x3e38aa3b, v0
	v_fmamk_f32 v27, v27, 0x3e38aa3b, v0
	v_fmamk_f32 v28, v28, 0x3e38aa3b, v0
	v_fmamk_f32 v29, v29, 0x3e38aa3b, v0
	v_fmamk_f32 v30, v30, 0x3e38aa3b, v0
	v_fmamk_f32 v31, v31, 0x3e38aa3b, v0
	v_fmamk_f32 v32, v32, 0x3e38aa3b, v0
	v_fmac_f32_e32 v55, 0x3e38aa3b, v33
	v_exp_f32_e32 v66, v18
	v_exp_f32_e32 v67, v19
	v_exp_f32_e32 v68, v20
	v_exp_f32_e32 v69, v21
	v_exp_f32_e32 v70, v22
	v_exp_f32_e32 v71, v23
	v_exp_f32_e32 v72, v24
	v_exp_f32_e32 v73, v25
	v_exp_f32_e32 v74, v26
	v_exp_f32_e32 v75, v27
	v_exp_f32_e32 v76, v28
	v_exp_f32_e32 v77, v29
	v_exp_f32_e32 v78, v30
	v_exp_f32_e32 v79, v31
	v_exp_f32_e32 v80, v32
	v_exp_f32_e32 v81, v55
	v_cndmask_b32_e64 v220, v56, 1.0, vcc
	v_pk_fma_f32 v[96:97], v[16:17], s[48:49], v[0:1] op_sel_hi:[1,0,0]
	v_pk_fma_f32 v[94:95], v[14:15], s[48:49], v[0:1] op_sel_hi:[1,0,0]
	v_pk_fma_f32 v[92:93], v[12:13], s[48:49], v[0:1] op_sel_hi:[1,0,0]
	v_pk_fma_f32 v[90:91], v[10:11], s[48:49], v[0:1] op_sel_hi:[1,0,0]
	v_pk_fma_f32 v[88:89], v[8:9], s[48:49], v[0:1] op_sel_hi:[1,0,0]
	v_pk_fma_f32 v[86:87], v[6:7], s[48:49], v[0:1] op_sel_hi:[1,0,0]
	v_pk_fma_f32 v[84:85], v[4:5], s[48:49], v[0:1] op_sel_hi:[1,0,0]
	v_pk_fma_f32 v[82:83], v[2:3], s[48:49], v[0:1] op_sel_hi:[1,0,0]

; template <int MODE>
; __device__ __forceinline__ void partialSM(f32x16& p0, f32x16& p1, float& m_reg, float& mn, float& alpha, int relh, int relw_min, int relw_max, const float* lut) {
;     ...
;       if (!nearT) {
;         float pmax = p0[0];
; #pragma unroll
;         for (int r = 1; r < 16; ++r) pmax = fmaxf(pmax, p0[r]);
; #pragma unroll
;         for (int r = 0; r < 16; ++r) pmax = fmaxf(pmax, p1[r]);
;         { auto rr = __builtin_amdgcn_permlane32_swap(__float_as_uint(pmax), __float_as_uint(pmax), false, false);
;           pmax = fmaxf(__uint_as_float(rr[0]), __uint_as_float(rr[1])); }
;         const float tmax = fmaf(pmax, C, cfar);
;         if (__builtin_expect(__all(tmax - m_reg <= THR2), 1)) { mn = m_reg; alpha = 1.f; }
;         else { mn = fmaxf(m_reg, tmax); alpha = __builtin_amdgcn_exp2f(m_reg - mn); m_reg = mn; }
;         const float off = cfar - mn;
; #pragma unroll
;         for (int r = 0; r < 16; ++r) p0[r] = fmaf(p0[r], C, off);
; #pragma unroll
;         for (int r = 0; r < 16; ++r) p1[r] = fmaf(p1[r], C, off);
; #pragma unroll
;         for (int r = 0; r < 16; ++r) p0[r] = __builtin_amdgcn_exp2f(p0[r]);
;         return;
.LBB0_181:
	s_or_b64 exec, exec, s[58:59]
	s_and_saveexec_b64 s[58:59], s[0:1]
	s_cbranch_execz .LBB0_183
	ds_read_b32 v66, v232
	s_waitcnt lgkmcnt(0)
	v_mov_b32_e32 v231, v222
	v_sub_f32_e32 v66, v66, v231
	v_fmamk_f32 v67, v114, 0x3e38aa3b, v66
	v_mov_b32_e32 v114, v66
	v_mov_b32_e32 v229, 1.0
	v_fmamk_f32 v68, v115, 0x3e38aa3b, v66
	v_fmamk_f32 v69, v116, 0x3e38aa3b, v66
	v_fmamk_f32 v70, v117, 0x3e38aa3b, v66
	v_fmamk_f32 v71, v118, 0x3e38aa3b, v66
	v_fmamk_f32 v72, v119, 0x3e38aa3b, v66
	v_fmamk_f32 v73, v120, 0x3e38aa3b, v66
	v_fmamk_f32 v74, v121, 0x3e38aa3b, v66
	v_fmamk_f32 v75, v122, 0x3e38aa3b, v66
	v_fmamk_f32 v76, v123, 0x3e38aa3b, v66
	v_fmamk_f32 v77, v124, 0x3e38aa3b, v66
	v_fmamk_f32 v78, v125, 0x3e38aa3b, v66
	v_fmamk_f32 v79, v126, 0x3e38aa3b, v66
	v_fmamk_f32 v80, v127, 0x3e38aa3b, v66
	v_fmamk_f32 v81, v128, 0x3e38aa3b, v66
	v_fmac_f32_e32 v114, 0x3e38aa3b, v129
	v_fmamk_f32 v97, v113, 0x3e38aa3b, v66
	v_fmamk_f32 v96, v112, 0x3e38aa3b, v66
	v_fmamk_f32 v95, v111, 0x3e38aa3b, v66
	v_fmamk_f32 v94, v110, 0x3e38aa3b, v66
	v_fmamk_f32 v93, v109, 0x3e38aa3b, v66
	v_fmamk_f32 v92, v108, 0x3e38aa3b, v66
	v_fmamk_f32 v91, v107, 0x3e38aa3b, v66
	v_fmamk_f32 v90, v106, 0x3e38aa3b, v66
	v_fmamk_f32 v89, v105, 0x3e38aa3b, v66
	v_fmamk_f32 v88, v104, 0x3e38aa3b, v66
	v_fmamk_f32 v87, v103, 0x3e38aa3b, v66
	v_fmamk_f32 v86, v102, 0x3e38aa3b, v66
	v_fmamk_f32 v85, v101, 0x3e38aa3b, v66
	v_fmamk_f32 v84, v100, 0x3e38aa3b, v66
	v_fmamk_f32 v83, v99, 0x3e38aa3b, v66
	v_fmamk_f32 v82, v98, 0x3e38aa3b, v66
	v_exp_f32_e32 v66, v67
	v_exp_f32_e32 v67, v68
	v_exp_f32_e32 v68, v69
	v_exp_f32_e32 v69, v70
	v_exp_f32_e32 v70, v71
	v_exp_f32_e32 v71, v72
	v_exp_f32_e32 v72, v73
	v_exp_f32_e32 v73, v74
	v_exp_f32_e32 v74, v75
	v_exp_f32_e32 v75, v76
	v_exp_f32_e32 v76, v77
	v_exp_f32_e32 v77, v78
	v_exp_f32_e32 v78, v79
	v_exp_f32_e32 v79, v80
	v_exp_f32_e32 v80, v81
	v_exp_f32_e32 v81, v114

; template <int MODE>
; __device__ __forceinline__ void partialSM(f32x16& p0, f32x16& p1, float& m_reg, float& mn, float& alpha, int relh, int relw_min, int relw_max, const float* lut) {
;     ...
;       if (!nearT) {
;         float pmax = p0[0];
; #pragma unroll
;         for (int r = 1; r < 16; ++r) pmax = fmaxf(pmax, p0[r]);
; #pragma unroll
;         for (int r = 0; r < 16; ++r) pmax = fmaxf(pmax, p1[r]);
;         { auto rr = __builtin_amdgcn_permlane32_swap(__float_as_uint(pmax), __float_as_uint(pmax), false, false);
;           pmax = fmaxf(__uint_as_float(rr[0]), __uint_as_float(rr[1])); }
;         const float tmax = fmaf(pmax, C, cfar);
;         if (__builtin_expect(__all(tmax - m_reg <= THR2), 1)) { mn = m_reg; alpha = 1.f; }
;         else { mn = fmaxf(m_reg, tmax); alpha = __builtin_amdgcn_exp2f(m_reg - mn); m_reg = mn; }
;         const float off = cfar - mn;
; #pragma unroll
;         for (int r = 0; r < 16; ++r) p0[r] = fmaf(p0[r], C, off);
; #pragma unroll
;         for (int r = 0; r < 16; ++r) p1[r] = fmaf(p1[r], C, off);
; #pragma unroll
;         for (int r = 0; r < 16; ++r) p0[r] = __builtin_amdgcn_exp2f(p0[r]);
;         return;
.LBB0_193:
	s_or_b64 exec, exec, s[60:61]
	s_and_saveexec_b64 s[60:61], s[58:59]
	s_cbranch_execz .LBB0_195
	ds_read_b32 v66, v234
	s_waitcnt lgkmcnt(0)
	v_mov_b32_e32 v222, v231
	v_sub_f32_e32 v66, v66, v222
	v_fmamk_f32 v67, v114, 0x3e38aa3b, v66
	v_mov_b32_e32 v114, v66
	v_mov_b32_e32 v228, 1.0
	v_fmamk_f32 v68, v115, 0x3e38aa3b, v66
	v_fmamk_f32 v69, v116, 0x3e38aa3b, v66
	v_fmamk_f32 v70, v117, 0x3e38aa3b, v66
	v_fmamk_f32 v71, v118, 0x3e38aa3b, v66
	v_fmamk_f32 v72, v119, 0x3e38aa3b, v66
	v_fmamk_f32 v73, v120, 0x3e38aa3b, v66
	v_fmamk_f32 v74, v121, 0x3e38aa3b, v66
	v_fmamk_f32 v75, v122, 0x3e38aa3b, v66
	v_fmamk_f32 v76, v123, 0x3e38aa3b, v66
	v_fmamk_f32 v77, v124, 0x3e38aa3b, v66
	v_fmamk_f32 v78, v125, 0x3e38aa3b, v66
	v_fmamk_f32 v79, v126, 0x3e38aa3b, v66
	v_fmamk_f32 v80, v127, 0x3e38aa3b, v66
	v_fmamk_f32 v81, v128, 0x3e38aa3b, v66
	v_fmac_f32_e32 v114, 0x3e38aa3b, v129
	v_fmamk_f32 v97, v113, 0x3e38aa3b, v66
	v_fmamk_f32 v96, v112, 0x3e38aa3b, v66
	v_fmamk_f32 v95, v111, 0x3e38aa3b, v66
	v_fmamk_f32 v94, v110, 0x3e38aa3b, v66
	v_fmamk_f32 v93, v109, 0x3e38aa3b, v66
	v_fmamk_f32 v92, v108, 0x3e38aa3b, v66
	v_fmamk_f32 v91, v107, 0x3e38aa3b, v66
	v_fmamk_f32 v90, v106, 0x3e38aa3b, v66
	v_fmamk_f32 v89, v105, 0x3e38aa3b, v66
	v_fmamk_f32 v88, v104, 0x3e38aa3b, v66
	v_fmamk_f32 v87, v103, 0x3e38aa3b, v66
	v_fmamk_f32 v86, v102, 0x3e38aa3b, v66
	v_fmamk_f32 v85, v101, 0x3e38aa3b, v66
	v_fmamk_f32 v84, v100, 0x3e38aa3b, v66
	v_fmamk_f32 v83, v99, 0x3e38aa3b, v66
	v_fmamk_f32 v82, v98, 0x3e38aa3b, v66
	v_exp_f32_e32 v66, v67
	v_exp_f32_e32 v67, v68
	v_exp_f32_e32 v68, v69
	v_exp_f32_e32 v69, v70
	v_exp_f32_e32 v70, v71
	v_exp_f32_e32 v71, v72
	v_exp_f32_e32 v72, v73
	v_exp_f32_e32 v73, v74
	v_exp_f32_e32 v74, v75
	v_exp_f32_e32 v75, v76
	v_exp_f32_e32 v76, v77
	v_exp_f32_e32 v77, v78
	v_exp_f32_e32 v78, v79
	v_exp_f32_e32 v79, v80
	v_exp_f32_e32 v80, v81
	v_exp_f32_e32 v81, v114
